# P11: cross-group reduction adds as v_pk_add_f32 (6 fewer VALU per token in the VALU-bound phase), bit-identical
# baseline (speedup 1.0000x reference)
; DI f2_t cvt8lo(unsigned w) { return __builtin_amdgcn_cvt_pk_f32_fp8(w, false); }
; DI f2_t cvt8hi(unsigned w) { return __builtin_amdgcn_cvt_pk_f32_fp8(w, true); }
; DI void wave_lds_sync() { asm volatile("s_waitcnt lgkmcnt(0)" ::: "memory"); __builtin_amdgcn_wave_barrier(); }
; DI void phase11(const Params& p, char* smem, int rep) {
;     ...
;     for (int t = 0; t < 4; ++t) {
;       const int tok = __builtin_amdgcn_readfirstlane(c * 16 + w * 4 + t);
;       const int i0 = IDS[(size_t)tok * 128 + lane], i1 = IDS[(size_t)tok * 128 + 64 + lane];
;       const float a0 = ACT[(size_t)tok * 128 + lane], a1 = ACT[(size_t)tok * 128 + 64 + lane];
;       wave_lds_sync();
;       lw[(lane & 3) * 32 + (lane >> 2)] = i0; lw[(lane & 3) * 32 + 16 + (lane >> 2)] = i1;
;       lf[(lane & 3) * 32 + (lane >> 2)] = a0; lf[(lane & 3) * 32 + 16 + (lane >> 2)] = a1;
;       wave_lds_sync();
;       f2_t o[8];
; #pragma unroll
;       for (int i = 0; i < 8; ++i) o[i] = f2_t{0.f, 0.f};
;       const unsigned char* vb = V8 + s * 256 + l15 * 16;
; #pragma unroll
;       for (int batch = 0; batch < 2; ++batch) {
;         int ida[16]; float aa[16];
; #pragma unroll
;         for (int q = 0; q < 4; ++q) {
;           const int4 v = *(const int4*)(lw + g * 32 + batch * 16 + q * 4); ida[q * 4] = v.x; ida[q * 4 + 1] = v.y; ida[q * 4 + 2] = v.z; ida[q * 4 + 3] = v.w;
;           const float4 f = *(const float4*)(lf + g * 32 + batch * 16 + q * 4); aa[q * 4] = f.x; aa[q * 4 + 1] = f.y; aa[q * 4 + 2] = f.z; aa[q * 4 + 3] = f.w;
;         }
;         u32x4 rows[16];
; #pragma unroll
;         for (int k = 0; k < 16; ++k) rows[k] = *(const u32x4*)(vb + (size_t)ida[k] * 2048);
; #pragma unroll
;         for (int k = 0; k < 16; ++k) {
;           const f2_t a2 = {aa[k], aa[k]};
; #pragma unroll
;           for (int d = 0; d < 4; ++d) { const unsigned ww = rows[k][d]; o[2 * d] += a2 * cvt8lo(ww); o[2 * d + 1] += a2 * cvt8hi(ww); }
.Lp11_body:
	s_add_i32 s54, s34, 0
	s_lshl_b32 s46, s54, 12
	s_add_i32 s46, s46, s24
	s_add_i32 s55, s34, 1
	s_lshl_b32 s47, s55, 9
	s_add_u32 s42, s6, s47
	s_addc_u32 s43, s7, 0
	s_add_u32 s44, s8, s47
	s_addc_u32 s45, s9, 0
	global_load_dword v10, v3, s[42:43]
	global_load_dword v11, v3, s[42:43] offset:256
	global_load_dword v12, v3, s[44:45]
	global_load_dword v13, v3, s[44:45] offset:256
	s_waitcnt lgkmcnt(0)
	v_lshl_add_u32 v20, v20, 11, v2
	v_lshl_add_u32 v21, v21, 11, v2
	v_lshl_add_u32 v22, v22, 11, v2
	v_lshl_add_u32 v23, v23, 11, v2
	v_lshl_add_u32 v24, v24, 11, v2
	v_lshl_add_u32 v25, v25, 11, v2
	v_lshl_add_u32 v26, v26, 11, v2
	v_lshl_add_u32 v27, v27, 11, v2
	v_lshl_add_u32 v28, v28, 11, v2
	v_lshl_add_u32 v29, v29, 11, v2
	v_lshl_add_u32 v30, v30, 11, v2
	v_lshl_add_u32 v31, v31, 11, v2
	v_lshl_add_u32 v32, v32, 11, v2
	v_lshl_add_u32 v33, v33, 11, v2
	v_lshl_add_u32 v34, v34, 11, v2
	v_lshl_add_u32 v35, v35, 11, v2
	v_lshl_add_u32 v36, v36, 11, v2
	v_lshl_add_u32 v37, v37, 11, v2
	v_lshl_add_u32 v38, v38, 11, v2
	v_lshl_add_u32 v39, v39, 11, v2
	v_lshl_add_u32 v40, v40, 11, v2
	v_lshl_add_u32 v41, v41, 11, v2
	v_lshl_add_u32 v42, v42, 11, v2
	v_lshl_add_u32 v43, v43, 11, v2
	v_lshl_add_u32 v44, v44, 11, v2
	v_lshl_add_u32 v45, v45, 11, v2
	v_lshl_add_u32 v46, v46, 11, v2
	v_lshl_add_u32 v47, v47, 11, v2
	v_lshl_add_u32 v48, v48, 11, v2
	v_lshl_add_u32 v49, v49, 11, v2
	v_lshl_add_u32 v50, v50, 11, v2
	v_lshl_add_u32 v51, v51, 11, v2
	global_load_dwordx4 v[84:87], v20, s[20:21]
	global_load_dwordx4 v[88:91], v21, s[20:21]
	global_load_dwordx4 v[92:95], v22, s[20:21]
	global_load_dwordx4 v[96:99], v23, s[20:21]
	global_load_dwordx4 v[100:103], v24, s[20:21]
	global_load_dwordx4 v[104:107], v25, s[20:21]
	global_load_dwordx4 v[108:111], v26, s[20:21]
	global_load_dwordx4 v[112:115], v27, s[20:21]
	global_load_dwordx4 v[116:119], v28, s[20:21]
	global_load_dwordx4 v[120:123], v29, s[20:21]
	global_load_dwordx4 v[124:127], v30, s[20:21]
	global_load_dwordx4 v[128:131], v31, s[20:21]
	global_load_dwordx4 v[132:135], v32, s[20:21]
	global_load_dwordx4 v[136:139], v33, s[20:21]
	global_load_dwordx4 v[140:143], v34, s[20:21]
	global_load_dwordx4 v[144:147], v35, s[20:21]
	global_load_dwordx4 v[148:151], v36, s[20:21]
	global_load_dwordx4 v[152:155], v37, s[20:21]
	global_load_dwordx4 v[156:159], v38, s[20:21]
	global_load_dwordx4 v[160:163], v39, s[20:21]
	global_load_dwordx4 v[164:167], v40, s[20:21]
	global_load_dwordx4 v[168:171], v41, s[20:21]
	global_load_dwordx4 v[172:175], v42, s[20:21]
	global_load_dwordx4 v[176:179], v43, s[20:21]
	global_load_dwordx4 v[180:183], v44, s[20:21]
	global_load_dwordx4 v[184:187], v45, s[20:21]
	global_load_dwordx4 v[190:193], v46, s[20:21]
	global_load_dwordx4 v[194:197], v47, s[20:21]
	global_load_dwordx4 v[198:201], v48, s[20:21]
	global_load_dwordx4 v[202:205], v49, s[20:21]
	global_load_dwordx4 v[206:209], v50, s[20:21]
	global_load_dwordx4 v[210:213], v51, s[20:21]
	s_waitcnt vmcnt(31)
	v_cvt_pk_f32_fp8_e32 v[232:233], v84
	v_cvt_pk_f32_fp8_sdwa v[234:235], v84 src0_sel:WORD_1
	v_pk_fma_f32 v[216:217], v[52:53], v[232:233], 0 op_sel_hi:[0,1,0]
	v_pk_fma_f32 v[218:219], v[52:53], v[234:235], 0 op_sel_hi:[0,1,0]
	v_cvt_pk_f32_fp8_e32 v[236:237], v85
	v_cvt_pk_f32_fp8_sdwa v[238:239], v85 src0_sel:WORD_1
	v_pk_fma_f32 v[220:221], v[52:53], v[236:237], 0 op_sel_hi:[0,1,0]
	v_pk_fma_f32 v[222:223], v[52:53], v[238:239], 0 op_sel_hi:[0,1,0]
	v_cvt_pk_f32_fp8_e32 v[232:233], v86
	v_cvt_pk_f32_fp8_sdwa v[234:235], v86 src0_sel:WORD_1
	v_pk_fma_f32 v[224:225], v[52:53], v[232:233], 0 op_sel_hi:[0,1,0]
	v_pk_fma_f32 v[226:227], v[52:53], v[234:235], 0 op_sel_hi:[0,1,0]
	v_cvt_pk_f32_fp8_e32 v[236:237], v87
	v_cvt_pk_f32_fp8_sdwa v[238:239], v87 src0_sel:WORD_1
	v_pk_fma_f32 v[228:229], v[52:53], v[236:237], 0 op_sel_hi:[0,1,0]
	v_pk_fma_f32 v[230:231], v[52:53], v[238:239], 0 op_sel_hi:[0,1,0]
	s_waitcnt vmcnt(30)
	v_cvt_pk_f32_fp8_e32 v[232:233], v88
	v_cvt_pk_f32_fp8_sdwa v[234:235], v88 src0_sel:WORD_1
	v_pk_fma_f32 v[216:217], v[52:53], v[232:233], v[216:217] op_sel:[1,0,0]
	v_pk_fma_f32 v[218:219], v[52:53], v[234:235], v[218:219] op_sel:[1,0,0]
	v_cvt_pk_f32_fp8_e32 v[236:237], v89
	v_cvt_pk_f32_fp8_sdwa v[238:239], v89 src0_sel:WORD_1
	v_pk_fma_f32 v[220:221], v[52:53], v[236:237], v[220:221] op_sel:[1,0,0]
	v_pk_fma_f32 v[222:223], v[52:53], v[238:239], v[222:223] op_sel:[1,0,0]
	v_cvt_pk_f32_fp8_e32 v[232:233], v90
	v_cvt_pk_f32_fp8_sdwa v[234:235], v90 src0_sel:WORD_1
	v_pk_fma_f32 v[224:225], v[52:53], v[232:233], v[224:225] op_sel:[1,0,0]
	v_pk_fma_f32 v[226:227], v[52:53], v[234:235], v[226:227] op_sel:[1,0,0]
	v_cvt_pk_f32_fp8_e32 v[236:237], v91
	v_cvt_pk_f32_fp8_sdwa v[238:239], v91 src0_sel:WORD_1
	v_pk_fma_f32 v[228:229], v[52:53], v[236:237], v[228:229] op_sel:[1,0,0]
	v_pk_fma_f32 v[230:231], v[52:53], v[238:239], v[230:231] op_sel:[1,0,0]
	s_waitcnt vmcnt(29)
	v_cvt_pk_f32_fp8_e32 v[232:233], v92
	v_cvt_pk_f32_fp8_sdwa v[234:235], v92 src0_sel:WORD_1
	v_pk_fma_f32 v[216:217], v[54:55], v[232:233], v[216:217] op_sel_hi:[0,1,1]
	v_pk_fma_f32 v[218:219], v[54:55], v[234:235], v[218:219] op_sel_hi:[0,1,1]
	v_cvt_pk_f32_fp8_e32 v[236:237], v93
	v_cvt_pk_f32_fp8_sdwa v[238:239], v93 src0_sel:WORD_1
	v_pk_fma_f32 v[220:221], v[54:55], v[236:237], v[220:221] op_sel_hi:[0,1,1]
	v_pk_fma_f32 v[222:223], v[54:55], v[238:239], v[222:223] op_sel_hi:[0,1,1]
	v_cvt_pk_f32_fp8_e32 v[232:233], v94
	v_cvt_pk_f32_fp8_sdwa v[234:235], v94 src0_sel:WORD_1
	v_pk_fma_f32 v[224:225], v[54:55], v[232:233], v[224:225] op_sel_hi:[0,1,1]
	v_pk_fma_f32 v[226:227], v[54:55], v[234:235], v[226:227] op_sel_hi:[0,1,1]
	v_cvt_pk_f32_fp8_e32 v[236:237], v95
	v_cvt_pk_f32_fp8_sdwa v[238:239], v95 src0_sel:WORD_1
	v_pk_fma_f32 v[228:229], v[54:55], v[236:237], v[228:229] op_sel_hi:[0,1,1]
	v_pk_fma_f32 v[230:231], v[54:55], v[238:239], v[230:231] op_sel_hi:[0,1,1]
	s_waitcnt vmcnt(28)
; DI f2_t cvt8lo(unsigned w) { return __builtin_amdgcn_cvt_pk_f32_fp8(w, false); }
; DI f2_t cvt8hi(unsigned w) { return __builtin_amdgcn_cvt_pk_f32_fp8(w, true); }
; DI void phase11(const Params& p, char* smem, int rep) {
;     ...
;         for (int k = 0; k < 16; ++k) {
;           const f2_t a2 = {aa[k], aa[k]};
; #pragma unroll
;           for (int d = 0; d < 4; ++d) { const unsigned ww = rows[k][d]; o[2 * d] += a2 * cvt8lo(ww); o[2 * d + 1] += a2 * cvt8hi(ww); }
;         }
	v_cvt_pk_f32_fp8_e32 v[232:233], v96
	v_cvt_pk_f32_fp8_sdwa v[234:235], v96 src0_sel:WORD_1
	v_pk_fma_f32 v[216:217], v[54:55], v[232:233], v[216:217] op_sel:[1,0,0]
	v_pk_fma_f32 v[218:219], v[54:55], v[234:235], v[218:219] op_sel:[1,0,0]
	v_cvt_pk_f32_fp8_e32 v[236:237], v97
	v_cvt_pk_f32_fp8_sdwa v[238:239], v97 src0_sel:WORD_1
	v_pk_fma_f32 v[220:221], v[54:55], v[236:237], v[220:221] op_sel:[1,0,0]
	v_pk_fma_f32 v[222:223], v[54:55], v[238:239], v[222:223] op_sel:[1,0,0]
	v_cvt_pk_f32_fp8_e32 v[232:233], v98
	v_cvt_pk_f32_fp8_sdwa v[234:235], v98 src0_sel:WORD_1
	v_pk_fma_f32 v[224:225], v[54:55], v[232:233], v[224:225] op_sel:[1,0,0]
	v_pk_fma_f32 v[226:227], v[54:55], v[234:235], v[226:227] op_sel:[1,0,0]
	v_cvt_pk_f32_fp8_e32 v[236:237], v99
	v_cvt_pk_f32_fp8_sdwa v[238:239], v99 src0_sel:WORD_1
	v_pk_fma_f32 v[228:229], v[54:55], v[236:237], v[228:229] op_sel:[1,0,0]
	v_pk_fma_f32 v[230:231], v[54:55], v[238:239], v[230:231] op_sel:[1,0,0]
	s_waitcnt vmcnt(27)
	v_cvt_pk_f32_fp8_e32 v[232:233], v100
	v_cvt_pk_f32_fp8_sdwa v[234:235], v100 src0_sel:WORD_1
	v_pk_fma_f32 v[216:217], v[56:57], v[232:233], v[216:217] op_sel_hi:[0,1,1]
	v_pk_fma_f32 v[218:219], v[56:57], v[234:235], v[218:219] op_sel_hi:[0,1,1]
	v_cvt_pk_f32_fp8_e32 v[236:237], v101
	v_cvt_pk_f32_fp8_sdwa v[238:239], v101 src0_sel:WORD_1
	v_pk_fma_f32 v[220:221], v[56:57], v[236:237], v[220:221] op_sel_hi:[0,1,1]
	v_pk_fma_f32 v[222:223], v[56:57], v[238:239], v[222:223] op_sel_hi:[0,1,1]
	v_cvt_pk_f32_fp8_e32 v[232:233], v102
	v_cvt_pk_f32_fp8_sdwa v[234:235], v102 src0_sel:WORD_1
	v_pk_fma_f32 v[224:225], v[56:57], v[232:233], v[224:225] op_sel_hi:[0,1,1]
	v_pk_fma_f32 v[226:227], v[56:57], v[234:235], v[226:227] op_sel_hi:[0,1,1]
	v_cvt_pk_f32_fp8_e32 v[236:237], v103
	v_cvt_pk_f32_fp8_sdwa v[238:239], v103 src0_sel:WORD_1
	v_pk_fma_f32 v[228:229], v[56:57], v[236:237], v[228:229] op_sel_hi:[0,1,1]
	v_pk_fma_f32 v[230:231], v[56:57], v[238:239], v[230:231] op_sel_hi:[0,1,1]
	s_waitcnt vmcnt(26)
	v_cvt_pk_f32_fp8_e32 v[232:233], v104
	v_cvt_pk_f32_fp8_sdwa v[234:235], v104 src0_sel:WORD_1
	v_pk_fma_f32 v[216:217], v[56:57], v[232:233], v[216:217] op_sel:[1,0,0]
	v_pk_fma_f32 v[218:219], v[56:57], v[234:235], v[218:219] op_sel:[1,0,0]
	v_cvt_pk_f32_fp8_e32 v[236:237], v105
	v_cvt_pk_f32_fp8_sdwa v[238:239], v105 src0_sel:WORD_1
	v_pk_fma_f32 v[220:221], v[56:57], v[236:237], v[220:221] op_sel:[1,0,0]
	v_pk_fma_f32 v[222:223], v[56:57], v[238:239], v[222:223] op_sel:[1,0,0]
	v_cvt_pk_f32_fp8_e32 v[232:233], v106
	v_cvt_pk_f32_fp8_sdwa v[234:235], v106 src0_sel:WORD_1
	v_pk_fma_f32 v[224:225], v[56:57], v[232:233], v[224:225] op_sel:[1,0,0]
	v_pk_fma_f32 v[226:227], v[56:57], v[234:235], v[226:227] op_sel:[1,0,0]
	v_cvt_pk_f32_fp8_e32 v[236:237], v107
	v_cvt_pk_f32_fp8_sdwa v[238:239], v107 src0_sel:WORD_1
	v_pk_fma_f32 v[228:229], v[56:57], v[236:237], v[228:229] op_sel:[1,0,0]
	v_pk_fma_f32 v[230:231], v[56:57], v[238:239], v[230:231] op_sel:[1,0,0]
	s_waitcnt vmcnt(25)
	v_cvt_pk_f32_fp8_e32 v[232:233], v108
	v_cvt_pk_f32_fp8_sdwa v[234:235], v108 src0_sel:WORD_1
	v_pk_fma_f32 v[216:217], v[58:59], v[232:233], v[216:217] op_sel_hi:[0,1,1]
	v_pk_fma_f32 v[218:219], v[58:59], v[234:235], v[218:219] op_sel_hi:[0,1,1]
	v_cvt_pk_f32_fp8_e32 v[236:237], v109
	v_cvt_pk_f32_fp8_sdwa v[238:239], v109 src0_sel:WORD_1
	v_pk_fma_f32 v[220:221], v[58:59], v[236:237], v[220:221] op_sel_hi:[0,1,1]
	v_pk_fma_f32 v[222:223], v[58:59], v[238:239], v[222:223] op_sel_hi:[0,1,1]
	v_cvt_pk_f32_fp8_e32 v[232:233], v110
	v_cvt_pk_f32_fp8_sdwa v[234:235], v110 src0_sel:WORD_1
	v_pk_fma_f32 v[224:225], v[58:59], v[232:233], v[224:225] op_sel_hi:[0,1,1]
	v_pk_fma_f32 v[226:227], v[58:59], v[234:235], v[226:227] op_sel_hi:[0,1,1]
	v_cvt_pk_f32_fp8_e32 v[236:237], v111
	v_cvt_pk_f32_fp8_sdwa v[238:239], v111 src0_sel:WORD_1
	v_pk_fma_f32 v[228:229], v[58:59], v[236:237], v[228:229] op_sel_hi:[0,1,1]
	v_pk_fma_f32 v[230:231], v[58:59], v[238:239], v[230:231] op_sel_hi:[0,1,1]
	s_waitcnt vmcnt(24)
	v_cvt_pk_f32_fp8_e32 v[232:233], v112
	v_cvt_pk_f32_fp8_sdwa v[234:235], v112 src0_sel:WORD_1
	v_pk_fma_f32 v[216:217], v[58:59], v[232:233], v[216:217] op_sel:[1,0,0]
	v_pk_fma_f32 v[218:219], v[58:59], v[234:235], v[218:219] op_sel:[1,0,0]
	v_cvt_pk_f32_fp8_e32 v[236:237], v113
	v_cvt_pk_f32_fp8_sdwa v[238:239], v113 src0_sel:WORD_1
	v_pk_fma_f32 v[220:221], v[58:59], v[236:237], v[220:221] op_sel:[1,0,0]
	v_pk_fma_f32 v[222:223], v[58:59], v[238:239], v[222:223] op_sel:[1,0,0]
	v_cvt_pk_f32_fp8_e32 v[232:233], v114
	v_cvt_pk_f32_fp8_sdwa v[234:235], v114 src0_sel:WORD_1
	v_pk_fma_f32 v[224:225], v[58:59], v[232:233], v[224:225] op_sel:[1,0,0]
	v_pk_fma_f32 v[226:227], v[58:59], v[234:235], v[226:227] op_sel:[1,0,0]
	v_cvt_pk_f32_fp8_e32 v[236:237], v115
	v_cvt_pk_f32_fp8_sdwa v[238:239], v115 src0_sel:WORD_1
	v_pk_fma_f32 v[228:229], v[58:59], v[236:237], v[228:229] op_sel:[1,0,0]
	v_pk_fma_f32 v[230:231], v[58:59], v[238:239], v[230:231] op_sel:[1,0,0]
	s_waitcnt vmcnt(23)
	v_cvt_pk_f32_fp8_e32 v[232:233], v116
	v_cvt_pk_f32_fp8_sdwa v[234:235], v116 src0_sel:WORD_1
	v_pk_fma_f32 v[216:217], v[60:61], v[232:233], v[216:217] op_sel_hi:[0,1,1]
	v_pk_fma_f32 v[218:219], v[60:61], v[234:235], v[218:219] op_sel_hi:[0,1,1]
	v_cvt_pk_f32_fp8_e32 v[236:237], v117
	v_cvt_pk_f32_fp8_sdwa v[238:239], v117 src0_sel:WORD_1
	v_pk_fma_f32 v[220:221], v[60:61], v[236:237], v[220:221] op_sel_hi:[0,1,1]
	v_pk_fma_f32 v[222:223], v[60:61], v[238:239], v[222:223] op_sel_hi:[0,1,1]
	v_cvt_pk_f32_fp8_e32 v[232:233], v118
	v_cvt_pk_f32_fp8_sdwa v[234:235], v118 src0_sel:WORD_1
	v_pk_fma_f32 v[224:225], v[60:61], v[232:233], v[224:225] op_sel_hi:[0,1,1]
	v_pk_fma_f32 v[226:227], v[60:61], v[234:235], v[226:227] op_sel_hi:[0,1,1]
	v_cvt_pk_f32_fp8_e32 v[236:237], v119
	v_cvt_pk_f32_fp8_sdwa v[238:239], v119 src0_sel:WORD_1
	v_pk_fma_f32 v[228:229], v[60:61], v[236:237], v[228:229] op_sel_hi:[0,1,1]
	v_pk_fma_f32 v[230:231], v[60:61], v[238:239], v[230:231] op_sel_hi:[0,1,1]
	s_waitcnt vmcnt(22)
; DI f2_t cvt8lo(unsigned w) { return __builtin_amdgcn_cvt_pk_f32_fp8(w, false); }
; DI f2_t cvt8hi(unsigned w) { return __builtin_amdgcn_cvt_pk_f32_fp8(w, true); }
; DI void phase11(const Params& p, char* smem, int rep) {
;     ...
;         for (int k = 0; k < 16; ++k) {
;           const f2_t a2 = {aa[k], aa[k]};
; #pragma unroll
;           for (int d = 0; d < 4; ++d) { const unsigned ww = rows[k][d]; o[2 * d] += a2 * cvt8lo(ww); o[2 * d + 1] += a2 * cvt8hi(ww); }
;         }
	v_cvt_pk_f32_fp8_e32 v[232:233], v120
	v_cvt_pk_f32_fp8_sdwa v[234:235], v120 src0_sel:WORD_1
	v_pk_fma_f32 v[216:217], v[60:61], v[232:233], v[216:217] op_sel:[1,0,0]
	v_pk_fma_f32 v[218:219], v[60:61], v[234:235], v[218:219] op_sel:[1,0,0]
	v_cvt_pk_f32_fp8_e32 v[236:237], v121
	v_cvt_pk_f32_fp8_sdwa v[238:239], v121 src0_sel:WORD_1
	v_pk_fma_f32 v[220:221], v[60:61], v[236:237], v[220:221] op_sel:[1,0,0]
	v_pk_fma_f32 v[222:223], v[60:61], v[238:239], v[222:223] op_sel:[1,0,0]
	v_cvt_pk_f32_fp8_e32 v[232:233], v122
	v_cvt_pk_f32_fp8_sdwa v[234:235], v122 src0_sel:WORD_1
	v_pk_fma_f32 v[224:225], v[60:61], v[232:233], v[224:225] op_sel:[1,0,0]
	v_pk_fma_f32 v[226:227], v[60:61], v[234:235], v[226:227] op_sel:[1,0,0]
	v_cvt_pk_f32_fp8_e32 v[236:237], v123
	v_cvt_pk_f32_fp8_sdwa v[238:239], v123 src0_sel:WORD_1
	v_pk_fma_f32 v[228:229], v[60:61], v[236:237], v[228:229] op_sel:[1,0,0]
	v_pk_fma_f32 v[230:231], v[60:61], v[238:239], v[230:231] op_sel:[1,0,0]
	s_waitcnt vmcnt(21)
	v_cvt_pk_f32_fp8_e32 v[232:233], v124
	v_cvt_pk_f32_fp8_sdwa v[234:235], v124 src0_sel:WORD_1
	v_pk_fma_f32 v[216:217], v[62:63], v[232:233], v[216:217] op_sel_hi:[0,1,1]
	v_pk_fma_f32 v[218:219], v[62:63], v[234:235], v[218:219] op_sel_hi:[0,1,1]
	v_cvt_pk_f32_fp8_e32 v[236:237], v125
	v_cvt_pk_f32_fp8_sdwa v[238:239], v125 src0_sel:WORD_1
	v_pk_fma_f32 v[220:221], v[62:63], v[236:237], v[220:221] op_sel_hi:[0,1,1]
	v_pk_fma_f32 v[222:223], v[62:63], v[238:239], v[222:223] op_sel_hi:[0,1,1]
	v_cvt_pk_f32_fp8_e32 v[232:233], v126
	v_cvt_pk_f32_fp8_sdwa v[234:235], v126 src0_sel:WORD_1
	v_pk_fma_f32 v[224:225], v[62:63], v[232:233], v[224:225] op_sel_hi:[0,1,1]
	v_pk_fma_f32 v[226:227], v[62:63], v[234:235], v[226:227] op_sel_hi:[0,1,1]
	v_cvt_pk_f32_fp8_e32 v[236:237], v127
	v_cvt_pk_f32_fp8_sdwa v[238:239], v127 src0_sel:WORD_1
	v_pk_fma_f32 v[228:229], v[62:63], v[236:237], v[228:229] op_sel_hi:[0,1,1]
	v_pk_fma_f32 v[230:231], v[62:63], v[238:239], v[230:231] op_sel_hi:[0,1,1]
	s_waitcnt vmcnt(20)
	v_cvt_pk_f32_fp8_e32 v[232:233], v128
	v_cvt_pk_f32_fp8_sdwa v[234:235], v128 src0_sel:WORD_1
	v_pk_fma_f32 v[216:217], v[62:63], v[232:233], v[216:217] op_sel:[1,0,0]
	v_pk_fma_f32 v[218:219], v[62:63], v[234:235], v[218:219] op_sel:[1,0,0]
	v_cvt_pk_f32_fp8_e32 v[236:237], v129
	v_cvt_pk_f32_fp8_sdwa v[238:239], v129 src0_sel:WORD_1
	v_pk_fma_f32 v[220:221], v[62:63], v[236:237], v[220:221] op_sel:[1,0,0]
	v_pk_fma_f32 v[222:223], v[62:63], v[238:239], v[222:223] op_sel:[1,0,0]
	v_cvt_pk_f32_fp8_e32 v[232:233], v130
	v_cvt_pk_f32_fp8_sdwa v[234:235], v130 src0_sel:WORD_1
	v_pk_fma_f32 v[224:225], v[62:63], v[232:233], v[224:225] op_sel:[1,0,0]
	v_pk_fma_f32 v[226:227], v[62:63], v[234:235], v[226:227] op_sel:[1,0,0]
	v_cvt_pk_f32_fp8_e32 v[236:237], v131
	v_cvt_pk_f32_fp8_sdwa v[238:239], v131 src0_sel:WORD_1
	v_pk_fma_f32 v[228:229], v[62:63], v[236:237], v[228:229] op_sel:[1,0,0]
	v_pk_fma_f32 v[230:231], v[62:63], v[238:239], v[230:231] op_sel:[1,0,0]
	s_waitcnt vmcnt(19)
	v_cvt_pk_f32_fp8_e32 v[232:233], v132
	v_cvt_pk_f32_fp8_sdwa v[234:235], v132 src0_sel:WORD_1
	v_pk_fma_f32 v[216:217], v[64:65], v[232:233], v[216:217] op_sel_hi:[0,1,1]
	v_pk_fma_f32 v[218:219], v[64:65], v[234:235], v[218:219] op_sel_hi:[0,1,1]
	v_cvt_pk_f32_fp8_e32 v[236:237], v133
	v_cvt_pk_f32_fp8_sdwa v[238:239], v133 src0_sel:WORD_1
	v_pk_fma_f32 v[220:221], v[64:65], v[236:237], v[220:221] op_sel_hi:[0,1,1]
	v_pk_fma_f32 v[222:223], v[64:65], v[238:239], v[222:223] op_sel_hi:[0,1,1]
	v_cvt_pk_f32_fp8_e32 v[232:233], v134
	v_cvt_pk_f32_fp8_sdwa v[234:235], v134 src0_sel:WORD_1
	v_pk_fma_f32 v[224:225], v[64:65], v[232:233], v[224:225] op_sel_hi:[0,1,1]
	v_pk_fma_f32 v[226:227], v[64:65], v[234:235], v[226:227] op_sel_hi:[0,1,1]
	v_cvt_pk_f32_fp8_e32 v[236:237], v135
	v_cvt_pk_f32_fp8_sdwa v[238:239], v135 src0_sel:WORD_1
	v_pk_fma_f32 v[228:229], v[64:65], v[236:237], v[228:229] op_sel_hi:[0,1,1]
	v_pk_fma_f32 v[230:231], v[64:65], v[238:239], v[230:231] op_sel_hi:[0,1,1]
	s_waitcnt vmcnt(18)
	v_cvt_pk_f32_fp8_e32 v[232:233], v136
	v_cvt_pk_f32_fp8_sdwa v[234:235], v136 src0_sel:WORD_1
	v_pk_fma_f32 v[216:217], v[64:65], v[232:233], v[216:217] op_sel:[1,0,0]
	v_pk_fma_f32 v[218:219], v[64:65], v[234:235], v[218:219] op_sel:[1,0,0]
	v_cvt_pk_f32_fp8_e32 v[236:237], v137
	v_cvt_pk_f32_fp8_sdwa v[238:239], v137 src0_sel:WORD_1
	v_pk_fma_f32 v[220:221], v[64:65], v[236:237], v[220:221] op_sel:[1,0,0]
	v_pk_fma_f32 v[222:223], v[64:65], v[238:239], v[222:223] op_sel:[1,0,0]
	v_cvt_pk_f32_fp8_e32 v[232:233], v138
	v_cvt_pk_f32_fp8_sdwa v[234:235], v138 src0_sel:WORD_1
	v_pk_fma_f32 v[224:225], v[64:65], v[232:233], v[224:225] op_sel:[1,0,0]
	v_pk_fma_f32 v[226:227], v[64:65], v[234:235], v[226:227] op_sel:[1,0,0]
	v_cvt_pk_f32_fp8_e32 v[236:237], v139
	v_cvt_pk_f32_fp8_sdwa v[238:239], v139 src0_sel:WORD_1
	v_pk_fma_f32 v[228:229], v[64:65], v[236:237], v[228:229] op_sel:[1,0,0]
	v_pk_fma_f32 v[230:231], v[64:65], v[238:239], v[230:231] op_sel:[1,0,0]
	s_waitcnt vmcnt(17)
	v_cvt_pk_f32_fp8_e32 v[232:233], v140
	v_cvt_pk_f32_fp8_sdwa v[234:235], v140 src0_sel:WORD_1
	v_pk_fma_f32 v[216:217], v[66:67], v[232:233], v[216:217] op_sel_hi:[0,1,1]
	v_pk_fma_f32 v[218:219], v[66:67], v[234:235], v[218:219] op_sel_hi:[0,1,1]
	v_cvt_pk_f32_fp8_e32 v[236:237], v141
	v_cvt_pk_f32_fp8_sdwa v[238:239], v141 src0_sel:WORD_1
	v_pk_fma_f32 v[220:221], v[66:67], v[236:237], v[220:221] op_sel_hi:[0,1,1]
	v_pk_fma_f32 v[222:223], v[66:67], v[238:239], v[222:223] op_sel_hi:[0,1,1]
	v_cvt_pk_f32_fp8_e32 v[232:233], v142
	v_cvt_pk_f32_fp8_sdwa v[234:235], v142 src0_sel:WORD_1
	v_pk_fma_f32 v[224:225], v[66:67], v[232:233], v[224:225] op_sel_hi:[0,1,1]
	v_pk_fma_f32 v[226:227], v[66:67], v[234:235], v[226:227] op_sel_hi:[0,1,1]
	v_cvt_pk_f32_fp8_e32 v[236:237], v143
	v_cvt_pk_f32_fp8_sdwa v[238:239], v143 src0_sel:WORD_1
	v_pk_fma_f32 v[228:229], v[66:67], v[236:237], v[228:229] op_sel_hi:[0,1,1]
	v_pk_fma_f32 v[230:231], v[66:67], v[238:239], v[230:231] op_sel_hi:[0,1,1]
	s_waitcnt vmcnt(16)
; DI f2_t cvt8lo(unsigned w) { return __builtin_amdgcn_cvt_pk_f32_fp8(w, false); }
; DI f2_t cvt8hi(unsigned w) { return __builtin_amdgcn_cvt_pk_f32_fp8(w, true); }
; DI void wave_lds_sync() { asm volatile("s_waitcnt lgkmcnt(0)" ::: "memory"); __builtin_amdgcn_wave_barrier(); }
; DI void phase11(const Params& p, char* smem, int rep) {
;     ...
;       lw[(lane & 3) * 32 + (lane >> 2)] = i0; lw[(lane & 3) * 32 + 16 + (lane >> 2)] = i1;
;       lf[(lane & 3) * 32 + (lane >> 2)] = a0; lf[(lane & 3) * 32 + 16 + (lane >> 2)] = a1;
;       wave_lds_sync();
;       f2_t o[8];
; #pragma unroll
;       for (int i = 0; i < 8; ++i) o[i] = f2_t{0.f, 0.f};
;       const unsigned char* vb = V8 + s * 256 + l15 * 16;
; #pragma unroll
;       for (int batch = 0; batch < 2; ++batch) {
;         int ida[16]; float aa[16];
; #pragma unroll
;         for (int q = 0; q < 4; ++q) {
;           const int4 v = *(const int4*)(lw + g * 32 + batch * 16 + q * 4); ida[q * 4] = v.x; ida[q * 4 + 1] = v.y; ida[q * 4 + 2] = v.z; ida[q * 4 + 3] = v.w;
;           const float4 f = *(const float4*)(lf + g * 32 + batch * 16 + q * 4); aa[q * 4] = f.x; aa[q * 4 + 1] = f.y; aa[q * 4 + 2] = f.z; aa[q * 4 + 3] = f.w;
;         }
;         u32x4 rows[16];
; #pragma unroll
;         for (int k = 0; k < 16; ++k) rows[k] = *(const u32x4*)(vb + (size_t)ida[k] * 2048);
; #pragma unroll
;         for (int k = 0; k < 16; ++k) {
;           const f2_t a2 = {aa[k], aa[k]};
; #pragma unroll
;           for (int d = 0; d < 4; ++d) { const unsigned ww = rows[k][d]; o[2 * d] += a2 * cvt8lo(ww); o[2 * d + 1] += a2 * cvt8hi(ww); }
	v_cvt_pk_f32_fp8_e32 v[232:233], v144
	v_cvt_pk_f32_fp8_sdwa v[234:235], v144 src0_sel:WORD_1
	v_pk_fma_f32 v[216:217], v[66:67], v[232:233], v[216:217] op_sel:[1,0,0]
	v_pk_fma_f32 v[218:219], v[66:67], v[234:235], v[218:219] op_sel:[1,0,0]
	v_cvt_pk_f32_fp8_e32 v[236:237], v145
	v_cvt_pk_f32_fp8_sdwa v[238:239], v145 src0_sel:WORD_1
	v_pk_fma_f32 v[220:221], v[66:67], v[236:237], v[220:221] op_sel:[1,0,0]
	v_pk_fma_f32 v[222:223], v[66:67], v[238:239], v[222:223] op_sel:[1,0,0]
	v_cvt_pk_f32_fp8_e32 v[232:233], v146
	v_cvt_pk_f32_fp8_sdwa v[234:235], v146 src0_sel:WORD_1
	v_pk_fma_f32 v[224:225], v[66:67], v[232:233], v[224:225] op_sel:[1,0,0]
	v_pk_fma_f32 v[226:227], v[66:67], v[234:235], v[226:227] op_sel:[1,0,0]
	v_cvt_pk_f32_fp8_e32 v[236:237], v147
	v_cvt_pk_f32_fp8_sdwa v[238:239], v147 src0_sel:WORD_1
	v_pk_fma_f32 v[228:229], v[66:67], v[236:237], v[228:229] op_sel:[1,0,0]
	v_pk_fma_f32 v[230:231], v[66:67], v[238:239], v[230:231] op_sel:[1,0,0]
	ds_write2_b32 v5, v10, v11 offset0:4 offset1:20
	ds_write2_b32 v5, v12, v13 offset0:132 offset1:148
	s_waitcnt lgkmcnt(0)
	ds_read_b128 v[20:23], v6 offset:16
	ds_read_b128 v[24:27], v6 offset:32
	ds_read_b128 v[28:31], v6 offset:48
	ds_read_b128 v[32:35], v6 offset:64
	ds_read_b128 v[36:39], v6 offset:80
	ds_read_b128 v[40:43], v6 offset:96
	ds_read_b128 v[44:47], v6 offset:112
	ds_read_b128 v[48:51], v6 offset:128
	s_waitcnt vmcnt(15)
	v_cvt_pk_f32_fp8_e32 v[232:233], v148
	v_cvt_pk_f32_fp8_sdwa v[234:235], v148 src0_sel:WORD_1
	v_pk_fma_f32 v[216:217], v[68:69], v[232:233], v[216:217] op_sel_hi:[0,1,1]
	v_pk_fma_f32 v[218:219], v[68:69], v[234:235], v[218:219] op_sel_hi:[0,1,1]
	v_cvt_pk_f32_fp8_e32 v[236:237], v149
	v_cvt_pk_f32_fp8_sdwa v[238:239], v149 src0_sel:WORD_1
	v_pk_fma_f32 v[220:221], v[68:69], v[236:237], v[220:221] op_sel_hi:[0,1,1]
	v_pk_fma_f32 v[222:223], v[68:69], v[238:239], v[222:223] op_sel_hi:[0,1,1]
	v_cvt_pk_f32_fp8_e32 v[232:233], v150
	v_cvt_pk_f32_fp8_sdwa v[234:235], v150 src0_sel:WORD_1
	v_pk_fma_f32 v[224:225], v[68:69], v[232:233], v[224:225] op_sel_hi:[0,1,1]
	v_pk_fma_f32 v[226:227], v[68:69], v[234:235], v[226:227] op_sel_hi:[0,1,1]
	v_cvt_pk_f32_fp8_e32 v[236:237], v151
	v_cvt_pk_f32_fp8_sdwa v[238:239], v151 src0_sel:WORD_1
	v_pk_fma_f32 v[228:229], v[68:69], v[236:237], v[228:229] op_sel_hi:[0,1,1]
	v_pk_fma_f32 v[230:231], v[68:69], v[238:239], v[230:231] op_sel_hi:[0,1,1]
	s_waitcnt vmcnt(14)
	v_cvt_pk_f32_fp8_e32 v[232:233], v152
	v_cvt_pk_f32_fp8_sdwa v[234:235], v152 src0_sel:WORD_1
	v_pk_fma_f32 v[216:217], v[68:69], v[232:233], v[216:217] op_sel:[1,0,0]
	v_pk_fma_f32 v[218:219], v[68:69], v[234:235], v[218:219] op_sel:[1,0,0]
	v_cvt_pk_f32_fp8_e32 v[236:237], v153
	v_cvt_pk_f32_fp8_sdwa v[238:239], v153 src0_sel:WORD_1
	v_pk_fma_f32 v[220:221], v[68:69], v[236:237], v[220:221] op_sel:[1,0,0]
	v_pk_fma_f32 v[222:223], v[68:69], v[238:239], v[222:223] op_sel:[1,0,0]
	v_cvt_pk_f32_fp8_e32 v[232:233], v154
	v_cvt_pk_f32_fp8_sdwa v[234:235], v154 src0_sel:WORD_1
	v_pk_fma_f32 v[224:225], v[68:69], v[232:233], v[224:225] op_sel:[1,0,0]
	v_pk_fma_f32 v[226:227], v[68:69], v[234:235], v[226:227] op_sel:[1,0,0]
	v_cvt_pk_f32_fp8_e32 v[236:237], v155
	v_cvt_pk_f32_fp8_sdwa v[238:239], v155 src0_sel:WORD_1
	v_pk_fma_f32 v[228:229], v[68:69], v[236:237], v[228:229] op_sel:[1,0,0]
	v_pk_fma_f32 v[230:231], v[68:69], v[238:239], v[230:231] op_sel:[1,0,0]
	s_waitcnt vmcnt(13)
	v_cvt_pk_f32_fp8_e32 v[232:233], v156
	v_cvt_pk_f32_fp8_sdwa v[234:235], v156 src0_sel:WORD_1
	v_pk_fma_f32 v[216:217], v[70:71], v[232:233], v[216:217] op_sel_hi:[0,1,1]
	v_pk_fma_f32 v[218:219], v[70:71], v[234:235], v[218:219] op_sel_hi:[0,1,1]
	v_cvt_pk_f32_fp8_e32 v[236:237], v157
	v_cvt_pk_f32_fp8_sdwa v[238:239], v157 src0_sel:WORD_1
	v_pk_fma_f32 v[220:221], v[70:71], v[236:237], v[220:221] op_sel_hi:[0,1,1]
	v_pk_fma_f32 v[222:223], v[70:71], v[238:239], v[222:223] op_sel_hi:[0,1,1]
	v_cvt_pk_f32_fp8_e32 v[232:233], v158
	v_cvt_pk_f32_fp8_sdwa v[234:235], v158 src0_sel:WORD_1
	v_pk_fma_f32 v[224:225], v[70:71], v[232:233], v[224:225] op_sel_hi:[0,1,1]
	v_pk_fma_f32 v[226:227], v[70:71], v[234:235], v[226:227] op_sel_hi:[0,1,1]
	v_cvt_pk_f32_fp8_e32 v[236:237], v159
	v_cvt_pk_f32_fp8_sdwa v[238:239], v159 src0_sel:WORD_1
	v_pk_fma_f32 v[228:229], v[70:71], v[236:237], v[228:229] op_sel_hi:[0,1,1]
	v_pk_fma_f32 v[230:231], v[70:71], v[238:239], v[230:231] op_sel_hi:[0,1,1]
	s_waitcnt vmcnt(12)
	v_cvt_pk_f32_fp8_e32 v[232:233], v160
	v_cvt_pk_f32_fp8_sdwa v[234:235], v160 src0_sel:WORD_1
	v_pk_fma_f32 v[216:217], v[70:71], v[232:233], v[216:217] op_sel:[1,0,0]
	v_pk_fma_f32 v[218:219], v[70:71], v[234:235], v[218:219] op_sel:[1,0,0]
	v_cvt_pk_f32_fp8_e32 v[236:237], v161
	v_cvt_pk_f32_fp8_sdwa v[238:239], v161 src0_sel:WORD_1
	v_pk_fma_f32 v[220:221], v[70:71], v[236:237], v[220:221] op_sel:[1,0,0]
	v_pk_fma_f32 v[222:223], v[70:71], v[238:239], v[222:223] op_sel:[1,0,0]
	v_cvt_pk_f32_fp8_e32 v[232:233], v162
	v_cvt_pk_f32_fp8_sdwa v[234:235], v162 src0_sel:WORD_1
	v_pk_fma_f32 v[224:225], v[70:71], v[232:233], v[224:225] op_sel:[1,0,0]
	v_pk_fma_f32 v[226:227], v[70:71], v[234:235], v[226:227] op_sel:[1,0,0]
	v_cvt_pk_f32_fp8_e32 v[236:237], v163
	v_cvt_pk_f32_fp8_sdwa v[238:239], v163 src0_sel:WORD_1
	v_pk_fma_f32 v[228:229], v[70:71], v[236:237], v[228:229] op_sel:[1,0,0]
	v_pk_fma_f32 v[230:231], v[70:71], v[238:239], v[230:231] op_sel:[1,0,0]
	s_waitcnt vmcnt(11)
; DI f2_t cvt8lo(unsigned w) { return __builtin_amdgcn_cvt_pk_f32_fp8(w, false); }
; DI f2_t cvt8hi(unsigned w) { return __builtin_amdgcn_cvt_pk_f32_fp8(w, true); }
; DI void phase11(const Params& p, char* smem, int rep) {
;     ...
;         for (int k = 0; k < 16; ++k) {
;           const f2_t a2 = {aa[k], aa[k]};
; #pragma unroll
;           for (int d = 0; d < 4; ++d) { const unsigned ww = rows[k][d]; o[2 * d] += a2 * cvt8lo(ww); o[2 * d + 1] += a2 * cvt8hi(ww); }
;         }
	v_cvt_pk_f32_fp8_e32 v[232:233], v164
	v_cvt_pk_f32_fp8_sdwa v[234:235], v164 src0_sel:WORD_1
	v_pk_fma_f32 v[216:217], v[72:73], v[232:233], v[216:217] op_sel_hi:[0,1,1]
	v_pk_fma_f32 v[218:219], v[72:73], v[234:235], v[218:219] op_sel_hi:[0,1,1]
	v_cvt_pk_f32_fp8_e32 v[236:237], v165
	v_cvt_pk_f32_fp8_sdwa v[238:239], v165 src0_sel:WORD_1
	v_pk_fma_f32 v[220:221], v[72:73], v[236:237], v[220:221] op_sel_hi:[0,1,1]
	v_pk_fma_f32 v[222:223], v[72:73], v[238:239], v[222:223] op_sel_hi:[0,1,1]
	v_cvt_pk_f32_fp8_e32 v[232:233], v166
	v_cvt_pk_f32_fp8_sdwa v[234:235], v166 src0_sel:WORD_1
	v_pk_fma_f32 v[224:225], v[72:73], v[232:233], v[224:225] op_sel_hi:[0,1,1]
	v_pk_fma_f32 v[226:227], v[72:73], v[234:235], v[226:227] op_sel_hi:[0,1,1]
	v_cvt_pk_f32_fp8_e32 v[236:237], v167
	v_cvt_pk_f32_fp8_sdwa v[238:239], v167 src0_sel:WORD_1
	v_pk_fma_f32 v[228:229], v[72:73], v[236:237], v[228:229] op_sel_hi:[0,1,1]
	v_pk_fma_f32 v[230:231], v[72:73], v[238:239], v[230:231] op_sel_hi:[0,1,1]
	s_waitcnt vmcnt(10)
	v_cvt_pk_f32_fp8_e32 v[232:233], v168
	v_cvt_pk_f32_fp8_sdwa v[234:235], v168 src0_sel:WORD_1
	v_pk_fma_f32 v[216:217], v[72:73], v[232:233], v[216:217] op_sel:[1,0,0]
	v_pk_fma_f32 v[218:219], v[72:73], v[234:235], v[218:219] op_sel:[1,0,0]
	v_cvt_pk_f32_fp8_e32 v[236:237], v169
	v_cvt_pk_f32_fp8_sdwa v[238:239], v169 src0_sel:WORD_1
	v_pk_fma_f32 v[220:221], v[72:73], v[236:237], v[220:221] op_sel:[1,0,0]
	v_pk_fma_f32 v[222:223], v[72:73], v[238:239], v[222:223] op_sel:[1,0,0]
	v_cvt_pk_f32_fp8_e32 v[232:233], v170
	v_cvt_pk_f32_fp8_sdwa v[234:235], v170 src0_sel:WORD_1
	v_pk_fma_f32 v[224:225], v[72:73], v[232:233], v[224:225] op_sel:[1,0,0]
	v_pk_fma_f32 v[226:227], v[72:73], v[234:235], v[226:227] op_sel:[1,0,0]
	v_cvt_pk_f32_fp8_e32 v[236:237], v171
	v_cvt_pk_f32_fp8_sdwa v[238:239], v171 src0_sel:WORD_1
	v_pk_fma_f32 v[228:229], v[72:73], v[236:237], v[228:229] op_sel:[1,0,0]
	v_pk_fma_f32 v[230:231], v[72:73], v[238:239], v[230:231] op_sel:[1,0,0]
	s_waitcnt vmcnt(9)
	v_cvt_pk_f32_fp8_e32 v[232:233], v172
	v_cvt_pk_f32_fp8_sdwa v[234:235], v172 src0_sel:WORD_1
	v_pk_fma_f32 v[216:217], v[74:75], v[232:233], v[216:217] op_sel_hi:[0,1,1]
	v_pk_fma_f32 v[218:219], v[74:75], v[234:235], v[218:219] op_sel_hi:[0,1,1]
	v_cvt_pk_f32_fp8_e32 v[236:237], v173
	v_cvt_pk_f32_fp8_sdwa v[238:239], v173 src0_sel:WORD_1
	v_pk_fma_f32 v[220:221], v[74:75], v[236:237], v[220:221] op_sel_hi:[0,1,1]
	v_pk_fma_f32 v[222:223], v[74:75], v[238:239], v[222:223] op_sel_hi:[0,1,1]
	v_cvt_pk_f32_fp8_e32 v[232:233], v174
	v_cvt_pk_f32_fp8_sdwa v[234:235], v174 src0_sel:WORD_1
	v_pk_fma_f32 v[224:225], v[74:75], v[232:233], v[224:225] op_sel_hi:[0,1,1]
	v_pk_fma_f32 v[226:227], v[74:75], v[234:235], v[226:227] op_sel_hi:[0,1,1]
	v_cvt_pk_f32_fp8_e32 v[236:237], v175
	v_cvt_pk_f32_fp8_sdwa v[238:239], v175 src0_sel:WORD_1
	v_pk_fma_f32 v[228:229], v[74:75], v[236:237], v[228:229] op_sel_hi:[0,1,1]
	v_pk_fma_f32 v[230:231], v[74:75], v[238:239], v[230:231] op_sel_hi:[0,1,1]
	s_waitcnt vmcnt(8)
	v_cvt_pk_f32_fp8_e32 v[232:233], v176
	v_cvt_pk_f32_fp8_sdwa v[234:235], v176 src0_sel:WORD_1
	v_pk_fma_f32 v[216:217], v[74:75], v[232:233], v[216:217] op_sel:[1,0,0]
	v_pk_fma_f32 v[218:219], v[74:75], v[234:235], v[218:219] op_sel:[1,0,0]
	v_cvt_pk_f32_fp8_e32 v[236:237], v177
	v_cvt_pk_f32_fp8_sdwa v[238:239], v177 src0_sel:WORD_1
	v_pk_fma_f32 v[220:221], v[74:75], v[236:237], v[220:221] op_sel:[1,0,0]
	v_pk_fma_f32 v[222:223], v[74:75], v[238:239], v[222:223] op_sel:[1,0,0]
	v_cvt_pk_f32_fp8_e32 v[232:233], v178
	v_cvt_pk_f32_fp8_sdwa v[234:235], v178 src0_sel:WORD_1
	v_pk_fma_f32 v[224:225], v[74:75], v[232:233], v[224:225] op_sel:[1,0,0]
	v_pk_fma_f32 v[226:227], v[74:75], v[234:235], v[226:227] op_sel:[1,0,0]
	v_cvt_pk_f32_fp8_e32 v[236:237], v179
	v_cvt_pk_f32_fp8_sdwa v[238:239], v179 src0_sel:WORD_1
	v_pk_fma_f32 v[228:229], v[74:75], v[236:237], v[228:229] op_sel:[1,0,0]
	v_pk_fma_f32 v[230:231], v[74:75], v[238:239], v[230:231] op_sel:[1,0,0]
	s_waitcnt vmcnt(7)
	v_cvt_pk_f32_fp8_e32 v[232:233], v180
	v_cvt_pk_f32_fp8_sdwa v[234:235], v180 src0_sel:WORD_1
	v_pk_fma_f32 v[216:217], v[76:77], v[232:233], v[216:217] op_sel_hi:[0,1,1]
	v_pk_fma_f32 v[218:219], v[76:77], v[234:235], v[218:219] op_sel_hi:[0,1,1]
	v_cvt_pk_f32_fp8_e32 v[236:237], v181
	v_cvt_pk_f32_fp8_sdwa v[238:239], v181 src0_sel:WORD_1
	v_pk_fma_f32 v[220:221], v[76:77], v[236:237], v[220:221] op_sel_hi:[0,1,1]
	v_pk_fma_f32 v[222:223], v[76:77], v[238:239], v[222:223] op_sel_hi:[0,1,1]
	v_cvt_pk_f32_fp8_e32 v[232:233], v182
	v_cvt_pk_f32_fp8_sdwa v[234:235], v182 src0_sel:WORD_1
	v_pk_fma_f32 v[224:225], v[76:77], v[232:233], v[224:225] op_sel_hi:[0,1,1]
	v_pk_fma_f32 v[226:227], v[76:77], v[234:235], v[226:227] op_sel_hi:[0,1,1]
	v_cvt_pk_f32_fp8_e32 v[236:237], v183
	v_cvt_pk_f32_fp8_sdwa v[238:239], v183 src0_sel:WORD_1
	v_pk_fma_f32 v[228:229], v[76:77], v[236:237], v[228:229] op_sel_hi:[0,1,1]
	v_pk_fma_f32 v[230:231], v[76:77], v[238:239], v[230:231] op_sel_hi:[0,1,1]
	s_waitcnt vmcnt(6)
	v_cvt_pk_f32_fp8_e32 v[232:233], v184
	v_cvt_pk_f32_fp8_sdwa v[234:235], v184 src0_sel:WORD_1
	v_pk_fma_f32 v[216:217], v[76:77], v[232:233], v[216:217] op_sel:[1,0,0]
	v_pk_fma_f32 v[218:219], v[76:77], v[234:235], v[218:219] op_sel:[1,0,0]
	v_cvt_pk_f32_fp8_e32 v[236:237], v185
	v_cvt_pk_f32_fp8_sdwa v[238:239], v185 src0_sel:WORD_1
	v_pk_fma_f32 v[220:221], v[76:77], v[236:237], v[220:221] op_sel:[1,0,0]
	v_pk_fma_f32 v[222:223], v[76:77], v[238:239], v[222:223] op_sel:[1,0,0]
	v_cvt_pk_f32_fp8_e32 v[232:233], v186
	v_cvt_pk_f32_fp8_sdwa v[234:235], v186 src0_sel:WORD_1
	v_pk_fma_f32 v[224:225], v[76:77], v[232:233], v[224:225] op_sel:[1,0,0]
	v_pk_fma_f32 v[226:227], v[76:77], v[234:235], v[226:227] op_sel:[1,0,0]
	v_cvt_pk_f32_fp8_e32 v[236:237], v187
	v_cvt_pk_f32_fp8_sdwa v[238:239], v187 src0_sel:WORD_1
	v_pk_fma_f32 v[228:229], v[76:77], v[236:237], v[228:229] op_sel:[1,0,0]
	v_pk_fma_f32 v[230:231], v[76:77], v[238:239], v[230:231] op_sel:[1,0,0]
	s_waitcnt vmcnt(5)
; DI f2_t cvt8lo(unsigned w) { return __builtin_amdgcn_cvt_pk_f32_fp8(w, false); }
; DI f2_t cvt8hi(unsigned w) { return __builtin_amdgcn_cvt_pk_f32_fp8(w, true); }
; DI void phase11(const Params& p, char* smem, int rep) {
;     ...
;         for (int k = 0; k < 16; ++k) {
;           const f2_t a2 = {aa[k], aa[k]};
; #pragma unroll
;           for (int d = 0; d < 4; ++d) { const unsigned ww = rows[k][d]; o[2 * d] += a2 * cvt8lo(ww); o[2 * d + 1] += a2 * cvt8hi(ww); }
;         }
	v_cvt_pk_f32_fp8_e32 v[232:233], v190
	v_cvt_pk_f32_fp8_sdwa v[234:235], v190 src0_sel:WORD_1
	v_pk_fma_f32 v[216:217], v[78:79], v[232:233], v[216:217] op_sel_hi:[0,1,1]
	v_pk_fma_f32 v[218:219], v[78:79], v[234:235], v[218:219] op_sel_hi:[0,1,1]
	v_cvt_pk_f32_fp8_e32 v[236:237], v191
	v_cvt_pk_f32_fp8_sdwa v[238:239], v191 src0_sel:WORD_1
	v_pk_fma_f32 v[220:221], v[78:79], v[236:237], v[220:221] op_sel_hi:[0,1,1]
	v_pk_fma_f32 v[222:223], v[78:79], v[238:239], v[222:223] op_sel_hi:[0,1,1]
	v_cvt_pk_f32_fp8_e32 v[232:233], v192
	v_cvt_pk_f32_fp8_sdwa v[234:235], v192 src0_sel:WORD_1
	v_pk_fma_f32 v[224:225], v[78:79], v[232:233], v[224:225] op_sel_hi:[0,1,1]
	v_pk_fma_f32 v[226:227], v[78:79], v[234:235], v[226:227] op_sel_hi:[0,1,1]
	v_cvt_pk_f32_fp8_e32 v[236:237], v193
	v_cvt_pk_f32_fp8_sdwa v[238:239], v193 src0_sel:WORD_1
	v_pk_fma_f32 v[228:229], v[78:79], v[236:237], v[228:229] op_sel_hi:[0,1,1]
	v_pk_fma_f32 v[230:231], v[78:79], v[238:239], v[230:231] op_sel_hi:[0,1,1]
	s_waitcnt vmcnt(4)
	v_cvt_pk_f32_fp8_e32 v[232:233], v194
	v_cvt_pk_f32_fp8_sdwa v[234:235], v194 src0_sel:WORD_1
	v_pk_fma_f32 v[216:217], v[78:79], v[232:233], v[216:217] op_sel:[1,0,0]
	v_pk_fma_f32 v[218:219], v[78:79], v[234:235], v[218:219] op_sel:[1,0,0]
	v_cvt_pk_f32_fp8_e32 v[236:237], v195
	v_cvt_pk_f32_fp8_sdwa v[238:239], v195 src0_sel:WORD_1
	v_pk_fma_f32 v[220:221], v[78:79], v[236:237], v[220:221] op_sel:[1,0,0]
	v_pk_fma_f32 v[222:223], v[78:79], v[238:239], v[222:223] op_sel:[1,0,0]
	v_cvt_pk_f32_fp8_e32 v[232:233], v196
	v_cvt_pk_f32_fp8_sdwa v[234:235], v196 src0_sel:WORD_1
	v_pk_fma_f32 v[224:225], v[78:79], v[232:233], v[224:225] op_sel:[1,0,0]
	v_pk_fma_f32 v[226:227], v[78:79], v[234:235], v[226:227] op_sel:[1,0,0]
	v_cvt_pk_f32_fp8_e32 v[236:237], v197
	v_cvt_pk_f32_fp8_sdwa v[238:239], v197 src0_sel:WORD_1
	v_pk_fma_f32 v[228:229], v[78:79], v[236:237], v[228:229] op_sel:[1,0,0]
	v_pk_fma_f32 v[230:231], v[78:79], v[238:239], v[230:231] op_sel:[1,0,0]
	s_waitcnt vmcnt(3)
	v_cvt_pk_f32_fp8_e32 v[232:233], v198
	v_cvt_pk_f32_fp8_sdwa v[234:235], v198 src0_sel:WORD_1
	v_pk_fma_f32 v[216:217], v[80:81], v[232:233], v[216:217] op_sel_hi:[0,1,1]
	v_pk_fma_f32 v[218:219], v[80:81], v[234:235], v[218:219] op_sel_hi:[0,1,1]
	v_cvt_pk_f32_fp8_e32 v[236:237], v199
	v_cvt_pk_f32_fp8_sdwa v[238:239], v199 src0_sel:WORD_1
	v_pk_fma_f32 v[220:221], v[80:81], v[236:237], v[220:221] op_sel_hi:[0,1,1]
	v_pk_fma_f32 v[222:223], v[80:81], v[238:239], v[222:223] op_sel_hi:[0,1,1]
	v_cvt_pk_f32_fp8_e32 v[232:233], v200
	v_cvt_pk_f32_fp8_sdwa v[234:235], v200 src0_sel:WORD_1
	v_pk_fma_f32 v[224:225], v[80:81], v[232:233], v[224:225] op_sel_hi:[0,1,1]
	v_pk_fma_f32 v[226:227], v[80:81], v[234:235], v[226:227] op_sel_hi:[0,1,1]
	v_cvt_pk_f32_fp8_e32 v[236:237], v201
	v_cvt_pk_f32_fp8_sdwa v[238:239], v201 src0_sel:WORD_1
	v_pk_fma_f32 v[228:229], v[80:81], v[236:237], v[228:229] op_sel_hi:[0,1,1]
	v_pk_fma_f32 v[230:231], v[80:81], v[238:239], v[230:231] op_sel_hi:[0,1,1]
	s_waitcnt vmcnt(2)
	v_cvt_pk_f32_fp8_e32 v[232:233], v202
	v_cvt_pk_f32_fp8_sdwa v[234:235], v202 src0_sel:WORD_1
	v_pk_fma_f32 v[216:217], v[80:81], v[232:233], v[216:217] op_sel:[1,0,0]
	v_pk_fma_f32 v[218:219], v[80:81], v[234:235], v[218:219] op_sel:[1,0,0]
	v_cvt_pk_f32_fp8_e32 v[236:237], v203
	v_cvt_pk_f32_fp8_sdwa v[238:239], v203 src0_sel:WORD_1
	v_pk_fma_f32 v[220:221], v[80:81], v[236:237], v[220:221] op_sel:[1,0,0]
	v_pk_fma_f32 v[222:223], v[80:81], v[238:239], v[222:223] op_sel:[1,0,0]
	v_cvt_pk_f32_fp8_e32 v[232:233], v204
	v_cvt_pk_f32_fp8_sdwa v[234:235], v204 src0_sel:WORD_1
	v_pk_fma_f32 v[224:225], v[80:81], v[232:233], v[224:225] op_sel:[1,0,0]
	v_pk_fma_f32 v[226:227], v[80:81], v[234:235], v[226:227] op_sel:[1,0,0]
	v_cvt_pk_f32_fp8_e32 v[236:237], v205
	v_cvt_pk_f32_fp8_sdwa v[238:239], v205 src0_sel:WORD_1
	v_pk_fma_f32 v[228:229], v[80:81], v[236:237], v[228:229] op_sel:[1,0,0]
	v_pk_fma_f32 v[230:231], v[80:81], v[238:239], v[230:231] op_sel:[1,0,0]
	s_waitcnt vmcnt(1)
	v_cvt_pk_f32_fp8_e32 v[232:233], v206
	v_cvt_pk_f32_fp8_sdwa v[234:235], v206 src0_sel:WORD_1
	v_pk_fma_f32 v[216:217], v[82:83], v[232:233], v[216:217] op_sel_hi:[0,1,1]
	v_pk_fma_f32 v[218:219], v[82:83], v[234:235], v[218:219] op_sel_hi:[0,1,1]
	v_cvt_pk_f32_fp8_e32 v[236:237], v207
	v_cvt_pk_f32_fp8_sdwa v[238:239], v207 src0_sel:WORD_1
	v_pk_fma_f32 v[220:221], v[82:83], v[236:237], v[220:221] op_sel_hi:[0,1,1]
	v_pk_fma_f32 v[222:223], v[82:83], v[238:239], v[222:223] op_sel_hi:[0,1,1]
	v_cvt_pk_f32_fp8_e32 v[232:233], v208
	v_cvt_pk_f32_fp8_sdwa v[234:235], v208 src0_sel:WORD_1
	v_pk_fma_f32 v[224:225], v[82:83], v[232:233], v[224:225] op_sel_hi:[0,1,1]
	v_pk_fma_f32 v[226:227], v[82:83], v[234:235], v[226:227] op_sel_hi:[0,1,1]
	v_cvt_pk_f32_fp8_e32 v[236:237], v209
	v_cvt_pk_f32_fp8_sdwa v[238:239], v209 src0_sel:WORD_1
	v_pk_fma_f32 v[228:229], v[82:83], v[236:237], v[228:229] op_sel_hi:[0,1,1]
	v_pk_fma_f32 v[230:231], v[82:83], v[238:239], v[230:231] op_sel_hi:[0,1,1]
	s_waitcnt vmcnt(0)
; DI unsigned pk2(float a, float b) { f2_t v = {a, b}; bf2_t r = __builtin_convertvector(v, bf2_t); return __builtin_bit_cast(unsigned, r); }
; DI f2_t cvt8lo(unsigned w) { return __builtin_amdgcn_cvt_pk_f32_fp8(w, false); }
; DI f2_t cvt8hi(unsigned w) { return __builtin_amdgcn_cvt_pk_f32_fp8(w, true); }
; DI void phase11(const Params& p, char* smem, int rep) {
;     ...
;         for (int k = 0; k < 16; ++k) {
;           const f2_t a2 = {aa[k], aa[k]};
; #pragma unroll
;           for (int d = 0; d < 4; ++d) { const unsigned ww = rows[k][d]; o[2 * d] += a2 * cvt8lo(ww); o[2 * d + 1] += a2 * cvt8hi(ww); }
;         }
;       }
;       float ov[16];
; #pragma unroll
;       for (int d = 0; d < 4; ++d) { ov[4 * d] = o[2 * d].x; ov[4 * d + 1] = o[2 * d].y; ov[4 * d + 2] = o[2 * d + 1].x; ov[4 * d + 3] = o[2 * d + 1].y; }
;       float q8[8], q4[4];
; #pragma unroll
;       for (int k = 0; k < 8; ++k) q8[k] = (b5 ? ov[8 + k] : ov[k]) + __shfl_xor(b5 ? ov[k] : ov[8 + k], 32);
; #pragma unroll
;       for (int k = 0; k < 4; ++k) q4[k] = (b4 ? q8[4 + k] : q8[k]) + __shfl_xor(b4 ? q8[k] : q8[4 + k], 16);
;       *(uint2*)(OUTP + (size_t)tok * D_ + s * 256 + l15 * 16 + 8 * b5 + 4 * b4) = make_uint2(pk2(q4[0], q4[1]), pk2(q4[2], q4[3]));
	v_cvt_pk_f32_fp8_e32 v[232:233], v210
	v_cvt_pk_f32_fp8_sdwa v[234:235], v210 src0_sel:WORD_1
	v_pk_fma_f32 v[216:217], v[82:83], v[232:233], v[216:217] op_sel:[1,0,0]
	v_pk_fma_f32 v[218:219], v[82:83], v[234:235], v[218:219] op_sel:[1,0,0]
	v_cvt_pk_f32_fp8_e32 v[236:237], v211
	v_cvt_pk_f32_fp8_sdwa v[238:239], v211 src0_sel:WORD_1
	v_pk_fma_f32 v[220:221], v[82:83], v[236:237], v[220:221] op_sel:[1,0,0]
	v_pk_fma_f32 v[222:223], v[82:83], v[238:239], v[222:223] op_sel:[1,0,0]
	v_cvt_pk_f32_fp8_e32 v[232:233], v212
	v_cvt_pk_f32_fp8_sdwa v[234:235], v212 src0_sel:WORD_1
	v_pk_fma_f32 v[224:225], v[82:83], v[232:233], v[224:225] op_sel:[1,0,0]
	v_pk_fma_f32 v[226:227], v[82:83], v[234:235], v[226:227] op_sel:[1,0,0]
	v_cvt_pk_f32_fp8_e32 v[236:237], v213
	v_cvt_pk_f32_fp8_sdwa v[238:239], v213 src0_sel:WORD_1
	v_pk_fma_f32 v[228:229], v[82:83], v[236:237], v[228:229] op_sel:[1,0,0]
	v_pk_fma_f32 v[230:231], v[82:83], v[238:239], v[230:231] op_sel:[1,0,0]
	ds_read_b128 v[52:55], v6 offset:528
	ds_read_b128 v[56:59], v6 offset:544
	ds_read_b128 v[60:63], v6 offset:560
	ds_read_b128 v[64:67], v6 offset:576
	ds_read_b128 v[68:71], v6 offset:592
	ds_read_b128 v[72:75], v6 offset:608
	ds_read_b128 v[76:79], v6 offset:624
	ds_read_b128 v[80:83], v6 offset:640
	v_add_u32_e32 v214, s46, v4
	s_nop 0
	v_permlane32_swap_b32_e32 v216, v224
	v_permlane32_swap_b32_e32 v217, v225
	v_permlane32_swap_b32_e32 v218, v226
	v_permlane32_swap_b32_e32 v219, v227
	v_permlane32_swap_b32_e32 v220, v228
	v_permlane32_swap_b32_e32 v221, v229
	v_permlane32_swap_b32_e32 v222, v230
	v_permlane32_swap_b32_e32 v223, v231
	v_pk_add_f32 v[216:217], v[216:217], v[224:225]
	v_pk_add_f32 v[218:219], v[218:219], v[226:227]
	v_pk_add_f32 v[220:221], v[220:221], v[228:229]
	v_pk_add_f32 v[222:223], v[222:223], v[230:231]
	s_nop 1
	v_permlane16_swap_b32_e32 v216, v220
	v_permlane16_swap_b32_e32 v217, v221
	v_permlane16_swap_b32_e32 v218, v222
	v_permlane16_swap_b32_e32 v219, v223
	v_pk_add_f32 v[216:217], v[216:217], v[220:221]
	v_pk_add_f32 v[218:219], v[218:219], v[222:223]
	v_cvt_pk_bf16_f32 v232, v216, v217
	v_cvt_pk_bf16_f32 v233, v218, v219
	global_store_dwordx2 v214, v[232:233], s[14:15]
	s_add_i32 s54, s34, 1
	s_lshl_b32 s46, s54, 12
	s_add_i32 s46, s46, s24
	s_add_i32 s55, s34, 2
	s_lshl_b32 s47, s55, 9
	s_add_u32 s42, s6, s47
	s_addc_u32 s43, s7, 0
	s_add_u32 s44, s8, s47
	s_addc_u32 s45, s9, 0
	global_load_dword v10, v3, s[42:43]
	global_load_dword v11, v3, s[42:43] offset:256
	global_load_dword v12, v3, s[44:45]
	global_load_dword v13, v3, s[44:45] offset:256
	s_waitcnt lgkmcnt(0)
	v_lshl_add_u32 v20, v20, 11, v2
	v_lshl_add_u32 v21, v21, 11, v2
	v_lshl_add_u32 v22, v22, 11, v2
	v_lshl_add_u32 v23, v23, 11, v2
	v_lshl_add_u32 v24, v24, 11, v2
	v_lshl_add_u32 v25, v25, 11, v2
	v_lshl_add_u32 v26, v26, 11, v2
	v_lshl_add_u32 v27, v27, 11, v2
	v_lshl_add_u32 v28, v28, 11, v2
	v_lshl_add_u32 v29, v29, 11, v2
	v_lshl_add_u32 v30, v30, 11, v2
	v_lshl_add_u32 v31, v31, 11, v2
	v_lshl_add_u32 v32, v32, 11, v2
	v_lshl_add_u32 v33, v33, 11, v2
	v_lshl_add_u32 v34, v34, 11, v2
	v_lshl_add_u32 v35, v35, 11, v2
	v_lshl_add_u32 v36, v36, 11, v2
	v_lshl_add_u32 v37, v37, 11, v2
	v_lshl_add_u32 v38, v38, 11, v2
	v_lshl_add_u32 v39, v39, 11, v2
	v_lshl_add_u32 v40, v40, 11, v2
	v_lshl_add_u32 v41, v41, 11, v2
	v_lshl_add_u32 v42, v42, 11, v2
	v_lshl_add_u32 v43, v43, 11, v2
	v_lshl_add_u32 v44, v44, 11, v2
	v_lshl_add_u32 v45, v45, 11, v2
	v_lshl_add_u32 v46, v46, 11, v2
	v_lshl_add_u32 v47, v47, 11, v2
	v_lshl_add_u32 v48, v48, 11, v2
	v_lshl_add_u32 v49, v49, 11, v2
	v_lshl_add_u32 v50, v50, 11, v2
	v_lshl_add_u32 v51, v51, 11, v2
	global_load_dwordx4 v[84:87], v20, s[20:21]
	global_load_dwordx4 v[88:91], v21, s[20:21]
	global_load_dwordx4 v[92:95], v22, s[20:21]
	global_load_dwordx4 v[96:99], v23, s[20:21]
	global_load_dwordx4 v[100:103], v24, s[20:21]
	global_load_dwordx4 v[104:107], v25, s[20:21]
	global_load_dwordx4 v[108:111], v26, s[20:21]
	global_load_dwordx4 v[112:115], v27, s[20:21]
	global_load_dwordx4 v[116:119], v28, s[20:21]
	global_load_dwordx4 v[120:123], v29, s[20:21]
	global_load_dwordx4 v[124:127], v30, s[20:21]
	global_load_dwordx4 v[128:131], v31, s[20:21]
	global_load_dwordx4 v[132:135], v32, s[20:21]
	global_load_dwordx4 v[136:139], v33, s[20:21]
	global_load_dwordx4 v[140:143], v34, s[20:21]
	global_load_dwordx4 v[144:147], v35, s[20:21]
	global_load_dwordx4 v[148:151], v36, s[20:21]
	global_load_dwordx4 v[152:155], v37, s[20:21]
	global_load_dwordx4 v[156:159], v38, s[20:21]
	global_load_dwordx4 v[160:163], v39, s[20:21]
	global_load_dwordx4 v[164:167], v40, s[20:21]
	global_load_dwordx4 v[168:171], v41, s[20:21]
	global_load_dwordx4 v[172:175], v42, s[20:21]
	global_load_dwordx4 v[176:179], v43, s[20:21]
	global_load_dwordx4 v[180:183], v44, s[20:21]
	global_load_dwordx4 v[184:187], v45, s[20:21]
	global_load_dwordx4 v[190:193], v46, s[20:21]
	global_load_dwordx4 v[194:197], v47, s[20:21]
	global_load_dwordx4 v[198:201], v48, s[20:21]
	global_load_dwordx4 v[202:205], v49, s[20:21]
	global_load_dwordx4 v[206:209], v50, s[20:21]
	global_load_dwordx4 v[210:213], v51, s[20:21]
	s_waitcnt vmcnt(31)
; DI f2_t cvt8lo(unsigned w) { return __builtin_amdgcn_cvt_pk_f32_fp8(w, false); }
; DI f2_t cvt8hi(unsigned w) { return __builtin_amdgcn_cvt_pk_f32_fp8(w, true); }
; DI void phase11(const Params& p, char* smem, int rep) {
;     ...
;         for (int k = 0; k < 16; ++k) {
;           const f2_t a2 = {aa[k], aa[k]};
; #pragma unroll
;           for (int d = 0; d < 4; ++d) { const unsigned ww = rows[k][d]; o[2 * d] += a2 * cvt8lo(ww); o[2 * d + 1] += a2 * cvt8hi(ww); }
;         }
	v_cvt_pk_f32_fp8_e32 v[232:233], v84
	v_cvt_pk_f32_fp8_sdwa v[234:235], v84 src0_sel:WORD_1
	v_pk_fma_f32 v[216:217], v[52:53], v[232:233], 0 op_sel_hi:[0,1,0]
	v_pk_fma_f32 v[218:219], v[52:53], v[234:235], 0 op_sel_hi:[0,1,0]
	v_cvt_pk_f32_fp8_e32 v[236:237], v85
	v_cvt_pk_f32_fp8_sdwa v[238:239], v85 src0_sel:WORD_1
	v_pk_fma_f32 v[220:221], v[52:53], v[236:237], 0 op_sel_hi:[0,1,0]
	v_pk_fma_f32 v[222:223], v[52:53], v[238:239], 0 op_sel_hi:[0,1,0]
	v_cvt_pk_f32_fp8_e32 v[232:233], v86
	v_cvt_pk_f32_fp8_sdwa v[234:235], v86 src0_sel:WORD_1
	v_pk_fma_f32 v[224:225], v[52:53], v[232:233], 0 op_sel_hi:[0,1,0]
	v_pk_fma_f32 v[226:227], v[52:53], v[234:235], 0 op_sel_hi:[0,1,0]
	v_cvt_pk_f32_fp8_e32 v[236:237], v87
	v_cvt_pk_f32_fp8_sdwa v[238:239], v87 src0_sel:WORD_1
	v_pk_fma_f32 v[228:229], v[52:53], v[236:237], 0 op_sel_hi:[0,1,0]
	v_pk_fma_f32 v[230:231], v[52:53], v[238:239], 0 op_sel_hi:[0,1,0]
	s_waitcnt vmcnt(30)
	v_cvt_pk_f32_fp8_e32 v[232:233], v88
	v_cvt_pk_f32_fp8_sdwa v[234:235], v88 src0_sel:WORD_1
	v_pk_fma_f32 v[216:217], v[52:53], v[232:233], v[216:217] op_sel:[1,0,0]
	v_pk_fma_f32 v[218:219], v[52:53], v[234:235], v[218:219] op_sel:[1,0,0]
	v_cvt_pk_f32_fp8_e32 v[236:237], v89
	v_cvt_pk_f32_fp8_sdwa v[238:239], v89 src0_sel:WORD_1
	v_pk_fma_f32 v[220:221], v[52:53], v[236:237], v[220:221] op_sel:[1,0,0]
	v_pk_fma_f32 v[222:223], v[52:53], v[238:239], v[222:223] op_sel:[1,0,0]
	v_cvt_pk_f32_fp8_e32 v[232:233], v90
	v_cvt_pk_f32_fp8_sdwa v[234:235], v90 src0_sel:WORD_1
	v_pk_fma_f32 v[224:225], v[52:53], v[232:233], v[224:225] op_sel:[1,0,0]
	v_pk_fma_f32 v[226:227], v[52:53], v[234:235], v[226:227] op_sel:[1,0,0]
	v_cvt_pk_f32_fp8_e32 v[236:237], v91
	v_cvt_pk_f32_fp8_sdwa v[238:239], v91 src0_sel:WORD_1
	v_pk_fma_f32 v[228:229], v[52:53], v[236:237], v[228:229] op_sel:[1,0,0]
	v_pk_fma_f32 v[230:231], v[52:53], v[238:239], v[230:231] op_sel:[1,0,0]
	s_waitcnt vmcnt(29)
	v_cvt_pk_f32_fp8_e32 v[232:233], v92
	v_cvt_pk_f32_fp8_sdwa v[234:235], v92 src0_sel:WORD_1
	v_pk_fma_f32 v[216:217], v[54:55], v[232:233], v[216:217] op_sel_hi:[0,1,1]
	v_pk_fma_f32 v[218:219], v[54:55], v[234:235], v[218:219] op_sel_hi:[0,1,1]
	v_cvt_pk_f32_fp8_e32 v[236:237], v93
	v_cvt_pk_f32_fp8_sdwa v[238:239], v93 src0_sel:WORD_1
	v_pk_fma_f32 v[220:221], v[54:55], v[236:237], v[220:221] op_sel_hi:[0,1,1]
	v_pk_fma_f32 v[222:223], v[54:55], v[238:239], v[222:223] op_sel_hi:[0,1,1]
	v_cvt_pk_f32_fp8_e32 v[232:233], v94
	v_cvt_pk_f32_fp8_sdwa v[234:235], v94 src0_sel:WORD_1
	v_pk_fma_f32 v[224:225], v[54:55], v[232:233], v[224:225] op_sel_hi:[0,1,1]
	v_pk_fma_f32 v[226:227], v[54:55], v[234:235], v[226:227] op_sel_hi:[0,1,1]
	v_cvt_pk_f32_fp8_e32 v[236:237], v95
	v_cvt_pk_f32_fp8_sdwa v[238:239], v95 src0_sel:WORD_1
	v_pk_fma_f32 v[228:229], v[54:55], v[236:237], v[228:229] op_sel_hi:[0,1,1]
	v_pk_fma_f32 v[230:231], v[54:55], v[238:239], v[230:231] op_sel_hi:[0,1,1]
	s_waitcnt vmcnt(28)
	v_cvt_pk_f32_fp8_e32 v[232:233], v96
	v_cvt_pk_f32_fp8_sdwa v[234:235], v96 src0_sel:WORD_1
	v_pk_fma_f32 v[216:217], v[54:55], v[232:233], v[216:217] op_sel:[1,0,0]
	v_pk_fma_f32 v[218:219], v[54:55], v[234:235], v[218:219] op_sel:[1,0,0]
	v_cvt_pk_f32_fp8_e32 v[236:237], v97
	v_cvt_pk_f32_fp8_sdwa v[238:239], v97 src0_sel:WORD_1
	v_pk_fma_f32 v[220:221], v[54:55], v[236:237], v[220:221] op_sel:[1,0,0]
	v_pk_fma_f32 v[222:223], v[54:55], v[238:239], v[222:223] op_sel:[1,0,0]
	v_cvt_pk_f32_fp8_e32 v[232:233], v98
	v_cvt_pk_f32_fp8_sdwa v[234:235], v98 src0_sel:WORD_1
	v_pk_fma_f32 v[224:225], v[54:55], v[232:233], v[224:225] op_sel:[1,0,0]
	v_pk_fma_f32 v[226:227], v[54:55], v[234:235], v[226:227] op_sel:[1,0,0]
	v_cvt_pk_f32_fp8_e32 v[236:237], v99
	v_cvt_pk_f32_fp8_sdwa v[238:239], v99 src0_sel:WORD_1
	v_pk_fma_f32 v[228:229], v[54:55], v[236:237], v[228:229] op_sel:[1,0,0]
	v_pk_fma_f32 v[230:231], v[54:55], v[238:239], v[230:231] op_sel:[1,0,0]
	s_waitcnt vmcnt(27)
	v_cvt_pk_f32_fp8_e32 v[232:233], v100
	v_cvt_pk_f32_fp8_sdwa v[234:235], v100 src0_sel:WORD_1
	v_pk_fma_f32 v[216:217], v[56:57], v[232:233], v[216:217] op_sel_hi:[0,1,1]
	v_pk_fma_f32 v[218:219], v[56:57], v[234:235], v[218:219] op_sel_hi:[0,1,1]
	v_cvt_pk_f32_fp8_e32 v[236:237], v101
	v_cvt_pk_f32_fp8_sdwa v[238:239], v101 src0_sel:WORD_1
	v_pk_fma_f32 v[220:221], v[56:57], v[236:237], v[220:221] op_sel_hi:[0,1,1]
	v_pk_fma_f32 v[222:223], v[56:57], v[238:239], v[222:223] op_sel_hi:[0,1,1]
	v_cvt_pk_f32_fp8_e32 v[232:233], v102
	v_cvt_pk_f32_fp8_sdwa v[234:235], v102 src0_sel:WORD_1
	v_pk_fma_f32 v[224:225], v[56:57], v[232:233], v[224:225] op_sel_hi:[0,1,1]
	v_pk_fma_f32 v[226:227], v[56:57], v[234:235], v[226:227] op_sel_hi:[0,1,1]
	v_cvt_pk_f32_fp8_e32 v[236:237], v103
	v_cvt_pk_f32_fp8_sdwa v[238:239], v103 src0_sel:WORD_1
	v_pk_fma_f32 v[228:229], v[56:57], v[236:237], v[228:229] op_sel_hi:[0,1,1]
	v_pk_fma_f32 v[230:231], v[56:57], v[238:239], v[230:231] op_sel_hi:[0,1,1]
	s_waitcnt vmcnt(26)
	v_cvt_pk_f32_fp8_e32 v[232:233], v104
	v_cvt_pk_f32_fp8_sdwa v[234:235], v104 src0_sel:WORD_1
	v_pk_fma_f32 v[216:217], v[56:57], v[232:233], v[216:217] op_sel:[1,0,0]
	v_pk_fma_f32 v[218:219], v[56:57], v[234:235], v[218:219] op_sel:[1,0,0]
	v_cvt_pk_f32_fp8_e32 v[236:237], v105
	v_cvt_pk_f32_fp8_sdwa v[238:239], v105 src0_sel:WORD_1
	v_pk_fma_f32 v[220:221], v[56:57], v[236:237], v[220:221] op_sel:[1,0,0]
	v_pk_fma_f32 v[222:223], v[56:57], v[238:239], v[222:223] op_sel:[1,0,0]
	v_cvt_pk_f32_fp8_e32 v[232:233], v106
	v_cvt_pk_f32_fp8_sdwa v[234:235], v106 src0_sel:WORD_1
	v_pk_fma_f32 v[224:225], v[56:57], v[232:233], v[224:225] op_sel:[1,0,0]
	v_pk_fma_f32 v[226:227], v[56:57], v[234:235], v[226:227] op_sel:[1,0,0]
	v_cvt_pk_f32_fp8_e32 v[236:237], v107
	v_cvt_pk_f32_fp8_sdwa v[238:239], v107 src0_sel:WORD_1
	v_pk_fma_f32 v[228:229], v[56:57], v[236:237], v[228:229] op_sel:[1,0,0]
	v_pk_fma_f32 v[230:231], v[56:57], v[238:239], v[230:231] op_sel:[1,0,0]
	s_waitcnt vmcnt(25)
; DI f2_t cvt8lo(unsigned w) { return __builtin_amdgcn_cvt_pk_f32_fp8(w, false); }
; DI f2_t cvt8hi(unsigned w) { return __builtin_amdgcn_cvt_pk_f32_fp8(w, true); }
; DI void phase11(const Params& p, char* smem, int rep) {
;     ...
;         for (int k = 0; k < 16; ++k) {
;           const f2_t a2 = {aa[k], aa[k]};
; #pragma unroll
;           for (int d = 0; d < 4; ++d) { const unsigned ww = rows[k][d]; o[2 * d] += a2 * cvt8lo(ww); o[2 * d + 1] += a2 * cvt8hi(ww); }
;         }
	v_cvt_pk_f32_fp8_e32 v[232:233], v108
	v_cvt_pk_f32_fp8_sdwa v[234:235], v108 src0_sel:WORD_1
	v_pk_fma_f32 v[216:217], v[58:59], v[232:233], v[216:217] op_sel_hi:[0,1,1]
	v_pk_fma_f32 v[218:219], v[58:59], v[234:235], v[218:219] op_sel_hi:[0,1,1]
	v_cvt_pk_f32_fp8_e32 v[236:237], v109
	v_cvt_pk_f32_fp8_sdwa v[238:239], v109 src0_sel:WORD_1
	v_pk_fma_f32 v[220:221], v[58:59], v[236:237], v[220:221] op_sel_hi:[0,1,1]
	v_pk_fma_f32 v[222:223], v[58:59], v[238:239], v[222:223] op_sel_hi:[0,1,1]
	v_cvt_pk_f32_fp8_e32 v[232:233], v110
	v_cvt_pk_f32_fp8_sdwa v[234:235], v110 src0_sel:WORD_1
	v_pk_fma_f32 v[224:225], v[58:59], v[232:233], v[224:225] op_sel_hi:[0,1,1]
	v_pk_fma_f32 v[226:227], v[58:59], v[234:235], v[226:227] op_sel_hi:[0,1,1]
	v_cvt_pk_f32_fp8_e32 v[236:237], v111
	v_cvt_pk_f32_fp8_sdwa v[238:239], v111 src0_sel:WORD_1
	v_pk_fma_f32 v[228:229], v[58:59], v[236:237], v[228:229] op_sel_hi:[0,1,1]
	v_pk_fma_f32 v[230:231], v[58:59], v[238:239], v[230:231] op_sel_hi:[0,1,1]
	s_waitcnt vmcnt(24)
	v_cvt_pk_f32_fp8_e32 v[232:233], v112
	v_cvt_pk_f32_fp8_sdwa v[234:235], v112 src0_sel:WORD_1
	v_pk_fma_f32 v[216:217], v[58:59], v[232:233], v[216:217] op_sel:[1,0,0]
	v_pk_fma_f32 v[218:219], v[58:59], v[234:235], v[218:219] op_sel:[1,0,0]
	v_cvt_pk_f32_fp8_e32 v[236:237], v113
	v_cvt_pk_f32_fp8_sdwa v[238:239], v113 src0_sel:WORD_1
	v_pk_fma_f32 v[220:221], v[58:59], v[236:237], v[220:221] op_sel:[1,0,0]
	v_pk_fma_f32 v[222:223], v[58:59], v[238:239], v[222:223] op_sel:[1,0,0]
	v_cvt_pk_f32_fp8_e32 v[232:233], v114
	v_cvt_pk_f32_fp8_sdwa v[234:235], v114 src0_sel:WORD_1
	v_pk_fma_f32 v[224:225], v[58:59], v[232:233], v[224:225] op_sel:[1,0,0]
	v_pk_fma_f32 v[226:227], v[58:59], v[234:235], v[226:227] op_sel:[1,0,0]
	v_cvt_pk_f32_fp8_e32 v[236:237], v115
	v_cvt_pk_f32_fp8_sdwa v[238:239], v115 src0_sel:WORD_1
	v_pk_fma_f32 v[228:229], v[58:59], v[236:237], v[228:229] op_sel:[1,0,0]
	v_pk_fma_f32 v[230:231], v[58:59], v[238:239], v[230:231] op_sel:[1,0,0]
	s_waitcnt vmcnt(23)
	v_cvt_pk_f32_fp8_e32 v[232:233], v116
	v_cvt_pk_f32_fp8_sdwa v[234:235], v116 src0_sel:WORD_1
	v_pk_fma_f32 v[216:217], v[60:61], v[232:233], v[216:217] op_sel_hi:[0,1,1]
	v_pk_fma_f32 v[218:219], v[60:61], v[234:235], v[218:219] op_sel_hi:[0,1,1]
	v_cvt_pk_f32_fp8_e32 v[236:237], v117
	v_cvt_pk_f32_fp8_sdwa v[238:239], v117 src0_sel:WORD_1
	v_pk_fma_f32 v[220:221], v[60:61], v[236:237], v[220:221] op_sel_hi:[0,1,1]
	v_pk_fma_f32 v[222:223], v[60:61], v[238:239], v[222:223] op_sel_hi:[0,1,1]
	v_cvt_pk_f32_fp8_e32 v[232:233], v118
	v_cvt_pk_f32_fp8_sdwa v[234:235], v118 src0_sel:WORD_1
	v_pk_fma_f32 v[224:225], v[60:61], v[232:233], v[224:225] op_sel_hi:[0,1,1]
	v_pk_fma_f32 v[226:227], v[60:61], v[234:235], v[226:227] op_sel_hi:[0,1,1]
	v_cvt_pk_f32_fp8_e32 v[236:237], v119
	v_cvt_pk_f32_fp8_sdwa v[238:239], v119 src0_sel:WORD_1
	v_pk_fma_f32 v[228:229], v[60:61], v[236:237], v[228:229] op_sel_hi:[0,1,1]
	v_pk_fma_f32 v[230:231], v[60:61], v[238:239], v[230:231] op_sel_hi:[0,1,1]
	s_waitcnt vmcnt(22)
	v_cvt_pk_f32_fp8_e32 v[232:233], v120
	v_cvt_pk_f32_fp8_sdwa v[234:235], v120 src0_sel:WORD_1
	v_pk_fma_f32 v[216:217], v[60:61], v[232:233], v[216:217] op_sel:[1,0,0]
	v_pk_fma_f32 v[218:219], v[60:61], v[234:235], v[218:219] op_sel:[1,0,0]
	v_cvt_pk_f32_fp8_e32 v[236:237], v121
	v_cvt_pk_f32_fp8_sdwa v[238:239], v121 src0_sel:WORD_1
	v_pk_fma_f32 v[220:221], v[60:61], v[236:237], v[220:221] op_sel:[1,0,0]
	v_pk_fma_f32 v[222:223], v[60:61], v[238:239], v[222:223] op_sel:[1,0,0]
	v_cvt_pk_f32_fp8_e32 v[232:233], v122
	v_cvt_pk_f32_fp8_sdwa v[234:235], v122 src0_sel:WORD_1
	v_pk_fma_f32 v[224:225], v[60:61], v[232:233], v[224:225] op_sel:[1,0,0]
	v_pk_fma_f32 v[226:227], v[60:61], v[234:235], v[226:227] op_sel:[1,0,0]
	v_cvt_pk_f32_fp8_e32 v[236:237], v123
	v_cvt_pk_f32_fp8_sdwa v[238:239], v123 src0_sel:WORD_1
	v_pk_fma_f32 v[228:229], v[60:61], v[236:237], v[228:229] op_sel:[1,0,0]
	v_pk_fma_f32 v[230:231], v[60:61], v[238:239], v[230:231] op_sel:[1,0,0]
	s_waitcnt vmcnt(21)
	v_cvt_pk_f32_fp8_e32 v[232:233], v124
	v_cvt_pk_f32_fp8_sdwa v[234:235], v124 src0_sel:WORD_1
	v_pk_fma_f32 v[216:217], v[62:63], v[232:233], v[216:217] op_sel_hi:[0,1,1]
	v_pk_fma_f32 v[218:219], v[62:63], v[234:235], v[218:219] op_sel_hi:[0,1,1]
	v_cvt_pk_f32_fp8_e32 v[236:237], v125
	v_cvt_pk_f32_fp8_sdwa v[238:239], v125 src0_sel:WORD_1
	v_pk_fma_f32 v[220:221], v[62:63], v[236:237], v[220:221] op_sel_hi:[0,1,1]
	v_pk_fma_f32 v[222:223], v[62:63], v[238:239], v[222:223] op_sel_hi:[0,1,1]
	v_cvt_pk_f32_fp8_e32 v[232:233], v126
	v_cvt_pk_f32_fp8_sdwa v[234:235], v126 src0_sel:WORD_1
	v_pk_fma_f32 v[224:225], v[62:63], v[232:233], v[224:225] op_sel_hi:[0,1,1]
	v_pk_fma_f32 v[226:227], v[62:63], v[234:235], v[226:227] op_sel_hi:[0,1,1]
	v_cvt_pk_f32_fp8_e32 v[236:237], v127
	v_cvt_pk_f32_fp8_sdwa v[238:239], v127 src0_sel:WORD_1
	v_pk_fma_f32 v[228:229], v[62:63], v[236:237], v[228:229] op_sel_hi:[0,1,1]
	v_pk_fma_f32 v[230:231], v[62:63], v[238:239], v[230:231] op_sel_hi:[0,1,1]
	s_waitcnt vmcnt(20)
	v_cvt_pk_f32_fp8_e32 v[232:233], v128
	v_cvt_pk_f32_fp8_sdwa v[234:235], v128 src0_sel:WORD_1
	v_pk_fma_f32 v[216:217], v[62:63], v[232:233], v[216:217] op_sel:[1,0,0]
	v_pk_fma_f32 v[218:219], v[62:63], v[234:235], v[218:219] op_sel:[1,0,0]
	v_cvt_pk_f32_fp8_e32 v[236:237], v129
	v_cvt_pk_f32_fp8_sdwa v[238:239], v129 src0_sel:WORD_1
	v_pk_fma_f32 v[220:221], v[62:63], v[236:237], v[220:221] op_sel:[1,0,0]
	v_pk_fma_f32 v[222:223], v[62:63], v[238:239], v[222:223] op_sel:[1,0,0]
	v_cvt_pk_f32_fp8_e32 v[232:233], v130
	v_cvt_pk_f32_fp8_sdwa v[234:235], v130 src0_sel:WORD_1
	v_pk_fma_f32 v[224:225], v[62:63], v[232:233], v[224:225] op_sel:[1,0,0]
	v_pk_fma_f32 v[226:227], v[62:63], v[234:235], v[226:227] op_sel:[1,0,0]
	v_cvt_pk_f32_fp8_e32 v[236:237], v131
	v_cvt_pk_f32_fp8_sdwa v[238:239], v131 src0_sel:WORD_1
	v_pk_fma_f32 v[228:229], v[62:63], v[236:237], v[228:229] op_sel:[1,0,0]
	v_pk_fma_f32 v[230:231], v[62:63], v[238:239], v[230:231] op_sel:[1,0,0]
	s_waitcnt vmcnt(19)
; DI f2_t cvt8lo(unsigned w) { return __builtin_amdgcn_cvt_pk_f32_fp8(w, false); }
; DI f2_t cvt8hi(unsigned w) { return __builtin_amdgcn_cvt_pk_f32_fp8(w, true); }
; DI void wave_lds_sync() { asm volatile("s_waitcnt lgkmcnt(0)" ::: "memory"); __builtin_amdgcn_wave_barrier(); }
; DI void phase11(const Params& p, char* smem, int rep) {
;     ...
;       lw[(lane & 3) * 32 + (lane >> 2)] = i0; lw[(lane & 3) * 32 + 16 + (lane >> 2)] = i1;
;       lf[(lane & 3) * 32 + (lane >> 2)] = a0; lf[(lane & 3) * 32 + 16 + (lane >> 2)] = a1;
;       wave_lds_sync();
;       f2_t o[8];
; #pragma unroll
;       for (int i = 0; i < 8; ++i) o[i] = f2_t{0.f, 0.f};
;       const unsigned char* vb = V8 + s * 256 + l15 * 16;
; #pragma unroll
;       for (int batch = 0; batch < 2; ++batch) {
;         int ida[16]; float aa[16];
; #pragma unroll
;         for (int q = 0; q < 4; ++q) {
;           const int4 v = *(const int4*)(lw + g * 32 + batch * 16 + q * 4); ida[q * 4] = v.x; ida[q * 4 + 1] = v.y; ida[q * 4 + 2] = v.z; ida[q * 4 + 3] = v.w;
;           const float4 f = *(const float4*)(lf + g * 32 + batch * 16 + q * 4); aa[q * 4] = f.x; aa[q * 4 + 1] = f.y; aa[q * 4 + 2] = f.z; aa[q * 4 + 3] = f.w;
;         }
;         u32x4 rows[16];
; #pragma unroll
;         for (int k = 0; k < 16; ++k) rows[k] = *(const u32x4*)(vb + (size_t)ida[k] * 2048);
; #pragma unroll
;         for (int k = 0; k < 16; ++k) {
;           const f2_t a2 = {aa[k], aa[k]};
; #pragma unroll
;           for (int d = 0; d < 4; ++d) { const unsigned ww = rows[k][d]; o[2 * d] += a2 * cvt8lo(ww); o[2 * d + 1] += a2 * cvt8hi(ww); }
	v_cvt_pk_f32_fp8_e32 v[232:233], v132
	v_cvt_pk_f32_fp8_sdwa v[234:235], v132 src0_sel:WORD_1
	v_pk_fma_f32 v[216:217], v[64:65], v[232:233], v[216:217] op_sel_hi:[0,1,1]
	v_pk_fma_f32 v[218:219], v[64:65], v[234:235], v[218:219] op_sel_hi:[0,1,1]
	v_cvt_pk_f32_fp8_e32 v[236:237], v133
	v_cvt_pk_f32_fp8_sdwa v[238:239], v133 src0_sel:WORD_1
	v_pk_fma_f32 v[220:221], v[64:65], v[236:237], v[220:221] op_sel_hi:[0,1,1]
	v_pk_fma_f32 v[222:223], v[64:65], v[238:239], v[222:223] op_sel_hi:[0,1,1]
	v_cvt_pk_f32_fp8_e32 v[232:233], v134
	v_cvt_pk_f32_fp8_sdwa v[234:235], v134 src0_sel:WORD_1
	v_pk_fma_f32 v[224:225], v[64:65], v[232:233], v[224:225] op_sel_hi:[0,1,1]
	v_pk_fma_f32 v[226:227], v[64:65], v[234:235], v[226:227] op_sel_hi:[0,1,1]
	v_cvt_pk_f32_fp8_e32 v[236:237], v135
	v_cvt_pk_f32_fp8_sdwa v[238:239], v135 src0_sel:WORD_1
	v_pk_fma_f32 v[228:229], v[64:65], v[236:237], v[228:229] op_sel_hi:[0,1,1]
	v_pk_fma_f32 v[230:231], v[64:65], v[238:239], v[230:231] op_sel_hi:[0,1,1]
	s_waitcnt vmcnt(18)
	v_cvt_pk_f32_fp8_e32 v[232:233], v136
	v_cvt_pk_f32_fp8_sdwa v[234:235], v136 src0_sel:WORD_1
	v_pk_fma_f32 v[216:217], v[64:65], v[232:233], v[216:217] op_sel:[1,0,0]
	v_pk_fma_f32 v[218:219], v[64:65], v[234:235], v[218:219] op_sel:[1,0,0]
	v_cvt_pk_f32_fp8_e32 v[236:237], v137
	v_cvt_pk_f32_fp8_sdwa v[238:239], v137 src0_sel:WORD_1
	v_pk_fma_f32 v[220:221], v[64:65], v[236:237], v[220:221] op_sel:[1,0,0]
	v_pk_fma_f32 v[222:223], v[64:65], v[238:239], v[222:223] op_sel:[1,0,0]
	v_cvt_pk_f32_fp8_e32 v[232:233], v138
	v_cvt_pk_f32_fp8_sdwa v[234:235], v138 src0_sel:WORD_1
	v_pk_fma_f32 v[224:225], v[64:65], v[232:233], v[224:225] op_sel:[1,0,0]
	v_pk_fma_f32 v[226:227], v[64:65], v[234:235], v[226:227] op_sel:[1,0,0]
	v_cvt_pk_f32_fp8_e32 v[236:237], v139
	v_cvt_pk_f32_fp8_sdwa v[238:239], v139 src0_sel:WORD_1
	v_pk_fma_f32 v[228:229], v[64:65], v[236:237], v[228:229] op_sel:[1,0,0]
	v_pk_fma_f32 v[230:231], v[64:65], v[238:239], v[230:231] op_sel:[1,0,0]
	s_waitcnt vmcnt(17)
	v_cvt_pk_f32_fp8_e32 v[232:233], v140
	v_cvt_pk_f32_fp8_sdwa v[234:235], v140 src0_sel:WORD_1
	v_pk_fma_f32 v[216:217], v[66:67], v[232:233], v[216:217] op_sel_hi:[0,1,1]
	v_pk_fma_f32 v[218:219], v[66:67], v[234:235], v[218:219] op_sel_hi:[0,1,1]
	v_cvt_pk_f32_fp8_e32 v[236:237], v141
	v_cvt_pk_f32_fp8_sdwa v[238:239], v141 src0_sel:WORD_1
	v_pk_fma_f32 v[220:221], v[66:67], v[236:237], v[220:221] op_sel_hi:[0,1,1]
	v_pk_fma_f32 v[222:223], v[66:67], v[238:239], v[222:223] op_sel_hi:[0,1,1]
	v_cvt_pk_f32_fp8_e32 v[232:233], v142
	v_cvt_pk_f32_fp8_sdwa v[234:235], v142 src0_sel:WORD_1
	v_pk_fma_f32 v[224:225], v[66:67], v[232:233], v[224:225] op_sel_hi:[0,1,1]
	v_pk_fma_f32 v[226:227], v[66:67], v[234:235], v[226:227] op_sel_hi:[0,1,1]
	v_cvt_pk_f32_fp8_e32 v[236:237], v143
	v_cvt_pk_f32_fp8_sdwa v[238:239], v143 src0_sel:WORD_1
	v_pk_fma_f32 v[228:229], v[66:67], v[236:237], v[228:229] op_sel_hi:[0,1,1]
	v_pk_fma_f32 v[230:231], v[66:67], v[238:239], v[230:231] op_sel_hi:[0,1,1]
	s_waitcnt vmcnt(16)
	v_cvt_pk_f32_fp8_e32 v[232:233], v144
	v_cvt_pk_f32_fp8_sdwa v[234:235], v144 src0_sel:WORD_1
	v_pk_fma_f32 v[216:217], v[66:67], v[232:233], v[216:217] op_sel:[1,0,0]
	v_pk_fma_f32 v[218:219], v[66:67], v[234:235], v[218:219] op_sel:[1,0,0]
	v_cvt_pk_f32_fp8_e32 v[236:237], v145
	v_cvt_pk_f32_fp8_sdwa v[238:239], v145 src0_sel:WORD_1
	v_pk_fma_f32 v[220:221], v[66:67], v[236:237], v[220:221] op_sel:[1,0,0]
	v_pk_fma_f32 v[222:223], v[66:67], v[238:239], v[222:223] op_sel:[1,0,0]
	v_cvt_pk_f32_fp8_e32 v[232:233], v146
	v_cvt_pk_f32_fp8_sdwa v[234:235], v146 src0_sel:WORD_1
	v_pk_fma_f32 v[224:225], v[66:67], v[232:233], v[224:225] op_sel:[1,0,0]
	v_pk_fma_f32 v[226:227], v[66:67], v[234:235], v[226:227] op_sel:[1,0,0]
	v_cvt_pk_f32_fp8_e32 v[236:237], v147
	v_cvt_pk_f32_fp8_sdwa v[238:239], v147 src0_sel:WORD_1
	v_pk_fma_f32 v[228:229], v[66:67], v[236:237], v[228:229] op_sel:[1,0,0]
	v_pk_fma_f32 v[230:231], v[66:67], v[238:239], v[230:231] op_sel:[1,0,0]
	ds_write2_b32 v5, v10, v11 offset0:4 offset1:20
	ds_write2_b32 v5, v12, v13 offset0:132 offset1:148
	s_waitcnt lgkmcnt(0)
	ds_read_b128 v[20:23], v6 offset:16
	ds_read_b128 v[24:27], v6 offset:32
	ds_read_b128 v[28:31], v6 offset:48
	ds_read_b128 v[32:35], v6 offset:64
	ds_read_b128 v[36:39], v6 offset:80
	ds_read_b128 v[40:43], v6 offset:96
	ds_read_b128 v[44:47], v6 offset:112
	ds_read_b128 v[48:51], v6 offset:128
	s_waitcnt vmcnt(15)
	v_cvt_pk_f32_fp8_e32 v[232:233], v148
	v_cvt_pk_f32_fp8_sdwa v[234:235], v148 src0_sel:WORD_1
	v_pk_fma_f32 v[216:217], v[68:69], v[232:233], v[216:217] op_sel_hi:[0,1,1]
	v_pk_fma_f32 v[218:219], v[68:69], v[234:235], v[218:219] op_sel_hi:[0,1,1]
	v_cvt_pk_f32_fp8_e32 v[236:237], v149
	v_cvt_pk_f32_fp8_sdwa v[238:239], v149 src0_sel:WORD_1
	v_pk_fma_f32 v[220:221], v[68:69], v[236:237], v[220:221] op_sel_hi:[0,1,1]
	v_pk_fma_f32 v[222:223], v[68:69], v[238:239], v[222:223] op_sel_hi:[0,1,1]
	v_cvt_pk_f32_fp8_e32 v[232:233], v150
	v_cvt_pk_f32_fp8_sdwa v[234:235], v150 src0_sel:WORD_1
	v_pk_fma_f32 v[224:225], v[68:69], v[232:233], v[224:225] op_sel_hi:[0,1,1]
	v_pk_fma_f32 v[226:227], v[68:69], v[234:235], v[226:227] op_sel_hi:[0,1,1]
	v_cvt_pk_f32_fp8_e32 v[236:237], v151
	v_cvt_pk_f32_fp8_sdwa v[238:239], v151 src0_sel:WORD_1
	v_pk_fma_f32 v[228:229], v[68:69], v[236:237], v[228:229] op_sel_hi:[0,1,1]
	v_pk_fma_f32 v[230:231], v[68:69], v[238:239], v[230:231] op_sel_hi:[0,1,1]
	s_waitcnt vmcnt(14)
; DI f2_t cvt8lo(unsigned w) { return __builtin_amdgcn_cvt_pk_f32_fp8(w, false); }
; DI f2_t cvt8hi(unsigned w) { return __builtin_amdgcn_cvt_pk_f32_fp8(w, true); }
; DI void phase11(const Params& p, char* smem, int rep) {
;     ...
;         for (int k = 0; k < 16; ++k) {
;           const f2_t a2 = {aa[k], aa[k]};
; #pragma unroll
;           for (int d = 0; d < 4; ++d) { const unsigned ww = rows[k][d]; o[2 * d] += a2 * cvt8lo(ww); o[2 * d + 1] += a2 * cvt8hi(ww); }
;         }
	v_cvt_pk_f32_fp8_e32 v[232:233], v152
	v_cvt_pk_f32_fp8_sdwa v[234:235], v152 src0_sel:WORD_1
	v_pk_fma_f32 v[216:217], v[68:69], v[232:233], v[216:217] op_sel:[1,0,0]
	v_pk_fma_f32 v[218:219], v[68:69], v[234:235], v[218:219] op_sel:[1,0,0]
	v_cvt_pk_f32_fp8_e32 v[236:237], v153
	v_cvt_pk_f32_fp8_sdwa v[238:239], v153 src0_sel:WORD_1
	v_pk_fma_f32 v[220:221], v[68:69], v[236:237], v[220:221] op_sel:[1,0,0]
	v_pk_fma_f32 v[222:223], v[68:69], v[238:239], v[222:223] op_sel:[1,0,0]
	v_cvt_pk_f32_fp8_e32 v[232:233], v154
	v_cvt_pk_f32_fp8_sdwa v[234:235], v154 src0_sel:WORD_1
	v_pk_fma_f32 v[224:225], v[68:69], v[232:233], v[224:225] op_sel:[1,0,0]
	v_pk_fma_f32 v[226:227], v[68:69], v[234:235], v[226:227] op_sel:[1,0,0]
	v_cvt_pk_f32_fp8_e32 v[236:237], v155
	v_cvt_pk_f32_fp8_sdwa v[238:239], v155 src0_sel:WORD_1
	v_pk_fma_f32 v[228:229], v[68:69], v[236:237], v[228:229] op_sel:[1,0,0]
	v_pk_fma_f32 v[230:231], v[68:69], v[238:239], v[230:231] op_sel:[1,0,0]
	s_waitcnt vmcnt(13)
	v_cvt_pk_f32_fp8_e32 v[232:233], v156
	v_cvt_pk_f32_fp8_sdwa v[234:235], v156 src0_sel:WORD_1
	v_pk_fma_f32 v[216:217], v[70:71], v[232:233], v[216:217] op_sel_hi:[0,1,1]
	v_pk_fma_f32 v[218:219], v[70:71], v[234:235], v[218:219] op_sel_hi:[0,1,1]
	v_cvt_pk_f32_fp8_e32 v[236:237], v157
	v_cvt_pk_f32_fp8_sdwa v[238:239], v157 src0_sel:WORD_1
	v_pk_fma_f32 v[220:221], v[70:71], v[236:237], v[220:221] op_sel_hi:[0,1,1]
	v_pk_fma_f32 v[222:223], v[70:71], v[238:239], v[222:223] op_sel_hi:[0,1,1]
	v_cvt_pk_f32_fp8_e32 v[232:233], v158
	v_cvt_pk_f32_fp8_sdwa v[234:235], v158 src0_sel:WORD_1
	v_pk_fma_f32 v[224:225], v[70:71], v[232:233], v[224:225] op_sel_hi:[0,1,1]
	v_pk_fma_f32 v[226:227], v[70:71], v[234:235], v[226:227] op_sel_hi:[0,1,1]
	v_cvt_pk_f32_fp8_e32 v[236:237], v159
	v_cvt_pk_f32_fp8_sdwa v[238:239], v159 src0_sel:WORD_1
	v_pk_fma_f32 v[228:229], v[70:71], v[236:237], v[228:229] op_sel_hi:[0,1,1]
	v_pk_fma_f32 v[230:231], v[70:71], v[238:239], v[230:231] op_sel_hi:[0,1,1]
	s_waitcnt vmcnt(12)
	v_cvt_pk_f32_fp8_e32 v[232:233], v160
	v_cvt_pk_f32_fp8_sdwa v[234:235], v160 src0_sel:WORD_1
	v_pk_fma_f32 v[216:217], v[70:71], v[232:233], v[216:217] op_sel:[1,0,0]
	v_pk_fma_f32 v[218:219], v[70:71], v[234:235], v[218:219] op_sel:[1,0,0]
	v_cvt_pk_f32_fp8_e32 v[236:237], v161
	v_cvt_pk_f32_fp8_sdwa v[238:239], v161 src0_sel:WORD_1
	v_pk_fma_f32 v[220:221], v[70:71], v[236:237], v[220:221] op_sel:[1,0,0]
	v_pk_fma_f32 v[222:223], v[70:71], v[238:239], v[222:223] op_sel:[1,0,0]
	v_cvt_pk_f32_fp8_e32 v[232:233], v162
	v_cvt_pk_f32_fp8_sdwa v[234:235], v162 src0_sel:WORD_1
	v_pk_fma_f32 v[224:225], v[70:71], v[232:233], v[224:225] op_sel:[1,0,0]
	v_pk_fma_f32 v[226:227], v[70:71], v[234:235], v[226:227] op_sel:[1,0,0]
	v_cvt_pk_f32_fp8_e32 v[236:237], v163
	v_cvt_pk_f32_fp8_sdwa v[238:239], v163 src0_sel:WORD_1
	v_pk_fma_f32 v[228:229], v[70:71], v[236:237], v[228:229] op_sel:[1,0,0]
	v_pk_fma_f32 v[230:231], v[70:71], v[238:239], v[230:231] op_sel:[1,0,0]
	s_waitcnt vmcnt(11)
	v_cvt_pk_f32_fp8_e32 v[232:233], v164
	v_cvt_pk_f32_fp8_sdwa v[234:235], v164 src0_sel:WORD_1
	v_pk_fma_f32 v[216:217], v[72:73], v[232:233], v[216:217] op_sel_hi:[0,1,1]
	v_pk_fma_f32 v[218:219], v[72:73], v[234:235], v[218:219] op_sel_hi:[0,1,1]
	v_cvt_pk_f32_fp8_e32 v[236:237], v165
	v_cvt_pk_f32_fp8_sdwa v[238:239], v165 src0_sel:WORD_1
	v_pk_fma_f32 v[220:221], v[72:73], v[236:237], v[220:221] op_sel_hi:[0,1,1]
	v_pk_fma_f32 v[222:223], v[72:73], v[238:239], v[222:223] op_sel_hi:[0,1,1]
	v_cvt_pk_f32_fp8_e32 v[232:233], v166
	v_cvt_pk_f32_fp8_sdwa v[234:235], v166 src0_sel:WORD_1
	v_pk_fma_f32 v[224:225], v[72:73], v[232:233], v[224:225] op_sel_hi:[0,1,1]
	v_pk_fma_f32 v[226:227], v[72:73], v[234:235], v[226:227] op_sel_hi:[0,1,1]
	v_cvt_pk_f32_fp8_e32 v[236:237], v167
	v_cvt_pk_f32_fp8_sdwa v[238:239], v167 src0_sel:WORD_1
	v_pk_fma_f32 v[228:229], v[72:73], v[236:237], v[228:229] op_sel_hi:[0,1,1]
	v_pk_fma_f32 v[230:231], v[72:73], v[238:239], v[230:231] op_sel_hi:[0,1,1]
	s_waitcnt vmcnt(10)
	v_cvt_pk_f32_fp8_e32 v[232:233], v168
	v_cvt_pk_f32_fp8_sdwa v[234:235], v168 src0_sel:WORD_1
	v_pk_fma_f32 v[216:217], v[72:73], v[232:233], v[216:217] op_sel:[1,0,0]
	v_pk_fma_f32 v[218:219], v[72:73], v[234:235], v[218:219] op_sel:[1,0,0]
	v_cvt_pk_f32_fp8_e32 v[236:237], v169
	v_cvt_pk_f32_fp8_sdwa v[238:239], v169 src0_sel:WORD_1
	v_pk_fma_f32 v[220:221], v[72:73], v[236:237], v[220:221] op_sel:[1,0,0]
	v_pk_fma_f32 v[222:223], v[72:73], v[238:239], v[222:223] op_sel:[1,0,0]
	v_cvt_pk_f32_fp8_e32 v[232:233], v170
	v_cvt_pk_f32_fp8_sdwa v[234:235], v170 src0_sel:WORD_1
	v_pk_fma_f32 v[224:225], v[72:73], v[232:233], v[224:225] op_sel:[1,0,0]
	v_pk_fma_f32 v[226:227], v[72:73], v[234:235], v[226:227] op_sel:[1,0,0]
	v_cvt_pk_f32_fp8_e32 v[236:237], v171
	v_cvt_pk_f32_fp8_sdwa v[238:239], v171 src0_sel:WORD_1
	v_pk_fma_f32 v[228:229], v[72:73], v[236:237], v[228:229] op_sel:[1,0,0]
	v_pk_fma_f32 v[230:231], v[72:73], v[238:239], v[230:231] op_sel:[1,0,0]
	s_waitcnt vmcnt(9)
	v_cvt_pk_f32_fp8_e32 v[232:233], v172
	v_cvt_pk_f32_fp8_sdwa v[234:235], v172 src0_sel:WORD_1
	v_pk_fma_f32 v[216:217], v[74:75], v[232:233], v[216:217] op_sel_hi:[0,1,1]
	v_pk_fma_f32 v[218:219], v[74:75], v[234:235], v[218:219] op_sel_hi:[0,1,1]
	v_cvt_pk_f32_fp8_e32 v[236:237], v173
	v_cvt_pk_f32_fp8_sdwa v[238:239], v173 src0_sel:WORD_1
	v_pk_fma_f32 v[220:221], v[74:75], v[236:237], v[220:221] op_sel_hi:[0,1,1]
	v_pk_fma_f32 v[222:223], v[74:75], v[238:239], v[222:223] op_sel_hi:[0,1,1]
	v_cvt_pk_f32_fp8_e32 v[232:233], v174
	v_cvt_pk_f32_fp8_sdwa v[234:235], v174 src0_sel:WORD_1
	v_pk_fma_f32 v[224:225], v[74:75], v[232:233], v[224:225] op_sel_hi:[0,1,1]
	v_pk_fma_f32 v[226:227], v[74:75], v[234:235], v[226:227] op_sel_hi:[0,1,1]
	v_cvt_pk_f32_fp8_e32 v[236:237], v175
	v_cvt_pk_f32_fp8_sdwa v[238:239], v175 src0_sel:WORD_1
	v_pk_fma_f32 v[228:229], v[74:75], v[236:237], v[228:229] op_sel_hi:[0,1,1]
	v_pk_fma_f32 v[230:231], v[74:75], v[238:239], v[230:231] op_sel_hi:[0,1,1]
	s_waitcnt vmcnt(8)
; DI f2_t cvt8lo(unsigned w) { return __builtin_amdgcn_cvt_pk_f32_fp8(w, false); }
; DI f2_t cvt8hi(unsigned w) { return __builtin_amdgcn_cvt_pk_f32_fp8(w, true); }
; DI void phase11(const Params& p, char* smem, int rep) {
;     ...
;         for (int k = 0; k < 16; ++k) {
;           const f2_t a2 = {aa[k], aa[k]};
; #pragma unroll
;           for (int d = 0; d < 4; ++d) { const unsigned ww = rows[k][d]; o[2 * d] += a2 * cvt8lo(ww); o[2 * d + 1] += a2 * cvt8hi(ww); }
;         }
	v_cvt_pk_f32_fp8_e32 v[232:233], v176
	v_cvt_pk_f32_fp8_sdwa v[234:235], v176 src0_sel:WORD_1
	v_pk_fma_f32 v[216:217], v[74:75], v[232:233], v[216:217] op_sel:[1,0,0]
	v_pk_fma_f32 v[218:219], v[74:75], v[234:235], v[218:219] op_sel:[1,0,0]
	v_cvt_pk_f32_fp8_e32 v[236:237], v177
	v_cvt_pk_f32_fp8_sdwa v[238:239], v177 src0_sel:WORD_1
	v_pk_fma_f32 v[220:221], v[74:75], v[236:237], v[220:221] op_sel:[1,0,0]
	v_pk_fma_f32 v[222:223], v[74:75], v[238:239], v[222:223] op_sel:[1,0,0]
	v_cvt_pk_f32_fp8_e32 v[232:233], v178
	v_cvt_pk_f32_fp8_sdwa v[234:235], v178 src0_sel:WORD_1
	v_pk_fma_f32 v[224:225], v[74:75], v[232:233], v[224:225] op_sel:[1,0,0]
	v_pk_fma_f32 v[226:227], v[74:75], v[234:235], v[226:227] op_sel:[1,0,0]
	v_cvt_pk_f32_fp8_e32 v[236:237], v179
	v_cvt_pk_f32_fp8_sdwa v[238:239], v179 src0_sel:WORD_1
	v_pk_fma_f32 v[228:229], v[74:75], v[236:237], v[228:229] op_sel:[1,0,0]
	v_pk_fma_f32 v[230:231], v[74:75], v[238:239], v[230:231] op_sel:[1,0,0]
	s_waitcnt vmcnt(7)
	v_cvt_pk_f32_fp8_e32 v[232:233], v180
	v_cvt_pk_f32_fp8_sdwa v[234:235], v180 src0_sel:WORD_1
	v_pk_fma_f32 v[216:217], v[76:77], v[232:233], v[216:217] op_sel_hi:[0,1,1]
	v_pk_fma_f32 v[218:219], v[76:77], v[234:235], v[218:219] op_sel_hi:[0,1,1]
	v_cvt_pk_f32_fp8_e32 v[236:237], v181
	v_cvt_pk_f32_fp8_sdwa v[238:239], v181 src0_sel:WORD_1
	v_pk_fma_f32 v[220:221], v[76:77], v[236:237], v[220:221] op_sel_hi:[0,1,1]
	v_pk_fma_f32 v[222:223], v[76:77], v[238:239], v[222:223] op_sel_hi:[0,1,1]
	v_cvt_pk_f32_fp8_e32 v[232:233], v182
	v_cvt_pk_f32_fp8_sdwa v[234:235], v182 src0_sel:WORD_1
	v_pk_fma_f32 v[224:225], v[76:77], v[232:233], v[224:225] op_sel_hi:[0,1,1]
	v_pk_fma_f32 v[226:227], v[76:77], v[234:235], v[226:227] op_sel_hi:[0,1,1]
	v_cvt_pk_f32_fp8_e32 v[236:237], v183
	v_cvt_pk_f32_fp8_sdwa v[238:239], v183 src0_sel:WORD_1
	v_pk_fma_f32 v[228:229], v[76:77], v[236:237], v[228:229] op_sel_hi:[0,1,1]
	v_pk_fma_f32 v[230:231], v[76:77], v[238:239], v[230:231] op_sel_hi:[0,1,1]
	s_waitcnt vmcnt(6)
	v_cvt_pk_f32_fp8_e32 v[232:233], v184
	v_cvt_pk_f32_fp8_sdwa v[234:235], v184 src0_sel:WORD_1
	v_pk_fma_f32 v[216:217], v[76:77], v[232:233], v[216:217] op_sel:[1,0,0]
	v_pk_fma_f32 v[218:219], v[76:77], v[234:235], v[218:219] op_sel:[1,0,0]
	v_cvt_pk_f32_fp8_e32 v[236:237], v185
	v_cvt_pk_f32_fp8_sdwa v[238:239], v185 src0_sel:WORD_1
	v_pk_fma_f32 v[220:221], v[76:77], v[236:237], v[220:221] op_sel:[1,0,0]
	v_pk_fma_f32 v[222:223], v[76:77], v[238:239], v[222:223] op_sel:[1,0,0]
	v_cvt_pk_f32_fp8_e32 v[232:233], v186
	v_cvt_pk_f32_fp8_sdwa v[234:235], v186 src0_sel:WORD_1
	v_pk_fma_f32 v[224:225], v[76:77], v[232:233], v[224:225] op_sel:[1,0,0]
	v_pk_fma_f32 v[226:227], v[76:77], v[234:235], v[226:227] op_sel:[1,0,0]
	v_cvt_pk_f32_fp8_e32 v[236:237], v187
	v_cvt_pk_f32_fp8_sdwa v[238:239], v187 src0_sel:WORD_1
	v_pk_fma_f32 v[228:229], v[76:77], v[236:237], v[228:229] op_sel:[1,0,0]
	v_pk_fma_f32 v[230:231], v[76:77], v[238:239], v[230:231] op_sel:[1,0,0]
	s_waitcnt vmcnt(5)
	v_cvt_pk_f32_fp8_e32 v[232:233], v190
	v_cvt_pk_f32_fp8_sdwa v[234:235], v190 src0_sel:WORD_1
	v_pk_fma_f32 v[216:217], v[78:79], v[232:233], v[216:217] op_sel_hi:[0,1,1]
	v_pk_fma_f32 v[218:219], v[78:79], v[234:235], v[218:219] op_sel_hi:[0,1,1]
	v_cvt_pk_f32_fp8_e32 v[236:237], v191
	v_cvt_pk_f32_fp8_sdwa v[238:239], v191 src0_sel:WORD_1
	v_pk_fma_f32 v[220:221], v[78:79], v[236:237], v[220:221] op_sel_hi:[0,1,1]
	v_pk_fma_f32 v[222:223], v[78:79], v[238:239], v[222:223] op_sel_hi:[0,1,1]
	v_cvt_pk_f32_fp8_e32 v[232:233], v192
	v_cvt_pk_f32_fp8_sdwa v[234:235], v192 src0_sel:WORD_1
	v_pk_fma_f32 v[224:225], v[78:79], v[232:233], v[224:225] op_sel_hi:[0,1,1]
	v_pk_fma_f32 v[226:227], v[78:79], v[234:235], v[226:227] op_sel_hi:[0,1,1]
	v_cvt_pk_f32_fp8_e32 v[236:237], v193
	v_cvt_pk_f32_fp8_sdwa v[238:239], v193 src0_sel:WORD_1
	v_pk_fma_f32 v[228:229], v[78:79], v[236:237], v[228:229] op_sel_hi:[0,1,1]
	v_pk_fma_f32 v[230:231], v[78:79], v[238:239], v[230:231] op_sel_hi:[0,1,1]
	s_waitcnt vmcnt(4)
	v_cvt_pk_f32_fp8_e32 v[232:233], v194
	v_cvt_pk_f32_fp8_sdwa v[234:235], v194 src0_sel:WORD_1
	v_pk_fma_f32 v[216:217], v[78:79], v[232:233], v[216:217] op_sel:[1,0,0]
	v_pk_fma_f32 v[218:219], v[78:79], v[234:235], v[218:219] op_sel:[1,0,0]
	v_cvt_pk_f32_fp8_e32 v[236:237], v195
	v_cvt_pk_f32_fp8_sdwa v[238:239], v195 src0_sel:WORD_1
	v_pk_fma_f32 v[220:221], v[78:79], v[236:237], v[220:221] op_sel:[1,0,0]
	v_pk_fma_f32 v[222:223], v[78:79], v[238:239], v[222:223] op_sel:[1,0,0]
	v_cvt_pk_f32_fp8_e32 v[232:233], v196
	v_cvt_pk_f32_fp8_sdwa v[234:235], v196 src0_sel:WORD_1
	v_pk_fma_f32 v[224:225], v[78:79], v[232:233], v[224:225] op_sel:[1,0,0]
	v_pk_fma_f32 v[226:227], v[78:79], v[234:235], v[226:227] op_sel:[1,0,0]
	v_cvt_pk_f32_fp8_e32 v[236:237], v197
	v_cvt_pk_f32_fp8_sdwa v[238:239], v197 src0_sel:WORD_1
	v_pk_fma_f32 v[228:229], v[78:79], v[236:237], v[228:229] op_sel:[1,0,0]
	v_pk_fma_f32 v[230:231], v[78:79], v[238:239], v[230:231] op_sel:[1,0,0]
	s_waitcnt vmcnt(3)
	v_cvt_pk_f32_fp8_e32 v[232:233], v198
	v_cvt_pk_f32_fp8_sdwa v[234:235], v198 src0_sel:WORD_1
	v_pk_fma_f32 v[216:217], v[80:81], v[232:233], v[216:217] op_sel_hi:[0,1,1]
	v_pk_fma_f32 v[218:219], v[80:81], v[234:235], v[218:219] op_sel_hi:[0,1,1]
	v_cvt_pk_f32_fp8_e32 v[236:237], v199
	v_cvt_pk_f32_fp8_sdwa v[238:239], v199 src0_sel:WORD_1
	v_pk_fma_f32 v[220:221], v[80:81], v[236:237], v[220:221] op_sel_hi:[0,1,1]
	v_pk_fma_f32 v[222:223], v[80:81], v[238:239], v[222:223] op_sel_hi:[0,1,1]
	v_cvt_pk_f32_fp8_e32 v[232:233], v200
	v_cvt_pk_f32_fp8_sdwa v[234:235], v200 src0_sel:WORD_1
	v_pk_fma_f32 v[224:225], v[80:81], v[232:233], v[224:225] op_sel_hi:[0,1,1]
	v_pk_fma_f32 v[226:227], v[80:81], v[234:235], v[226:227] op_sel_hi:[0,1,1]
	v_cvt_pk_f32_fp8_e32 v[236:237], v201
	v_cvt_pk_f32_fp8_sdwa v[238:239], v201 src0_sel:WORD_1
	v_pk_fma_f32 v[228:229], v[80:81], v[236:237], v[228:229] op_sel_hi:[0,1,1]
	v_pk_fma_f32 v[230:231], v[80:81], v[238:239], v[230:231] op_sel_hi:[0,1,1]
	s_waitcnt vmcnt(2)
; DI unsigned pk2(float a, float b) { f2_t v = {a, b}; bf2_t r = __builtin_convertvector(v, bf2_t); return __builtin_bit_cast(unsigned, r); }
; DI f2_t cvt8lo(unsigned w) { return __builtin_amdgcn_cvt_pk_f32_fp8(w, false); }
; DI f2_t cvt8hi(unsigned w) { return __builtin_amdgcn_cvt_pk_f32_fp8(w, true); }
; DI void phase11(const Params& p, char* smem, int rep) {
;     ...
;         for (int k = 0; k < 16; ++k) {
;           const f2_t a2 = {aa[k], aa[k]};
; #pragma unroll
;           for (int d = 0; d < 4; ++d) { const unsigned ww = rows[k][d]; o[2 * d] += a2 * cvt8lo(ww); o[2 * d + 1] += a2 * cvt8hi(ww); }
;         }
;       }
;       float ov[16];
; #pragma unroll
;       for (int d = 0; d < 4; ++d) { ov[4 * d] = o[2 * d].x; ov[4 * d + 1] = o[2 * d].y; ov[4 * d + 2] = o[2 * d + 1].x; ov[4 * d + 3] = o[2 * d + 1].y; }
;       float q8[8], q4[4];
; #pragma unroll
;       for (int k = 0; k < 8; ++k) q8[k] = (b5 ? ov[8 + k] : ov[k]) + __shfl_xor(b5 ? ov[k] : ov[8 + k], 32);
; #pragma unroll
;       for (int k = 0; k < 4; ++k) q4[k] = (b4 ? q8[4 + k] : q8[k]) + __shfl_xor(b4 ? q8[k] : q8[4 + k], 16);
;       *(uint2*)(OUTP + (size_t)tok * D_ + s * 256 + l15 * 16 + 8 * b5 + 4 * b4) = make_uint2(pk2(q4[0], q4[1]), pk2(q4[2], q4[3]));
	v_cvt_pk_f32_fp8_e32 v[232:233], v202
	v_cvt_pk_f32_fp8_sdwa v[234:235], v202 src0_sel:WORD_1
	v_pk_fma_f32 v[216:217], v[80:81], v[232:233], v[216:217] op_sel:[1,0,0]
	v_pk_fma_f32 v[218:219], v[80:81], v[234:235], v[218:219] op_sel:[1,0,0]
	v_cvt_pk_f32_fp8_e32 v[236:237], v203
	v_cvt_pk_f32_fp8_sdwa v[238:239], v203 src0_sel:WORD_1
	v_pk_fma_f32 v[220:221], v[80:81], v[236:237], v[220:221] op_sel:[1,0,0]
	v_pk_fma_f32 v[222:223], v[80:81], v[238:239], v[222:223] op_sel:[1,0,0]
	v_cvt_pk_f32_fp8_e32 v[232:233], v204
	v_cvt_pk_f32_fp8_sdwa v[234:235], v204 src0_sel:WORD_1
	v_pk_fma_f32 v[224:225], v[80:81], v[232:233], v[224:225] op_sel:[1,0,0]
	v_pk_fma_f32 v[226:227], v[80:81], v[234:235], v[226:227] op_sel:[1,0,0]
	v_cvt_pk_f32_fp8_e32 v[236:237], v205
	v_cvt_pk_f32_fp8_sdwa v[238:239], v205 src0_sel:WORD_1
	v_pk_fma_f32 v[228:229], v[80:81], v[236:237], v[228:229] op_sel:[1,0,0]
	v_pk_fma_f32 v[230:231], v[80:81], v[238:239], v[230:231] op_sel:[1,0,0]
	s_waitcnt vmcnt(1)
	v_cvt_pk_f32_fp8_e32 v[232:233], v206
	v_cvt_pk_f32_fp8_sdwa v[234:235], v206 src0_sel:WORD_1
	v_pk_fma_f32 v[216:217], v[82:83], v[232:233], v[216:217] op_sel_hi:[0,1,1]
	v_pk_fma_f32 v[218:219], v[82:83], v[234:235], v[218:219] op_sel_hi:[0,1,1]
	v_cvt_pk_f32_fp8_e32 v[236:237], v207
	v_cvt_pk_f32_fp8_sdwa v[238:239], v207 src0_sel:WORD_1
	v_pk_fma_f32 v[220:221], v[82:83], v[236:237], v[220:221] op_sel_hi:[0,1,1]
	v_pk_fma_f32 v[222:223], v[82:83], v[238:239], v[222:223] op_sel_hi:[0,1,1]
	v_cvt_pk_f32_fp8_e32 v[232:233], v208
	v_cvt_pk_f32_fp8_sdwa v[234:235], v208 src0_sel:WORD_1
	v_pk_fma_f32 v[224:225], v[82:83], v[232:233], v[224:225] op_sel_hi:[0,1,1]
	v_pk_fma_f32 v[226:227], v[82:83], v[234:235], v[226:227] op_sel_hi:[0,1,1]
	v_cvt_pk_f32_fp8_e32 v[236:237], v209
	v_cvt_pk_f32_fp8_sdwa v[238:239], v209 src0_sel:WORD_1
	v_pk_fma_f32 v[228:229], v[82:83], v[236:237], v[228:229] op_sel_hi:[0,1,1]
	v_pk_fma_f32 v[230:231], v[82:83], v[238:239], v[230:231] op_sel_hi:[0,1,1]
	s_waitcnt vmcnt(0)
	v_cvt_pk_f32_fp8_e32 v[232:233], v210
	v_cvt_pk_f32_fp8_sdwa v[234:235], v210 src0_sel:WORD_1
	v_pk_fma_f32 v[216:217], v[82:83], v[232:233], v[216:217] op_sel:[1,0,0]
	v_pk_fma_f32 v[218:219], v[82:83], v[234:235], v[218:219] op_sel:[1,0,0]
	v_cvt_pk_f32_fp8_e32 v[236:237], v211
	v_cvt_pk_f32_fp8_sdwa v[238:239], v211 src0_sel:WORD_1
	v_pk_fma_f32 v[220:221], v[82:83], v[236:237], v[220:221] op_sel:[1,0,0]
	v_pk_fma_f32 v[222:223], v[82:83], v[238:239], v[222:223] op_sel:[1,0,0]
	v_cvt_pk_f32_fp8_e32 v[232:233], v212
	v_cvt_pk_f32_fp8_sdwa v[234:235], v212 src0_sel:WORD_1
	v_pk_fma_f32 v[224:225], v[82:83], v[232:233], v[224:225] op_sel:[1,0,0]
	v_pk_fma_f32 v[226:227], v[82:83], v[234:235], v[226:227] op_sel:[1,0,0]
	v_cvt_pk_f32_fp8_e32 v[236:237], v213
	v_cvt_pk_f32_fp8_sdwa v[238:239], v213 src0_sel:WORD_1
	v_pk_fma_f32 v[228:229], v[82:83], v[236:237], v[228:229] op_sel:[1,0,0]
	v_pk_fma_f32 v[230:231], v[82:83], v[238:239], v[230:231] op_sel:[1,0,0]
	ds_read_b128 v[52:55], v6 offset:528
	ds_read_b128 v[56:59], v6 offset:544
	ds_read_b128 v[60:63], v6 offset:560
	ds_read_b128 v[64:67], v6 offset:576
	ds_read_b128 v[68:71], v6 offset:592
	ds_read_b128 v[72:75], v6 offset:608
	ds_read_b128 v[76:79], v6 offset:624
	ds_read_b128 v[80:83], v6 offset:640
	v_add_u32_e32 v214, s46, v4
	s_nop 0
	v_permlane32_swap_b32_e32 v216, v224
	v_permlane32_swap_b32_e32 v217, v225
	v_permlane32_swap_b32_e32 v218, v226
	v_permlane32_swap_b32_e32 v219, v227
	v_permlane32_swap_b32_e32 v220, v228
	v_permlane32_swap_b32_e32 v221, v229
	v_permlane32_swap_b32_e32 v222, v230
	v_permlane32_swap_b32_e32 v223, v231
	v_pk_add_f32 v[216:217], v[216:217], v[224:225]
	v_pk_add_f32 v[218:219], v[218:219], v[226:227]
	v_pk_add_f32 v[220:221], v[220:221], v[228:229]
	v_pk_add_f32 v[222:223], v[222:223], v[230:231]
	s_nop 1
	v_permlane16_swap_b32_e32 v216, v220
	v_permlane16_swap_b32_e32 v217, v221
	v_permlane16_swap_b32_e32 v218, v222
	v_permlane16_swap_b32_e32 v219, v223
	v_pk_add_f32 v[216:217], v[216:217], v[220:221]
	v_pk_add_f32 v[218:219], v[218:219], v[222:223]
	v_cvt_pk_bf16_f32 v232, v216, v217
	v_cvt_pk_bf16_f32 v233, v218, v219
	global_store_dwordx2 v214, v[232:233], s[14:15]
	s_add_i32 s54, s34, 2
	s_lshl_b32 s46, s54, 12
	s_add_i32 s46, s46, s24
	s_add_i32 s55, s34, 3
	s_lshl_b32 s47, s55, 9
	s_add_u32 s42, s6, s47
	s_addc_u32 s43, s7, 0
	s_add_u32 s44, s8, s47
	s_addc_u32 s45, s9, 0
	global_load_dword v10, v3, s[42:43]
	global_load_dword v11, v3, s[42:43] offset:256
	global_load_dword v12, v3, s[44:45]
	global_load_dword v13, v3, s[44:45] offset:256
	s_waitcnt lgkmcnt(0)
; DI f2_t cvt8lo(unsigned w) { return __builtin_amdgcn_cvt_pk_f32_fp8(w, false); }
; DI f2_t cvt8hi(unsigned w) { return __builtin_amdgcn_cvt_pk_f32_fp8(w, true); }
; DI void phase11(const Params& p, char* smem, int rep) {
;     ...
;         for (int k = 0; k < 16; ++k) rows[k] = *(const u32x4*)(vb + (size_t)ida[k] * 2048);
; #pragma unroll
;         for (int k = 0; k < 16; ++k) {
;           const f2_t a2 = {aa[k], aa[k]};
; #pragma unroll
;           for (int d = 0; d < 4; ++d) { const unsigned ww = rows[k][d]; o[2 * d] += a2 * cvt8lo(ww); o[2 * d + 1] += a2 * cvt8hi(ww); }
	v_lshl_add_u32 v20, v20, 11, v2
	v_lshl_add_u32 v21, v21, 11, v2
	v_lshl_add_u32 v22, v22, 11, v2
	v_lshl_add_u32 v23, v23, 11, v2
	v_lshl_add_u32 v24, v24, 11, v2
	v_lshl_add_u32 v25, v25, 11, v2
	v_lshl_add_u32 v26, v26, 11, v2
	v_lshl_add_u32 v27, v27, 11, v2
	v_lshl_add_u32 v28, v28, 11, v2
	v_lshl_add_u32 v29, v29, 11, v2
	v_lshl_add_u32 v30, v30, 11, v2
	v_lshl_add_u32 v31, v31, 11, v2
	v_lshl_add_u32 v32, v32, 11, v2
	v_lshl_add_u32 v33, v33, 11, v2
	v_lshl_add_u32 v34, v34, 11, v2
	v_lshl_add_u32 v35, v35, 11, v2
	v_lshl_add_u32 v36, v36, 11, v2
	v_lshl_add_u32 v37, v37, 11, v2
	v_lshl_add_u32 v38, v38, 11, v2
	v_lshl_add_u32 v39, v39, 11, v2
	v_lshl_add_u32 v40, v40, 11, v2
	v_lshl_add_u32 v41, v41, 11, v2
	v_lshl_add_u32 v42, v42, 11, v2
	v_lshl_add_u32 v43, v43, 11, v2
	v_lshl_add_u32 v44, v44, 11, v2
	v_lshl_add_u32 v45, v45, 11, v2
	v_lshl_add_u32 v46, v46, 11, v2
	v_lshl_add_u32 v47, v47, 11, v2
	v_lshl_add_u32 v48, v48, 11, v2
	v_lshl_add_u32 v49, v49, 11, v2
	v_lshl_add_u32 v50, v50, 11, v2
	v_lshl_add_u32 v51, v51, 11, v2
	global_load_dwordx4 v[84:87], v20, s[20:21]
	global_load_dwordx4 v[88:91], v21, s[20:21]
	global_load_dwordx4 v[92:95], v22, s[20:21]
	global_load_dwordx4 v[96:99], v23, s[20:21]
	global_load_dwordx4 v[100:103], v24, s[20:21]
	global_load_dwordx4 v[104:107], v25, s[20:21]
	global_load_dwordx4 v[108:111], v26, s[20:21]
	global_load_dwordx4 v[112:115], v27, s[20:21]
	global_load_dwordx4 v[116:119], v28, s[20:21]
	global_load_dwordx4 v[120:123], v29, s[20:21]
	global_load_dwordx4 v[124:127], v30, s[20:21]
	global_load_dwordx4 v[128:131], v31, s[20:21]
	global_load_dwordx4 v[132:135], v32, s[20:21]
	global_load_dwordx4 v[136:139], v33, s[20:21]
	global_load_dwordx4 v[140:143], v34, s[20:21]
	global_load_dwordx4 v[144:147], v35, s[20:21]
	global_load_dwordx4 v[148:151], v36, s[20:21]
	global_load_dwordx4 v[152:155], v37, s[20:21]
	global_load_dwordx4 v[156:159], v38, s[20:21]
	global_load_dwordx4 v[160:163], v39, s[20:21]
	global_load_dwordx4 v[164:167], v40, s[20:21]
	global_load_dwordx4 v[168:171], v41, s[20:21]
	global_load_dwordx4 v[172:175], v42, s[20:21]
	global_load_dwordx4 v[176:179], v43, s[20:21]
	global_load_dwordx4 v[180:183], v44, s[20:21]
	global_load_dwordx4 v[184:187], v45, s[20:21]
	global_load_dwordx4 v[190:193], v46, s[20:21]
	global_load_dwordx4 v[194:197], v47, s[20:21]
	global_load_dwordx4 v[198:201], v48, s[20:21]
	global_load_dwordx4 v[202:205], v49, s[20:21]
	global_load_dwordx4 v[206:209], v50, s[20:21]
	global_load_dwordx4 v[210:213], v51, s[20:21]
	s_waitcnt vmcnt(31)
	v_cvt_pk_f32_fp8_e32 v[232:233], v84
	v_cvt_pk_f32_fp8_sdwa v[234:235], v84 src0_sel:WORD_1
	v_pk_fma_f32 v[216:217], v[52:53], v[232:233], 0 op_sel_hi:[0,1,0]
	v_pk_fma_f32 v[218:219], v[52:53], v[234:235], 0 op_sel_hi:[0,1,0]
	v_cvt_pk_f32_fp8_e32 v[236:237], v85
	v_cvt_pk_f32_fp8_sdwa v[238:239], v85 src0_sel:WORD_1
	v_pk_fma_f32 v[220:221], v[52:53], v[236:237], 0 op_sel_hi:[0,1,0]
	v_pk_fma_f32 v[222:223], v[52:53], v[238:239], 0 op_sel_hi:[0,1,0]
	v_cvt_pk_f32_fp8_e32 v[232:233], v86
	v_cvt_pk_f32_fp8_sdwa v[234:235], v86 src0_sel:WORD_1
	v_pk_fma_f32 v[224:225], v[52:53], v[232:233], 0 op_sel_hi:[0,1,0]
	v_pk_fma_f32 v[226:227], v[52:53], v[234:235], 0 op_sel_hi:[0,1,0]
	v_cvt_pk_f32_fp8_e32 v[236:237], v87
	v_cvt_pk_f32_fp8_sdwa v[238:239], v87 src0_sel:WORD_1
	v_pk_fma_f32 v[228:229], v[52:53], v[236:237], 0 op_sel_hi:[0,1,0]
	v_pk_fma_f32 v[230:231], v[52:53], v[238:239], 0 op_sel_hi:[0,1,0]
	s_waitcnt vmcnt(30)
	v_cvt_pk_f32_fp8_e32 v[232:233], v88
	v_cvt_pk_f32_fp8_sdwa v[234:235], v88 src0_sel:WORD_1
	v_pk_fma_f32 v[216:217], v[52:53], v[232:233], v[216:217] op_sel:[1,0,0]
	v_pk_fma_f32 v[218:219], v[52:53], v[234:235], v[218:219] op_sel:[1,0,0]
	v_cvt_pk_f32_fp8_e32 v[236:237], v89
	v_cvt_pk_f32_fp8_sdwa v[238:239], v89 src0_sel:WORD_1
	v_pk_fma_f32 v[220:221], v[52:53], v[236:237], v[220:221] op_sel:[1,0,0]
	v_pk_fma_f32 v[222:223], v[52:53], v[238:239], v[222:223] op_sel:[1,0,0]
	v_cvt_pk_f32_fp8_e32 v[232:233], v90
	v_cvt_pk_f32_fp8_sdwa v[234:235], v90 src0_sel:WORD_1
	v_pk_fma_f32 v[224:225], v[52:53], v[232:233], v[224:225] op_sel:[1,0,0]
	v_pk_fma_f32 v[226:227], v[52:53], v[234:235], v[226:227] op_sel:[1,0,0]
	v_cvt_pk_f32_fp8_e32 v[236:237], v91
	v_cvt_pk_f32_fp8_sdwa v[238:239], v91 src0_sel:WORD_1
	v_pk_fma_f32 v[228:229], v[52:53], v[236:237], v[228:229] op_sel:[1,0,0]
	v_pk_fma_f32 v[230:231], v[52:53], v[238:239], v[230:231] op_sel:[1,0,0]
	s_waitcnt vmcnt(29)
	v_cvt_pk_f32_fp8_e32 v[232:233], v92
	v_cvt_pk_f32_fp8_sdwa v[234:235], v92 src0_sel:WORD_1
	v_pk_fma_f32 v[216:217], v[54:55], v[232:233], v[216:217] op_sel_hi:[0,1,1]
	v_pk_fma_f32 v[218:219], v[54:55], v[234:235], v[218:219] op_sel_hi:[0,1,1]
	v_cvt_pk_f32_fp8_e32 v[236:237], v93
	v_cvt_pk_f32_fp8_sdwa v[238:239], v93 src0_sel:WORD_1
	v_pk_fma_f32 v[220:221], v[54:55], v[236:237], v[220:221] op_sel_hi:[0,1,1]
	v_pk_fma_f32 v[222:223], v[54:55], v[238:239], v[222:223] op_sel_hi:[0,1,1]
	v_cvt_pk_f32_fp8_e32 v[232:233], v94
	v_cvt_pk_f32_fp8_sdwa v[234:235], v94 src0_sel:WORD_1
	v_pk_fma_f32 v[224:225], v[54:55], v[232:233], v[224:225] op_sel_hi:[0,1,1]
	v_pk_fma_f32 v[226:227], v[54:55], v[234:235], v[226:227] op_sel_hi:[0,1,1]
	v_cvt_pk_f32_fp8_e32 v[236:237], v95
	v_cvt_pk_f32_fp8_sdwa v[238:239], v95 src0_sel:WORD_1
	v_pk_fma_f32 v[228:229], v[54:55], v[236:237], v[228:229] op_sel_hi:[0,1,1]
	v_pk_fma_f32 v[230:231], v[54:55], v[238:239], v[230:231] op_sel_hi:[0,1,1]
	s_waitcnt vmcnt(28)
; DI f2_t cvt8lo(unsigned w) { return __builtin_amdgcn_cvt_pk_f32_fp8(w, false); }
; DI f2_t cvt8hi(unsigned w) { return __builtin_amdgcn_cvt_pk_f32_fp8(w, true); }
; DI void phase11(const Params& p, char* smem, int rep) {
;     ...
;         for (int k = 0; k < 16; ++k) rows[k] = *(const u32x4*)(vb + (size_t)ida[k] * 2048);
; #pragma unroll
;         for (int k = 0; k < 16; ++k) {
;           const f2_t a2 = {aa[k], aa[k]};
; #pragma unroll
;           for (int d = 0; d < 4; ++d) { const unsigned ww = rows[k][d]; o[2 * d] += a2 * cvt8lo(ww); o[2 * d + 1] += a2 * cvt8hi(ww); }
	v_cvt_pk_f32_fp8_e32 v[232:233], v96
	v_cvt_pk_f32_fp8_sdwa v[234:235], v96 src0_sel:WORD_1
	v_pk_fma_f32 v[216:217], v[54:55], v[232:233], v[216:217] op_sel:[1,0,0]
	v_pk_fma_f32 v[218:219], v[54:55], v[234:235], v[218:219] op_sel:[1,0,0]
	v_cvt_pk_f32_fp8_e32 v[236:237], v97
	v_cvt_pk_f32_fp8_sdwa v[238:239], v97 src0_sel:WORD_1
	v_pk_fma_f32 v[220:221], v[54:55], v[236:237], v[220:221] op_sel:[1,0,0]
	v_pk_fma_f32 v[222:223], v[54:55], v[238:239], v[222:223] op_sel:[1,0,0]
	v_cvt_pk_f32_fp8_e32 v[232:233], v98
	v_cvt_pk_f32_fp8_sdwa v[234:235], v98 src0_sel:WORD_1
	v_pk_fma_f32 v[224:225], v[54:55], v[232:233], v[224:225] op_sel:[1,0,0]
	v_pk_fma_f32 v[226:227], v[54:55], v[234:235], v[226:227] op_sel:[1,0,0]
	v_cvt_pk_f32_fp8_e32 v[236:237], v99
	v_cvt_pk_f32_fp8_sdwa v[238:239], v99 src0_sel:WORD_1
	v_pk_fma_f32 v[228:229], v[54:55], v[236:237], v[228:229] op_sel:[1,0,0]
	v_pk_fma_f32 v[230:231], v[54:55], v[238:239], v[230:231] op_sel:[1,0,0]
	s_waitcnt vmcnt(27)
	v_cvt_pk_f32_fp8_e32 v[232:233], v100
	v_cvt_pk_f32_fp8_sdwa v[234:235], v100 src0_sel:WORD_1
	v_pk_fma_f32 v[216:217], v[56:57], v[232:233], v[216:217] op_sel_hi:[0,1,1]
	v_pk_fma_f32 v[218:219], v[56:57], v[234:235], v[218:219] op_sel_hi:[0,1,1]
	v_cvt_pk_f32_fp8_e32 v[236:237], v101
	v_cvt_pk_f32_fp8_sdwa v[238:239], v101 src0_sel:WORD_1
	v_pk_fma_f32 v[220:221], v[56:57], v[236:237], v[220:221] op_sel_hi:[0,1,1]
	v_pk_fma_f32 v[222:223], v[56:57], v[238:239], v[222:223] op_sel_hi:[0,1,1]
	v_cvt_pk_f32_fp8_e32 v[232:233], v102
	v_cvt_pk_f32_fp8_sdwa v[234:235], v102 src0_sel:WORD_1
	v_pk_fma_f32 v[224:225], v[56:57], v[232:233], v[224:225] op_sel_hi:[0,1,1]
	v_pk_fma_f32 v[226:227], v[56:57], v[234:235], v[226:227] op_sel_hi:[0,1,1]
	v_cvt_pk_f32_fp8_e32 v[236:237], v103
	v_cvt_pk_f32_fp8_sdwa v[238:239], v103 src0_sel:WORD_1
	v_pk_fma_f32 v[228:229], v[56:57], v[236:237], v[228:229] op_sel_hi:[0,1,1]
	v_pk_fma_f32 v[230:231], v[56:57], v[238:239], v[230:231] op_sel_hi:[0,1,1]
	s_waitcnt vmcnt(26)
	v_cvt_pk_f32_fp8_e32 v[232:233], v104
	v_cvt_pk_f32_fp8_sdwa v[234:235], v104 src0_sel:WORD_1
	v_pk_fma_f32 v[216:217], v[56:57], v[232:233], v[216:217] op_sel:[1,0,0]
	v_pk_fma_f32 v[218:219], v[56:57], v[234:235], v[218:219] op_sel:[1,0,0]
	v_cvt_pk_f32_fp8_e32 v[236:237], v105
	v_cvt_pk_f32_fp8_sdwa v[238:239], v105 src0_sel:WORD_1
	v_pk_fma_f32 v[220:221], v[56:57], v[236:237], v[220:221] op_sel:[1,0,0]
	v_pk_fma_f32 v[222:223], v[56:57], v[238:239], v[222:223] op_sel:[1,0,0]
	v_cvt_pk_f32_fp8_e32 v[232:233], v106
	v_cvt_pk_f32_fp8_sdwa v[234:235], v106 src0_sel:WORD_1
	v_pk_fma_f32 v[224:225], v[56:57], v[232:233], v[224:225] op_sel:[1,0,0]
	v_pk_fma_f32 v[226:227], v[56:57], v[234:235], v[226:227] op_sel:[1,0,0]
	v_cvt_pk_f32_fp8_e32 v[236:237], v107
	v_cvt_pk_f32_fp8_sdwa v[238:239], v107 src0_sel:WORD_1
	v_pk_fma_f32 v[228:229], v[56:57], v[236:237], v[228:229] op_sel:[1,0,0]
	v_pk_fma_f32 v[230:231], v[56:57], v[238:239], v[230:231] op_sel:[1,0,0]
	s_waitcnt vmcnt(25)
	v_cvt_pk_f32_fp8_e32 v[232:233], v108
	v_cvt_pk_f32_fp8_sdwa v[234:235], v108 src0_sel:WORD_1
	v_pk_fma_f32 v[216:217], v[58:59], v[232:233], v[216:217] op_sel_hi:[0,1,1]
	v_pk_fma_f32 v[218:219], v[58:59], v[234:235], v[218:219] op_sel_hi:[0,1,1]
	v_cvt_pk_f32_fp8_e32 v[236:237], v109
	v_cvt_pk_f32_fp8_sdwa v[238:239], v109 src0_sel:WORD_1
	v_pk_fma_f32 v[220:221], v[58:59], v[236:237], v[220:221] op_sel_hi:[0,1,1]
	v_pk_fma_f32 v[222:223], v[58:59], v[238:239], v[222:223] op_sel_hi:[0,1,1]
	v_cvt_pk_f32_fp8_e32 v[232:233], v110
	v_cvt_pk_f32_fp8_sdwa v[234:235], v110 src0_sel:WORD_1
	v_pk_fma_f32 v[224:225], v[58:59], v[232:233], v[224:225] op_sel_hi:[0,1,1]
	v_pk_fma_f32 v[226:227], v[58:59], v[234:235], v[226:227] op_sel_hi:[0,1,1]
	v_cvt_pk_f32_fp8_e32 v[236:237], v111
	v_cvt_pk_f32_fp8_sdwa v[238:239], v111 src0_sel:WORD_1
	v_pk_fma_f32 v[228:229], v[58:59], v[236:237], v[228:229] op_sel_hi:[0,1,1]
	v_pk_fma_f32 v[230:231], v[58:59], v[238:239], v[230:231] op_sel_hi:[0,1,1]
	s_waitcnt vmcnt(24)
	v_cvt_pk_f32_fp8_e32 v[232:233], v112
	v_cvt_pk_f32_fp8_sdwa v[234:235], v112 src0_sel:WORD_1
	v_pk_fma_f32 v[216:217], v[58:59], v[232:233], v[216:217] op_sel:[1,0,0]
	v_pk_fma_f32 v[218:219], v[58:59], v[234:235], v[218:219] op_sel:[1,0,0]
	v_cvt_pk_f32_fp8_e32 v[236:237], v113
	v_cvt_pk_f32_fp8_sdwa v[238:239], v113 src0_sel:WORD_1
	v_pk_fma_f32 v[220:221], v[58:59], v[236:237], v[220:221] op_sel:[1,0,0]
	v_pk_fma_f32 v[222:223], v[58:59], v[238:239], v[222:223] op_sel:[1,0,0]
	v_cvt_pk_f32_fp8_e32 v[232:233], v114
	v_cvt_pk_f32_fp8_sdwa v[234:235], v114 src0_sel:WORD_1
	v_pk_fma_f32 v[224:225], v[58:59], v[232:233], v[224:225] op_sel:[1,0,0]
	v_pk_fma_f32 v[226:227], v[58:59], v[234:235], v[226:227] op_sel:[1,0,0]
	v_cvt_pk_f32_fp8_e32 v[236:237], v115
	v_cvt_pk_f32_fp8_sdwa v[238:239], v115 src0_sel:WORD_1
	v_pk_fma_f32 v[228:229], v[58:59], v[236:237], v[228:229] op_sel:[1,0,0]
	v_pk_fma_f32 v[230:231], v[58:59], v[238:239], v[230:231] op_sel:[1,0,0]
	s_waitcnt vmcnt(23)
	v_cvt_pk_f32_fp8_e32 v[232:233], v116
	v_cvt_pk_f32_fp8_sdwa v[234:235], v116 src0_sel:WORD_1
	v_pk_fma_f32 v[216:217], v[60:61], v[232:233], v[216:217] op_sel_hi:[0,1,1]
	v_pk_fma_f32 v[218:219], v[60:61], v[234:235], v[218:219] op_sel_hi:[0,1,1]
	v_cvt_pk_f32_fp8_e32 v[236:237], v117
	v_cvt_pk_f32_fp8_sdwa v[238:239], v117 src0_sel:WORD_1
	v_pk_fma_f32 v[220:221], v[60:61], v[236:237], v[220:221] op_sel_hi:[0,1,1]
	v_pk_fma_f32 v[222:223], v[60:61], v[238:239], v[222:223] op_sel_hi:[0,1,1]
	v_cvt_pk_f32_fp8_e32 v[232:233], v118
	v_cvt_pk_f32_fp8_sdwa v[234:235], v118 src0_sel:WORD_1
	v_pk_fma_f32 v[224:225], v[60:61], v[232:233], v[224:225] op_sel_hi:[0,1,1]
	v_pk_fma_f32 v[226:227], v[60:61], v[234:235], v[226:227] op_sel_hi:[0,1,1]
	v_cvt_pk_f32_fp8_e32 v[236:237], v119
	v_cvt_pk_f32_fp8_sdwa v[238:239], v119 src0_sel:WORD_1
	v_pk_fma_f32 v[228:229], v[60:61], v[236:237], v[228:229] op_sel_hi:[0,1,1]
	v_pk_fma_f32 v[230:231], v[60:61], v[238:239], v[230:231] op_sel_hi:[0,1,1]
	s_waitcnt vmcnt(22)
; DI f2_t cvt8lo(unsigned w) { return __builtin_amdgcn_cvt_pk_f32_fp8(w, false); }
; DI f2_t cvt8hi(unsigned w) { return __builtin_amdgcn_cvt_pk_f32_fp8(w, true); }
; DI void phase11(const Params& p, char* smem, int rep) {
;     ...
;         for (int k = 0; k < 16; ++k) rows[k] = *(const u32x4*)(vb + (size_t)ida[k] * 2048);
; #pragma unroll
;         for (int k = 0; k < 16; ++k) {
;           const f2_t a2 = {aa[k], aa[k]};
; #pragma unroll
;           for (int d = 0; d < 4; ++d) { const unsigned ww = rows[k][d]; o[2 * d] += a2 * cvt8lo(ww); o[2 * d + 1] += a2 * cvt8hi(ww); }
	v_cvt_pk_f32_fp8_e32 v[232:233], v120
	v_cvt_pk_f32_fp8_sdwa v[234:235], v120 src0_sel:WORD_1
	v_pk_fma_f32 v[216:217], v[60:61], v[232:233], v[216:217] op_sel:[1,0,0]
	v_pk_fma_f32 v[218:219], v[60:61], v[234:235], v[218:219] op_sel:[1,0,0]
	v_cvt_pk_f32_fp8_e32 v[236:237], v121
	v_cvt_pk_f32_fp8_sdwa v[238:239], v121 src0_sel:WORD_1
	v_pk_fma_f32 v[220:221], v[60:61], v[236:237], v[220:221] op_sel:[1,0,0]
	v_pk_fma_f32 v[222:223], v[60:61], v[238:239], v[222:223] op_sel:[1,0,0]
	v_cvt_pk_f32_fp8_e32 v[232:233], v122
	v_cvt_pk_f32_fp8_sdwa v[234:235], v122 src0_sel:WORD_1
	v_pk_fma_f32 v[224:225], v[60:61], v[232:233], v[224:225] op_sel:[1,0,0]
	v_pk_fma_f32 v[226:227], v[60:61], v[234:235], v[226:227] op_sel:[1,0,0]
	v_cvt_pk_f32_fp8_e32 v[236:237], v123
	v_cvt_pk_f32_fp8_sdwa v[238:239], v123 src0_sel:WORD_1
	v_pk_fma_f32 v[228:229], v[60:61], v[236:237], v[228:229] op_sel:[1,0,0]
	v_pk_fma_f32 v[230:231], v[60:61], v[238:239], v[230:231] op_sel:[1,0,0]
	s_waitcnt vmcnt(21)
	v_cvt_pk_f32_fp8_e32 v[232:233], v124
	v_cvt_pk_f32_fp8_sdwa v[234:235], v124 src0_sel:WORD_1
	v_pk_fma_f32 v[216:217], v[62:63], v[232:233], v[216:217] op_sel_hi:[0,1,1]
	v_pk_fma_f32 v[218:219], v[62:63], v[234:235], v[218:219] op_sel_hi:[0,1,1]
	v_cvt_pk_f32_fp8_e32 v[236:237], v125
	v_cvt_pk_f32_fp8_sdwa v[238:239], v125 src0_sel:WORD_1
	v_pk_fma_f32 v[220:221], v[62:63], v[236:237], v[220:221] op_sel_hi:[0,1,1]
	v_pk_fma_f32 v[222:223], v[62:63], v[238:239], v[222:223] op_sel_hi:[0,1,1]
	v_cvt_pk_f32_fp8_e32 v[232:233], v126
	v_cvt_pk_f32_fp8_sdwa v[234:235], v126 src0_sel:WORD_1
	v_pk_fma_f32 v[224:225], v[62:63], v[232:233], v[224:225] op_sel_hi:[0,1,1]
	v_pk_fma_f32 v[226:227], v[62:63], v[234:235], v[226:227] op_sel_hi:[0,1,1]
	v_cvt_pk_f32_fp8_e32 v[236:237], v127
	v_cvt_pk_f32_fp8_sdwa v[238:239], v127 src0_sel:WORD_1
	v_pk_fma_f32 v[228:229], v[62:63], v[236:237], v[228:229] op_sel_hi:[0,1,1]
	v_pk_fma_f32 v[230:231], v[62:63], v[238:239], v[230:231] op_sel_hi:[0,1,1]
	s_waitcnt vmcnt(20)
	v_cvt_pk_f32_fp8_e32 v[232:233], v128
	v_cvt_pk_f32_fp8_sdwa v[234:235], v128 src0_sel:WORD_1
	v_pk_fma_f32 v[216:217], v[62:63], v[232:233], v[216:217] op_sel:[1,0,0]
	v_pk_fma_f32 v[218:219], v[62:63], v[234:235], v[218:219] op_sel:[1,0,0]
	v_cvt_pk_f32_fp8_e32 v[236:237], v129
	v_cvt_pk_f32_fp8_sdwa v[238:239], v129 src0_sel:WORD_1
	v_pk_fma_f32 v[220:221], v[62:63], v[236:237], v[220:221] op_sel:[1,0,0]
	v_pk_fma_f32 v[222:223], v[62:63], v[238:239], v[222:223] op_sel:[1,0,0]
	v_cvt_pk_f32_fp8_e32 v[232:233], v130
	v_cvt_pk_f32_fp8_sdwa v[234:235], v130 src0_sel:WORD_1
	v_pk_fma_f32 v[224:225], v[62:63], v[232:233], v[224:225] op_sel:[1,0,0]
	v_pk_fma_f32 v[226:227], v[62:63], v[234:235], v[226:227] op_sel:[1,0,0]
	v_cvt_pk_f32_fp8_e32 v[236:237], v131
	v_cvt_pk_f32_fp8_sdwa v[238:239], v131 src0_sel:WORD_1
	v_pk_fma_f32 v[228:229], v[62:63], v[236:237], v[228:229] op_sel:[1,0,0]
	v_pk_fma_f32 v[230:231], v[62:63], v[238:239], v[230:231] op_sel:[1,0,0]
	s_waitcnt vmcnt(19)
	v_cvt_pk_f32_fp8_e32 v[232:233], v132
	v_cvt_pk_f32_fp8_sdwa v[234:235], v132 src0_sel:WORD_1
	v_pk_fma_f32 v[216:217], v[64:65], v[232:233], v[216:217] op_sel_hi:[0,1,1]
	v_pk_fma_f32 v[218:219], v[64:65], v[234:235], v[218:219] op_sel_hi:[0,1,1]
	v_cvt_pk_f32_fp8_e32 v[236:237], v133
	v_cvt_pk_f32_fp8_sdwa v[238:239], v133 src0_sel:WORD_1
	v_pk_fma_f32 v[220:221], v[64:65], v[236:237], v[220:221] op_sel_hi:[0,1,1]
	v_pk_fma_f32 v[222:223], v[64:65], v[238:239], v[222:223] op_sel_hi:[0,1,1]
	v_cvt_pk_f32_fp8_e32 v[232:233], v134
	v_cvt_pk_f32_fp8_sdwa v[234:235], v134 src0_sel:WORD_1
	v_pk_fma_f32 v[224:225], v[64:65], v[232:233], v[224:225] op_sel_hi:[0,1,1]
	v_pk_fma_f32 v[226:227], v[64:65], v[234:235], v[226:227] op_sel_hi:[0,1,1]
	v_cvt_pk_f32_fp8_e32 v[236:237], v135
	v_cvt_pk_f32_fp8_sdwa v[238:239], v135 src0_sel:WORD_1
	v_pk_fma_f32 v[228:229], v[64:65], v[236:237], v[228:229] op_sel_hi:[0,1,1]
	v_pk_fma_f32 v[230:231], v[64:65], v[238:239], v[230:231] op_sel_hi:[0,1,1]
	s_waitcnt vmcnt(18)
	v_cvt_pk_f32_fp8_e32 v[232:233], v136
	v_cvt_pk_f32_fp8_sdwa v[234:235], v136 src0_sel:WORD_1
	v_pk_fma_f32 v[216:217], v[64:65], v[232:233], v[216:217] op_sel:[1,0,0]
	v_pk_fma_f32 v[218:219], v[64:65], v[234:235], v[218:219] op_sel:[1,0,0]
	v_cvt_pk_f32_fp8_e32 v[236:237], v137
	v_cvt_pk_f32_fp8_sdwa v[238:239], v137 src0_sel:WORD_1
	v_pk_fma_f32 v[220:221], v[64:65], v[236:237], v[220:221] op_sel:[1,0,0]
	v_pk_fma_f32 v[222:223], v[64:65], v[238:239], v[222:223] op_sel:[1,0,0]
	v_cvt_pk_f32_fp8_e32 v[232:233], v138
	v_cvt_pk_f32_fp8_sdwa v[234:235], v138 src0_sel:WORD_1
	v_pk_fma_f32 v[224:225], v[64:65], v[232:233], v[224:225] op_sel:[1,0,0]
	v_pk_fma_f32 v[226:227], v[64:65], v[234:235], v[226:227] op_sel:[1,0,0]
	v_cvt_pk_f32_fp8_e32 v[236:237], v139
	v_cvt_pk_f32_fp8_sdwa v[238:239], v139 src0_sel:WORD_1
	v_pk_fma_f32 v[228:229], v[64:65], v[236:237], v[228:229] op_sel:[1,0,0]
	v_pk_fma_f32 v[230:231], v[64:65], v[238:239], v[230:231] op_sel:[1,0,0]
	s_waitcnt vmcnt(17)
	v_cvt_pk_f32_fp8_e32 v[232:233], v140
	v_cvt_pk_f32_fp8_sdwa v[234:235], v140 src0_sel:WORD_1
	v_pk_fma_f32 v[216:217], v[66:67], v[232:233], v[216:217] op_sel_hi:[0,1,1]
	v_pk_fma_f32 v[218:219], v[66:67], v[234:235], v[218:219] op_sel_hi:[0,1,1]
	v_cvt_pk_f32_fp8_e32 v[236:237], v141
	v_cvt_pk_f32_fp8_sdwa v[238:239], v141 src0_sel:WORD_1
	v_pk_fma_f32 v[220:221], v[66:67], v[236:237], v[220:221] op_sel_hi:[0,1,1]
	v_pk_fma_f32 v[222:223], v[66:67], v[238:239], v[222:223] op_sel_hi:[0,1,1]
	v_cvt_pk_f32_fp8_e32 v[232:233], v142
	v_cvt_pk_f32_fp8_sdwa v[234:235], v142 src0_sel:WORD_1
	v_pk_fma_f32 v[224:225], v[66:67], v[232:233], v[224:225] op_sel_hi:[0,1,1]
	v_pk_fma_f32 v[226:227], v[66:67], v[234:235], v[226:227] op_sel_hi:[0,1,1]
	v_cvt_pk_f32_fp8_e32 v[236:237], v143
	v_cvt_pk_f32_fp8_sdwa v[238:239], v143 src0_sel:WORD_1
	v_pk_fma_f32 v[228:229], v[66:67], v[236:237], v[228:229] op_sel_hi:[0,1,1]
	v_pk_fma_f32 v[230:231], v[66:67], v[238:239], v[230:231] op_sel_hi:[0,1,1]
	s_waitcnt vmcnt(16)
; DI f2_t cvt8lo(unsigned w) { return __builtin_amdgcn_cvt_pk_f32_fp8(w, false); }
; DI f2_t cvt8hi(unsigned w) { return __builtin_amdgcn_cvt_pk_f32_fp8(w, true); }
; DI void wave_lds_sync() { asm volatile("s_waitcnt lgkmcnt(0)" ::: "memory"); __builtin_amdgcn_wave_barrier(); }
; DI void phase11(const Params& p, char* smem, int rep) {
;     ...
;       wave_lds_sync();
;       lw[(lane & 3) * 32 + (lane >> 2)] = i0; lw[(lane & 3) * 32 + 16 + (lane >> 2)] = i1;
;       lf[(lane & 3) * 32 + (lane >> 2)] = a0; lf[(lane & 3) * 32 + 16 + (lane >> 2)] = a1;
;       wave_lds_sync();
;     ...
;         for (int k = 0; k < 16; ++k) rows[k] = *(const u32x4*)(vb + (size_t)ida[k] * 2048);
; #pragma unroll
;         for (int k = 0; k < 16; ++k) {
;           const f2_t a2 = {aa[k], aa[k]};
; #pragma unroll
;           for (int d = 0; d < 4; ++d) { const unsigned ww = rows[k][d]; o[2 * d] += a2 * cvt8lo(ww); o[2 * d + 1] += a2 * cvt8hi(ww); }
	v_cvt_pk_f32_fp8_e32 v[232:233], v144
	v_cvt_pk_f32_fp8_sdwa v[234:235], v144 src0_sel:WORD_1
	v_pk_fma_f32 v[216:217], v[66:67], v[232:233], v[216:217] op_sel:[1,0,0]
	v_pk_fma_f32 v[218:219], v[66:67], v[234:235], v[218:219] op_sel:[1,0,0]
	v_cvt_pk_f32_fp8_e32 v[236:237], v145
	v_cvt_pk_f32_fp8_sdwa v[238:239], v145 src0_sel:WORD_1
	v_pk_fma_f32 v[220:221], v[66:67], v[236:237], v[220:221] op_sel:[1,0,0]
	v_pk_fma_f32 v[222:223], v[66:67], v[238:239], v[222:223] op_sel:[1,0,0]
	v_cvt_pk_f32_fp8_e32 v[232:233], v146
	v_cvt_pk_f32_fp8_sdwa v[234:235], v146 src0_sel:WORD_1
	v_pk_fma_f32 v[224:225], v[66:67], v[232:233], v[224:225] op_sel:[1,0,0]
	v_pk_fma_f32 v[226:227], v[66:67], v[234:235], v[226:227] op_sel:[1,0,0]
	v_cvt_pk_f32_fp8_e32 v[236:237], v147
	v_cvt_pk_f32_fp8_sdwa v[238:239], v147 src0_sel:WORD_1
	v_pk_fma_f32 v[228:229], v[66:67], v[236:237], v[228:229] op_sel:[1,0,0]
	v_pk_fma_f32 v[230:231], v[66:67], v[238:239], v[230:231] op_sel:[1,0,0]
	ds_write2_b32 v5, v10, v11 offset0:4 offset1:20
	ds_write2_b32 v5, v12, v13 offset0:132 offset1:148
	s_waitcnt lgkmcnt(0)
	ds_read_b128 v[20:23], v6 offset:16
	ds_read_b128 v[24:27], v6 offset:32
	ds_read_b128 v[28:31], v6 offset:48
	ds_read_b128 v[32:35], v6 offset:64
	ds_read_b128 v[36:39], v6 offset:80
	ds_read_b128 v[40:43], v6 offset:96
	ds_read_b128 v[44:47], v6 offset:112
	ds_read_b128 v[48:51], v6 offset:128
	s_waitcnt vmcnt(15)
	v_cvt_pk_f32_fp8_e32 v[232:233], v148
	v_cvt_pk_f32_fp8_sdwa v[234:235], v148 src0_sel:WORD_1
	v_pk_fma_f32 v[216:217], v[68:69], v[232:233], v[216:217] op_sel_hi:[0,1,1]
	v_pk_fma_f32 v[218:219], v[68:69], v[234:235], v[218:219] op_sel_hi:[0,1,1]
	v_cvt_pk_f32_fp8_e32 v[236:237], v149
	v_cvt_pk_f32_fp8_sdwa v[238:239], v149 src0_sel:WORD_1
	v_pk_fma_f32 v[220:221], v[68:69], v[236:237], v[220:221] op_sel_hi:[0,1,1]
	v_pk_fma_f32 v[222:223], v[68:69], v[238:239], v[222:223] op_sel_hi:[0,1,1]
	v_cvt_pk_f32_fp8_e32 v[232:233], v150
	v_cvt_pk_f32_fp8_sdwa v[234:235], v150 src0_sel:WORD_1
	v_pk_fma_f32 v[224:225], v[68:69], v[232:233], v[224:225] op_sel_hi:[0,1,1]
	v_pk_fma_f32 v[226:227], v[68:69], v[234:235], v[226:227] op_sel_hi:[0,1,1]
	v_cvt_pk_f32_fp8_e32 v[236:237], v151
	v_cvt_pk_f32_fp8_sdwa v[238:239], v151 src0_sel:WORD_1
	v_pk_fma_f32 v[228:229], v[68:69], v[236:237], v[228:229] op_sel_hi:[0,1,1]
	v_pk_fma_f32 v[230:231], v[68:69], v[238:239], v[230:231] op_sel_hi:[0,1,1]
	s_waitcnt vmcnt(14)
	v_cvt_pk_f32_fp8_e32 v[232:233], v152
	v_cvt_pk_f32_fp8_sdwa v[234:235], v152 src0_sel:WORD_1
	v_pk_fma_f32 v[216:217], v[68:69], v[232:233], v[216:217] op_sel:[1,0,0]
	v_pk_fma_f32 v[218:219], v[68:69], v[234:235], v[218:219] op_sel:[1,0,0]
	v_cvt_pk_f32_fp8_e32 v[236:237], v153
	v_cvt_pk_f32_fp8_sdwa v[238:239], v153 src0_sel:WORD_1
	v_pk_fma_f32 v[220:221], v[68:69], v[236:237], v[220:221] op_sel:[1,0,0]
	v_pk_fma_f32 v[222:223], v[68:69], v[238:239], v[222:223] op_sel:[1,0,0]
	v_cvt_pk_f32_fp8_e32 v[232:233], v154
	v_cvt_pk_f32_fp8_sdwa v[234:235], v154 src0_sel:WORD_1
	v_pk_fma_f32 v[224:225], v[68:69], v[232:233], v[224:225] op_sel:[1,0,0]
	v_pk_fma_f32 v[226:227], v[68:69], v[234:235], v[226:227] op_sel:[1,0,0]
	v_cvt_pk_f32_fp8_e32 v[236:237], v155
	v_cvt_pk_f32_fp8_sdwa v[238:239], v155 src0_sel:WORD_1
	v_pk_fma_f32 v[228:229], v[68:69], v[236:237], v[228:229] op_sel:[1,0,0]
	v_pk_fma_f32 v[230:231], v[68:69], v[238:239], v[230:231] op_sel:[1,0,0]
	s_waitcnt vmcnt(13)
	v_cvt_pk_f32_fp8_e32 v[232:233], v156
	v_cvt_pk_f32_fp8_sdwa v[234:235], v156 src0_sel:WORD_1
	v_pk_fma_f32 v[216:217], v[70:71], v[232:233], v[216:217] op_sel_hi:[0,1,1]
	v_pk_fma_f32 v[218:219], v[70:71], v[234:235], v[218:219] op_sel_hi:[0,1,1]
	v_cvt_pk_f32_fp8_e32 v[236:237], v157
	v_cvt_pk_f32_fp8_sdwa v[238:239], v157 src0_sel:WORD_1
	v_pk_fma_f32 v[220:221], v[70:71], v[236:237], v[220:221] op_sel_hi:[0,1,1]
	v_pk_fma_f32 v[222:223], v[70:71], v[238:239], v[222:223] op_sel_hi:[0,1,1]
	v_cvt_pk_f32_fp8_e32 v[232:233], v158
	v_cvt_pk_f32_fp8_sdwa v[234:235], v158 src0_sel:WORD_1
	v_pk_fma_f32 v[224:225], v[70:71], v[232:233], v[224:225] op_sel_hi:[0,1,1]
	v_pk_fma_f32 v[226:227], v[70:71], v[234:235], v[226:227] op_sel_hi:[0,1,1]
	v_cvt_pk_f32_fp8_e32 v[236:237], v159
	v_cvt_pk_f32_fp8_sdwa v[238:239], v159 src0_sel:WORD_1
	v_pk_fma_f32 v[228:229], v[70:71], v[236:237], v[228:229] op_sel_hi:[0,1,1]
	v_pk_fma_f32 v[230:231], v[70:71], v[238:239], v[230:231] op_sel_hi:[0,1,1]
	s_waitcnt vmcnt(12)
	v_cvt_pk_f32_fp8_e32 v[232:233], v160
	v_cvt_pk_f32_fp8_sdwa v[234:235], v160 src0_sel:WORD_1
	v_pk_fma_f32 v[216:217], v[70:71], v[232:233], v[216:217] op_sel:[1,0,0]
	v_pk_fma_f32 v[218:219], v[70:71], v[234:235], v[218:219] op_sel:[1,0,0]
	v_cvt_pk_f32_fp8_e32 v[236:237], v161
	v_cvt_pk_f32_fp8_sdwa v[238:239], v161 src0_sel:WORD_1
	v_pk_fma_f32 v[220:221], v[70:71], v[236:237], v[220:221] op_sel:[1,0,0]
	v_pk_fma_f32 v[222:223], v[70:71], v[238:239], v[222:223] op_sel:[1,0,0]
	v_cvt_pk_f32_fp8_e32 v[232:233], v162
	v_cvt_pk_f32_fp8_sdwa v[234:235], v162 src0_sel:WORD_1
	v_pk_fma_f32 v[224:225], v[70:71], v[232:233], v[224:225] op_sel:[1,0,0]
	v_pk_fma_f32 v[226:227], v[70:71], v[234:235], v[226:227] op_sel:[1,0,0]
	v_cvt_pk_f32_fp8_e32 v[236:237], v163
	v_cvt_pk_f32_fp8_sdwa v[238:239], v163 src0_sel:WORD_1
	v_pk_fma_f32 v[228:229], v[70:71], v[236:237], v[228:229] op_sel:[1,0,0]
	v_pk_fma_f32 v[230:231], v[70:71], v[238:239], v[230:231] op_sel:[1,0,0]
	s_waitcnt vmcnt(11)
; DI f2_t cvt8lo(unsigned w) { return __builtin_amdgcn_cvt_pk_f32_fp8(w, false); }
; DI f2_t cvt8hi(unsigned w) { return __builtin_amdgcn_cvt_pk_f32_fp8(w, true); }
; DI void phase11(const Params& p, char* smem, int rep) {
;     ...
;         for (int k = 0; k < 16; ++k) rows[k] = *(const u32x4*)(vb + (size_t)ida[k] * 2048);
; #pragma unroll
;         for (int k = 0; k < 16; ++k) {
;           const f2_t a2 = {aa[k], aa[k]};
; #pragma unroll
;           for (int d = 0; d < 4; ++d) { const unsigned ww = rows[k][d]; o[2 * d] += a2 * cvt8lo(ww); o[2 * d + 1] += a2 * cvt8hi(ww); }
	v_cvt_pk_f32_fp8_e32 v[232:233], v164
	v_cvt_pk_f32_fp8_sdwa v[234:235], v164 src0_sel:WORD_1
	v_pk_fma_f32 v[216:217], v[72:73], v[232:233], v[216:217] op_sel_hi:[0,1,1]
	v_pk_fma_f32 v[218:219], v[72:73], v[234:235], v[218:219] op_sel_hi:[0,1,1]
	v_cvt_pk_f32_fp8_e32 v[236:237], v165
	v_cvt_pk_f32_fp8_sdwa v[238:239], v165 src0_sel:WORD_1
	v_pk_fma_f32 v[220:221], v[72:73], v[236:237], v[220:221] op_sel_hi:[0,1,1]
	v_pk_fma_f32 v[222:223], v[72:73], v[238:239], v[222:223] op_sel_hi:[0,1,1]
	v_cvt_pk_f32_fp8_e32 v[232:233], v166
	v_cvt_pk_f32_fp8_sdwa v[234:235], v166 src0_sel:WORD_1
	v_pk_fma_f32 v[224:225], v[72:73], v[232:233], v[224:225] op_sel_hi:[0,1,1]
	v_pk_fma_f32 v[226:227], v[72:73], v[234:235], v[226:227] op_sel_hi:[0,1,1]
	v_cvt_pk_f32_fp8_e32 v[236:237], v167
	v_cvt_pk_f32_fp8_sdwa v[238:239], v167 src0_sel:WORD_1
	v_pk_fma_f32 v[228:229], v[72:73], v[236:237], v[228:229] op_sel_hi:[0,1,1]
	v_pk_fma_f32 v[230:231], v[72:73], v[238:239], v[230:231] op_sel_hi:[0,1,1]
	s_waitcnt vmcnt(10)
	v_cvt_pk_f32_fp8_e32 v[232:233], v168
	v_cvt_pk_f32_fp8_sdwa v[234:235], v168 src0_sel:WORD_1
	v_pk_fma_f32 v[216:217], v[72:73], v[232:233], v[216:217] op_sel:[1,0,0]
	v_pk_fma_f32 v[218:219], v[72:73], v[234:235], v[218:219] op_sel:[1,0,0]
	v_cvt_pk_f32_fp8_e32 v[236:237], v169
	v_cvt_pk_f32_fp8_sdwa v[238:239], v169 src0_sel:WORD_1
	v_pk_fma_f32 v[220:221], v[72:73], v[236:237], v[220:221] op_sel:[1,0,0]
	v_pk_fma_f32 v[222:223], v[72:73], v[238:239], v[222:223] op_sel:[1,0,0]
	v_cvt_pk_f32_fp8_e32 v[232:233], v170
	v_cvt_pk_f32_fp8_sdwa v[234:235], v170 src0_sel:WORD_1
	v_pk_fma_f32 v[224:225], v[72:73], v[232:233], v[224:225] op_sel:[1,0,0]
	v_pk_fma_f32 v[226:227], v[72:73], v[234:235], v[226:227] op_sel:[1,0,0]
	v_cvt_pk_f32_fp8_e32 v[236:237], v171
	v_cvt_pk_f32_fp8_sdwa v[238:239], v171 src0_sel:WORD_1
	v_pk_fma_f32 v[228:229], v[72:73], v[236:237], v[228:229] op_sel:[1,0,0]
	v_pk_fma_f32 v[230:231], v[72:73], v[238:239], v[230:231] op_sel:[1,0,0]
	s_waitcnt vmcnt(9)
	v_cvt_pk_f32_fp8_e32 v[232:233], v172
	v_cvt_pk_f32_fp8_sdwa v[234:235], v172 src0_sel:WORD_1
	v_pk_fma_f32 v[216:217], v[74:75], v[232:233], v[216:217] op_sel_hi:[0,1,1]
	v_pk_fma_f32 v[218:219], v[74:75], v[234:235], v[218:219] op_sel_hi:[0,1,1]
	v_cvt_pk_f32_fp8_e32 v[236:237], v173
	v_cvt_pk_f32_fp8_sdwa v[238:239], v173 src0_sel:WORD_1
	v_pk_fma_f32 v[220:221], v[74:75], v[236:237], v[220:221] op_sel_hi:[0,1,1]
	v_pk_fma_f32 v[222:223], v[74:75], v[238:239], v[222:223] op_sel_hi:[0,1,1]
	v_cvt_pk_f32_fp8_e32 v[232:233], v174
	v_cvt_pk_f32_fp8_sdwa v[234:235], v174 src0_sel:WORD_1
	v_pk_fma_f32 v[224:225], v[74:75], v[232:233], v[224:225] op_sel_hi:[0,1,1]
	v_pk_fma_f32 v[226:227], v[74:75], v[234:235], v[226:227] op_sel_hi:[0,1,1]
	v_cvt_pk_f32_fp8_e32 v[236:237], v175
	v_cvt_pk_f32_fp8_sdwa v[238:239], v175 src0_sel:WORD_1
	v_pk_fma_f32 v[228:229], v[74:75], v[236:237], v[228:229] op_sel_hi:[0,1,1]
	v_pk_fma_f32 v[230:231], v[74:75], v[238:239], v[230:231] op_sel_hi:[0,1,1]
	s_waitcnt vmcnt(8)
	v_cvt_pk_f32_fp8_e32 v[232:233], v176
	v_cvt_pk_f32_fp8_sdwa v[234:235], v176 src0_sel:WORD_1
	v_pk_fma_f32 v[216:217], v[74:75], v[232:233], v[216:217] op_sel:[1,0,0]
	v_pk_fma_f32 v[218:219], v[74:75], v[234:235], v[218:219] op_sel:[1,0,0]
	v_cvt_pk_f32_fp8_e32 v[236:237], v177
	v_cvt_pk_f32_fp8_sdwa v[238:239], v177 src0_sel:WORD_1
	v_pk_fma_f32 v[220:221], v[74:75], v[236:237], v[220:221] op_sel:[1,0,0]
	v_pk_fma_f32 v[222:223], v[74:75], v[238:239], v[222:223] op_sel:[1,0,0]
	v_cvt_pk_f32_fp8_e32 v[232:233], v178
	v_cvt_pk_f32_fp8_sdwa v[234:235], v178 src0_sel:WORD_1
	v_pk_fma_f32 v[224:225], v[74:75], v[232:233], v[224:225] op_sel:[1,0,0]
	v_pk_fma_f32 v[226:227], v[74:75], v[234:235], v[226:227] op_sel:[1,0,0]
	v_cvt_pk_f32_fp8_e32 v[236:237], v179
	v_cvt_pk_f32_fp8_sdwa v[238:239], v179 src0_sel:WORD_1
	v_pk_fma_f32 v[228:229], v[74:75], v[236:237], v[228:229] op_sel:[1,0,0]
	v_pk_fma_f32 v[230:231], v[74:75], v[238:239], v[230:231] op_sel:[1,0,0]
	s_waitcnt vmcnt(7)
	v_cvt_pk_f32_fp8_e32 v[232:233], v180
	v_cvt_pk_f32_fp8_sdwa v[234:235], v180 src0_sel:WORD_1
	v_pk_fma_f32 v[216:217], v[76:77], v[232:233], v[216:217] op_sel_hi:[0,1,1]
	v_pk_fma_f32 v[218:219], v[76:77], v[234:235], v[218:219] op_sel_hi:[0,1,1]
	v_cvt_pk_f32_fp8_e32 v[236:237], v181
	v_cvt_pk_f32_fp8_sdwa v[238:239], v181 src0_sel:WORD_1
	v_pk_fma_f32 v[220:221], v[76:77], v[236:237], v[220:221] op_sel_hi:[0,1,1]
	v_pk_fma_f32 v[222:223], v[76:77], v[238:239], v[222:223] op_sel_hi:[0,1,1]
	v_cvt_pk_f32_fp8_e32 v[232:233], v182
	v_cvt_pk_f32_fp8_sdwa v[234:235], v182 src0_sel:WORD_1
	v_pk_fma_f32 v[224:225], v[76:77], v[232:233], v[224:225] op_sel_hi:[0,1,1]
	v_pk_fma_f32 v[226:227], v[76:77], v[234:235], v[226:227] op_sel_hi:[0,1,1]
	v_cvt_pk_f32_fp8_e32 v[236:237], v183
	v_cvt_pk_f32_fp8_sdwa v[238:239], v183 src0_sel:WORD_1
	v_pk_fma_f32 v[228:229], v[76:77], v[236:237], v[228:229] op_sel_hi:[0,1,1]
	v_pk_fma_f32 v[230:231], v[76:77], v[238:239], v[230:231] op_sel_hi:[0,1,1]
	s_waitcnt vmcnt(6)
	v_cvt_pk_f32_fp8_e32 v[232:233], v184
	v_cvt_pk_f32_fp8_sdwa v[234:235], v184 src0_sel:WORD_1
	v_pk_fma_f32 v[216:217], v[76:77], v[232:233], v[216:217] op_sel:[1,0,0]
	v_pk_fma_f32 v[218:219], v[76:77], v[234:235], v[218:219] op_sel:[1,0,0]
	v_cvt_pk_f32_fp8_e32 v[236:237], v185
	v_cvt_pk_f32_fp8_sdwa v[238:239], v185 src0_sel:WORD_1
	v_pk_fma_f32 v[220:221], v[76:77], v[236:237], v[220:221] op_sel:[1,0,0]
	v_pk_fma_f32 v[222:223], v[76:77], v[238:239], v[222:223] op_sel:[1,0,0]
	v_cvt_pk_f32_fp8_e32 v[232:233], v186
	v_cvt_pk_f32_fp8_sdwa v[234:235], v186 src0_sel:WORD_1
	v_pk_fma_f32 v[224:225], v[76:77], v[232:233], v[224:225] op_sel:[1,0,0]
	v_pk_fma_f32 v[226:227], v[76:77], v[234:235], v[226:227] op_sel:[1,0,0]
	v_cvt_pk_f32_fp8_e32 v[236:237], v187
	v_cvt_pk_f32_fp8_sdwa v[238:239], v187 src0_sel:WORD_1
	v_pk_fma_f32 v[228:229], v[76:77], v[236:237], v[228:229] op_sel:[1,0,0]
	v_pk_fma_f32 v[230:231], v[76:77], v[238:239], v[230:231] op_sel:[1,0,0]
	s_waitcnt vmcnt(5)
; DI f2_t cvt8lo(unsigned w) { return __builtin_amdgcn_cvt_pk_f32_fp8(w, false); }
; DI f2_t cvt8hi(unsigned w) { return __builtin_amdgcn_cvt_pk_f32_fp8(w, true); }
; DI void phase11(const Params& p, char* smem, int rep) {
;     ...
;         for (int k = 0; k < 16; ++k) rows[k] = *(const u32x4*)(vb + (size_t)ida[k] * 2048);
; #pragma unroll
;         for (int k = 0; k < 16; ++k) {
;           const f2_t a2 = {aa[k], aa[k]};
; #pragma unroll
;           for (int d = 0; d < 4; ++d) { const unsigned ww = rows[k][d]; o[2 * d] += a2 * cvt8lo(ww); o[2 * d + 1] += a2 * cvt8hi(ww); }
	v_cvt_pk_f32_fp8_e32 v[232:233], v190
	v_cvt_pk_f32_fp8_sdwa v[234:235], v190 src0_sel:WORD_1
	v_pk_fma_f32 v[216:217], v[78:79], v[232:233], v[216:217] op_sel_hi:[0,1,1]
	v_pk_fma_f32 v[218:219], v[78:79], v[234:235], v[218:219] op_sel_hi:[0,1,1]
	v_cvt_pk_f32_fp8_e32 v[236:237], v191
	v_cvt_pk_f32_fp8_sdwa v[238:239], v191 src0_sel:WORD_1
	v_pk_fma_f32 v[220:221], v[78:79], v[236:237], v[220:221] op_sel_hi:[0,1,1]
	v_pk_fma_f32 v[222:223], v[78:79], v[238:239], v[222:223] op_sel_hi:[0,1,1]
	v_cvt_pk_f32_fp8_e32 v[232:233], v192
	v_cvt_pk_f32_fp8_sdwa v[234:235], v192 src0_sel:WORD_1
	v_pk_fma_f32 v[224:225], v[78:79], v[232:233], v[224:225] op_sel_hi:[0,1,1]
	v_pk_fma_f32 v[226:227], v[78:79], v[234:235], v[226:227] op_sel_hi:[0,1,1]
	v_cvt_pk_f32_fp8_e32 v[236:237], v193
	v_cvt_pk_f32_fp8_sdwa v[238:239], v193 src0_sel:WORD_1
	v_pk_fma_f32 v[228:229], v[78:79], v[236:237], v[228:229] op_sel_hi:[0,1,1]
	v_pk_fma_f32 v[230:231], v[78:79], v[238:239], v[230:231] op_sel_hi:[0,1,1]
	s_waitcnt vmcnt(4)
	v_cvt_pk_f32_fp8_e32 v[232:233], v194
	v_cvt_pk_f32_fp8_sdwa v[234:235], v194 src0_sel:WORD_1
	v_pk_fma_f32 v[216:217], v[78:79], v[232:233], v[216:217] op_sel:[1,0,0]
	v_pk_fma_f32 v[218:219], v[78:79], v[234:235], v[218:219] op_sel:[1,0,0]
	v_cvt_pk_f32_fp8_e32 v[236:237], v195
	v_cvt_pk_f32_fp8_sdwa v[238:239], v195 src0_sel:WORD_1
	v_pk_fma_f32 v[220:221], v[78:79], v[236:237], v[220:221] op_sel:[1,0,0]
	v_pk_fma_f32 v[222:223], v[78:79], v[238:239], v[222:223] op_sel:[1,0,0]
	v_cvt_pk_f32_fp8_e32 v[232:233], v196
	v_cvt_pk_f32_fp8_sdwa v[234:235], v196 src0_sel:WORD_1
	v_pk_fma_f32 v[224:225], v[78:79], v[232:233], v[224:225] op_sel:[1,0,0]
	v_pk_fma_f32 v[226:227], v[78:79], v[234:235], v[226:227] op_sel:[1,0,0]
	v_cvt_pk_f32_fp8_e32 v[236:237], v197
	v_cvt_pk_f32_fp8_sdwa v[238:239], v197 src0_sel:WORD_1
	v_pk_fma_f32 v[228:229], v[78:79], v[236:237], v[228:229] op_sel:[1,0,0]
	v_pk_fma_f32 v[230:231], v[78:79], v[238:239], v[230:231] op_sel:[1,0,0]
	s_waitcnt vmcnt(3)
	v_cvt_pk_f32_fp8_e32 v[232:233], v198
	v_cvt_pk_f32_fp8_sdwa v[234:235], v198 src0_sel:WORD_1
	v_pk_fma_f32 v[216:217], v[80:81], v[232:233], v[216:217] op_sel_hi:[0,1,1]
	v_pk_fma_f32 v[218:219], v[80:81], v[234:235], v[218:219] op_sel_hi:[0,1,1]
	v_cvt_pk_f32_fp8_e32 v[236:237], v199
	v_cvt_pk_f32_fp8_sdwa v[238:239], v199 src0_sel:WORD_1
	v_pk_fma_f32 v[220:221], v[80:81], v[236:237], v[220:221] op_sel_hi:[0,1,1]
	v_pk_fma_f32 v[222:223], v[80:81], v[238:239], v[222:223] op_sel_hi:[0,1,1]
	v_cvt_pk_f32_fp8_e32 v[232:233], v200
	v_cvt_pk_f32_fp8_sdwa v[234:235], v200 src0_sel:WORD_1
	v_pk_fma_f32 v[224:225], v[80:81], v[232:233], v[224:225] op_sel_hi:[0,1,1]
	v_pk_fma_f32 v[226:227], v[80:81], v[234:235], v[226:227] op_sel_hi:[0,1,1]
	v_cvt_pk_f32_fp8_e32 v[236:237], v201
	v_cvt_pk_f32_fp8_sdwa v[238:239], v201 src0_sel:WORD_1
	v_pk_fma_f32 v[228:229], v[80:81], v[236:237], v[228:229] op_sel_hi:[0,1,1]
	v_pk_fma_f32 v[230:231], v[80:81], v[238:239], v[230:231] op_sel_hi:[0,1,1]
	s_waitcnt vmcnt(2)
	v_cvt_pk_f32_fp8_e32 v[232:233], v202
	v_cvt_pk_f32_fp8_sdwa v[234:235], v202 src0_sel:WORD_1
	v_pk_fma_f32 v[216:217], v[80:81], v[232:233], v[216:217] op_sel:[1,0,0]
	v_pk_fma_f32 v[218:219], v[80:81], v[234:235], v[218:219] op_sel:[1,0,0]
	v_cvt_pk_f32_fp8_e32 v[236:237], v203
	v_cvt_pk_f32_fp8_sdwa v[238:239], v203 src0_sel:WORD_1
	v_pk_fma_f32 v[220:221], v[80:81], v[236:237], v[220:221] op_sel:[1,0,0]
	v_pk_fma_f32 v[222:223], v[80:81], v[238:239], v[222:223] op_sel:[1,0,0]
	v_cvt_pk_f32_fp8_e32 v[232:233], v204
	v_cvt_pk_f32_fp8_sdwa v[234:235], v204 src0_sel:WORD_1
	v_pk_fma_f32 v[224:225], v[80:81], v[232:233], v[224:225] op_sel:[1,0,0]
	v_pk_fma_f32 v[226:227], v[80:81], v[234:235], v[226:227] op_sel:[1,0,0]
	v_cvt_pk_f32_fp8_e32 v[236:237], v205
	v_cvt_pk_f32_fp8_sdwa v[238:239], v205 src0_sel:WORD_1
	v_pk_fma_f32 v[228:229], v[80:81], v[236:237], v[228:229] op_sel:[1,0,0]
	v_pk_fma_f32 v[230:231], v[80:81], v[238:239], v[230:231] op_sel:[1,0,0]
	s_waitcnt vmcnt(1)
	v_cvt_pk_f32_fp8_e32 v[232:233], v206
	v_cvt_pk_f32_fp8_sdwa v[234:235], v206 src0_sel:WORD_1
	v_pk_fma_f32 v[216:217], v[82:83], v[232:233], v[216:217] op_sel_hi:[0,1,1]
	v_pk_fma_f32 v[218:219], v[82:83], v[234:235], v[218:219] op_sel_hi:[0,1,1]
	v_cvt_pk_f32_fp8_e32 v[236:237], v207
	v_cvt_pk_f32_fp8_sdwa v[238:239], v207 src0_sel:WORD_1
	v_pk_fma_f32 v[220:221], v[82:83], v[236:237], v[220:221] op_sel_hi:[0,1,1]
	v_pk_fma_f32 v[222:223], v[82:83], v[238:239], v[222:223] op_sel_hi:[0,1,1]
	v_cvt_pk_f32_fp8_e32 v[232:233], v208
	v_cvt_pk_f32_fp8_sdwa v[234:235], v208 src0_sel:WORD_1
	v_pk_fma_f32 v[224:225], v[82:83], v[232:233], v[224:225] op_sel_hi:[0,1,1]
	v_pk_fma_f32 v[226:227], v[82:83], v[234:235], v[226:227] op_sel_hi:[0,1,1]
	v_cvt_pk_f32_fp8_e32 v[236:237], v209
	v_cvt_pk_f32_fp8_sdwa v[238:239], v209 src0_sel:WORD_1
	v_pk_fma_f32 v[228:229], v[82:83], v[236:237], v[228:229] op_sel_hi:[0,1,1]
	v_pk_fma_f32 v[230:231], v[82:83], v[238:239], v[230:231] op_sel_hi:[0,1,1]
	s_waitcnt vmcnt(0)
; DI unsigned pk2(float a, float b) { f2_t v = {a, b}; bf2_t r = __builtin_convertvector(v, bf2_t); return __builtin_bit_cast(unsigned, r); }
; DI f2_t cvt8lo(unsigned w) { return __builtin_amdgcn_cvt_pk_f32_fp8(w, false); }
; DI f2_t cvt8hi(unsigned w) { return __builtin_amdgcn_cvt_pk_f32_fp8(w, true); }
; DI void wave_lds_sync() { asm volatile("s_waitcnt lgkmcnt(0)" ::: "memory"); __builtin_amdgcn_wave_barrier(); }
; DI void phase11(const Params& p, char* smem, int rep) {
;     ...
;     for (int t = 0; t < 4; ++t) {
;       const int tok = __builtin_amdgcn_readfirstlane(c * 16 + w * 4 + t);
;       const int i0 = IDS[(size_t)tok * 128 + lane], i1 = IDS[(size_t)tok * 128 + 64 + lane];
;       const float a0 = ACT[(size_t)tok * 128 + lane], a1 = ACT[(size_t)tok * 128 + 64 + lane];
;       wave_lds_sync();
;       lw[(lane & 3) * 32 + (lane >> 2)] = i0; lw[(lane & 3) * 32 + 16 + (lane >> 2)] = i1;
;       lf[(lane & 3) * 32 + (lane >> 2)] = a0; lf[(lane & 3) * 32 + 16 + (lane >> 2)] = a1;
;       wave_lds_sync();
;     ...
;         for (int k = 0; k < 16; ++k) rows[k] = *(const u32x4*)(vb + (size_t)ida[k] * 2048);
; #pragma unroll
;         for (int k = 0; k < 16; ++k) {
;           const f2_t a2 = {aa[k], aa[k]};
; #pragma unroll
;           for (int d = 0; d < 4; ++d) { const unsigned ww = rows[k][d]; o[2 * d] += a2 * cvt8lo(ww); o[2 * d + 1] += a2 * cvt8hi(ww); }
;         }
;       }
;       float ov[16];
; #pragma unroll
;       for (int d = 0; d < 4; ++d) { ov[4 * d] = o[2 * d].x; ov[4 * d + 1] = o[2 * d].y; ov[4 * d + 2] = o[2 * d + 1].x; ov[4 * d + 3] = o[2 * d + 1].y; }
;       float q8[8], q4[4];
; #pragma unroll
;       for (int k = 0; k < 8; ++k) q8[k] = (b5 ? ov[8 + k] : ov[k]) + __shfl_xor(b5 ? ov[k] : ov[8 + k], 32);
; #pragma unroll
;       for (int k = 0; k < 4; ++k) q4[k] = (b4 ? q8[4 + k] : q8[k]) + __shfl_xor(b4 ? q8[k] : q8[4 + k], 16);
;       *(uint2*)(OUTP + (size_t)tok * D_ + s * 256 + l15 * 16 + 8 * b5 + 4 * b4) = make_uint2(pk2(q4[0], q4[1]), pk2(q4[2], q4[3]));
	v_cvt_pk_f32_fp8_e32 v[232:233], v210
	v_cvt_pk_f32_fp8_sdwa v[234:235], v210 src0_sel:WORD_1
	v_pk_fma_f32 v[216:217], v[82:83], v[232:233], v[216:217] op_sel:[1,0,0]
	v_pk_fma_f32 v[218:219], v[82:83], v[234:235], v[218:219] op_sel:[1,0,0]
	v_cvt_pk_f32_fp8_e32 v[236:237], v211
	v_cvt_pk_f32_fp8_sdwa v[238:239], v211 src0_sel:WORD_1
	v_pk_fma_f32 v[220:221], v[82:83], v[236:237], v[220:221] op_sel:[1,0,0]
	v_pk_fma_f32 v[222:223], v[82:83], v[238:239], v[222:223] op_sel:[1,0,0]
	v_cvt_pk_f32_fp8_e32 v[232:233], v212
	v_cvt_pk_f32_fp8_sdwa v[234:235], v212 src0_sel:WORD_1
	v_pk_fma_f32 v[224:225], v[82:83], v[232:233], v[224:225] op_sel:[1,0,0]
	v_pk_fma_f32 v[226:227], v[82:83], v[234:235], v[226:227] op_sel:[1,0,0]
	v_cvt_pk_f32_fp8_e32 v[236:237], v213
	v_cvt_pk_f32_fp8_sdwa v[238:239], v213 src0_sel:WORD_1
	v_pk_fma_f32 v[228:229], v[82:83], v[236:237], v[228:229] op_sel:[1,0,0]
	v_pk_fma_f32 v[230:231], v[82:83], v[238:239], v[230:231] op_sel:[1,0,0]
	ds_read_b128 v[52:55], v6 offset:528
	ds_read_b128 v[56:59], v6 offset:544
	ds_read_b128 v[60:63], v6 offset:560
	ds_read_b128 v[64:67], v6 offset:576
	ds_read_b128 v[68:71], v6 offset:592
	ds_read_b128 v[72:75], v6 offset:608
	ds_read_b128 v[76:79], v6 offset:624
	ds_read_b128 v[80:83], v6 offset:640
	v_add_u32_e32 v214, s46, v4
	s_nop 0
	v_permlane32_swap_b32_e32 v216, v224
	v_permlane32_swap_b32_e32 v217, v225
	v_permlane32_swap_b32_e32 v218, v226
	v_permlane32_swap_b32_e32 v219, v227
	v_permlane32_swap_b32_e32 v220, v228
	v_permlane32_swap_b32_e32 v221, v229
	v_permlane32_swap_b32_e32 v222, v230
	v_permlane32_swap_b32_e32 v223, v231
	v_pk_add_f32 v[216:217], v[216:217], v[224:225]
	v_pk_add_f32 v[218:219], v[218:219], v[226:227]
	v_pk_add_f32 v[220:221], v[220:221], v[228:229]
	v_pk_add_f32 v[222:223], v[222:223], v[230:231]
	s_nop 1
	v_permlane16_swap_b32_e32 v216, v220
	v_permlane16_swap_b32_e32 v217, v221
	v_permlane16_swap_b32_e32 v218, v222
	v_permlane16_swap_b32_e32 v219, v223
	v_pk_add_f32 v[216:217], v[216:217], v[220:221]
	v_pk_add_f32 v[218:219], v[218:219], v[222:223]
	v_cvt_pk_bf16_f32 v232, v216, v217
	v_cvt_pk_bf16_f32 v233, v218, v219
	global_store_dwordx2 v214, v[232:233], s[14:15]
	s_add_i32 s54, s34, 3
	s_lshl_b32 s46, s54, 12
	s_add_i32 s46, s46, s24
	s_add_i32 s55, s34, 4
	s_add_i32 s51, s48, 1
	s_cmp_lt_u32 s51, s49
	s_cselect_b32 s55, s55, 8192
	s_cmp_lt_u32 s55, 8192
	s_cselect_b32 s55, s55, 0
	s_lshl_b32 s47, s55, 9
	s_add_u32 s42, s6, s47
	s_addc_u32 s43, s7, 0
	s_add_u32 s44, s8, s47
	s_addc_u32 s45, s9, 0
	global_load_dword v10, v3, s[42:43]
	global_load_dword v11, v3, s[42:43] offset:256
	global_load_dword v12, v3, s[44:45]
	global_load_dword v13, v3, s[44:45] offset:256
	s_waitcnt lgkmcnt(0)
	v_lshl_add_u32 v20, v20, 11, v2
	v_lshl_add_u32 v21, v21, 11, v2
	v_lshl_add_u32 v22, v22, 11, v2
	v_lshl_add_u32 v23, v23, 11, v2
	v_lshl_add_u32 v24, v24, 11, v2
	v_lshl_add_u32 v25, v25, 11, v2
	v_lshl_add_u32 v26, v26, 11, v2
	v_lshl_add_u32 v27, v27, 11, v2
	v_lshl_add_u32 v28, v28, 11, v2
	v_lshl_add_u32 v29, v29, 11, v2
	v_lshl_add_u32 v30, v30, 11, v2
	v_lshl_add_u32 v31, v31, 11, v2
	v_lshl_add_u32 v32, v32, 11, v2
	v_lshl_add_u32 v33, v33, 11, v2
	v_lshl_add_u32 v34, v34, 11, v2
	v_lshl_add_u32 v35, v35, 11, v2
	v_lshl_add_u32 v36, v36, 11, v2
	v_lshl_add_u32 v37, v37, 11, v2
	v_lshl_add_u32 v38, v38, 11, v2
	v_lshl_add_u32 v39, v39, 11, v2
	v_lshl_add_u32 v40, v40, 11, v2
	v_lshl_add_u32 v41, v41, 11, v2
	v_lshl_add_u32 v42, v42, 11, v2
	v_lshl_add_u32 v43, v43, 11, v2
	v_lshl_add_u32 v44, v44, 11, v2
	v_lshl_add_u32 v45, v45, 11, v2
	v_lshl_add_u32 v46, v46, 11, v2
	v_lshl_add_u32 v47, v47, 11, v2
	v_lshl_add_u32 v48, v48, 11, v2
	v_lshl_add_u32 v49, v49, 11, v2
	v_lshl_add_u32 v50, v50, 11, v2
	v_lshl_add_u32 v51, v51, 11, v2
	global_load_dwordx4 v[84:87], v20, s[20:21]
	global_load_dwordx4 v[88:91], v21, s[20:21]
	global_load_dwordx4 v[92:95], v22, s[20:21]
	global_load_dwordx4 v[96:99], v23, s[20:21]
	global_load_dwordx4 v[100:103], v24, s[20:21]
	global_load_dwordx4 v[104:107], v25, s[20:21]
	global_load_dwordx4 v[108:111], v26, s[20:21]
	global_load_dwordx4 v[112:115], v27, s[20:21]
	global_load_dwordx4 v[116:119], v28, s[20:21]
	global_load_dwordx4 v[120:123], v29, s[20:21]
	global_load_dwordx4 v[124:127], v30, s[20:21]
	global_load_dwordx4 v[128:131], v31, s[20:21]
	global_load_dwordx4 v[132:135], v32, s[20:21]
	global_load_dwordx4 v[136:139], v33, s[20:21]
	global_load_dwordx4 v[140:143], v34, s[20:21]
	global_load_dwordx4 v[144:147], v35, s[20:21]
	global_load_dwordx4 v[148:151], v36, s[20:21]
	global_load_dwordx4 v[152:155], v37, s[20:21]
	global_load_dwordx4 v[156:159], v38, s[20:21]
	global_load_dwordx4 v[160:163], v39, s[20:21]
	global_load_dwordx4 v[164:167], v40, s[20:21]
	global_load_dwordx4 v[168:171], v41, s[20:21]
	global_load_dwordx4 v[172:175], v42, s[20:21]
	global_load_dwordx4 v[176:179], v43, s[20:21]
	global_load_dwordx4 v[180:183], v44, s[20:21]
	global_load_dwordx4 v[184:187], v45, s[20:21]
	global_load_dwordx4 v[190:193], v46, s[20:21]
	global_load_dwordx4 v[194:197], v47, s[20:21]
	global_load_dwordx4 v[198:201], v48, s[20:21]
	global_load_dwordx4 v[202:205], v49, s[20:21]
	global_load_dwordx4 v[206:209], v50, s[20:21]
	global_load_dwordx4 v[210:213], v51, s[20:21]
	s_waitcnt vmcnt(31)
; DI f2_t cvt8lo(unsigned w) { return __builtin_amdgcn_cvt_pk_f32_fp8(w, false); }
; DI f2_t cvt8hi(unsigned w) { return __builtin_amdgcn_cvt_pk_f32_fp8(w, true); }
; DI void phase11(const Params& p, char* smem, int rep) {
;     ...
;         for (int k = 0; k < 16; ++k) rows[k] = *(const u32x4*)(vb + (size_t)ida[k] * 2048);
; #pragma unroll
;         for (int k = 0; k < 16; ++k) {
;           const f2_t a2 = {aa[k], aa[k]};
; #pragma unroll
;           for (int d = 0; d < 4; ++d) { const unsigned ww = rows[k][d]; o[2 * d] += a2 * cvt8lo(ww); o[2 * d + 1] += a2 * cvt8hi(ww); }
	v_cvt_pk_f32_fp8_e32 v[232:233], v84
	v_cvt_pk_f32_fp8_sdwa v[234:235], v84 src0_sel:WORD_1
	v_pk_fma_f32 v[216:217], v[52:53], v[232:233], 0 op_sel_hi:[0,1,0]
	v_pk_fma_f32 v[218:219], v[52:53], v[234:235], 0 op_sel_hi:[0,1,0]
	v_cvt_pk_f32_fp8_e32 v[236:237], v85
	v_cvt_pk_f32_fp8_sdwa v[238:239], v85 src0_sel:WORD_1
	v_pk_fma_f32 v[220:221], v[52:53], v[236:237], 0 op_sel_hi:[0,1,0]
	v_pk_fma_f32 v[222:223], v[52:53], v[238:239], 0 op_sel_hi:[0,1,0]
	v_cvt_pk_f32_fp8_e32 v[232:233], v86
	v_cvt_pk_f32_fp8_sdwa v[234:235], v86 src0_sel:WORD_1
	v_pk_fma_f32 v[224:225], v[52:53], v[232:233], 0 op_sel_hi:[0,1,0]
	v_pk_fma_f32 v[226:227], v[52:53], v[234:235], 0 op_sel_hi:[0,1,0]
	v_cvt_pk_f32_fp8_e32 v[236:237], v87
	v_cvt_pk_f32_fp8_sdwa v[238:239], v87 src0_sel:WORD_1
	v_pk_fma_f32 v[228:229], v[52:53], v[236:237], 0 op_sel_hi:[0,1,0]
	v_pk_fma_f32 v[230:231], v[52:53], v[238:239], 0 op_sel_hi:[0,1,0]
	s_waitcnt vmcnt(30)
	v_cvt_pk_f32_fp8_e32 v[232:233], v88
	v_cvt_pk_f32_fp8_sdwa v[234:235], v88 src0_sel:WORD_1
	v_pk_fma_f32 v[216:217], v[52:53], v[232:233], v[216:217] op_sel:[1,0,0]
	v_pk_fma_f32 v[218:219], v[52:53], v[234:235], v[218:219] op_sel:[1,0,0]
	v_cvt_pk_f32_fp8_e32 v[236:237], v89
	v_cvt_pk_f32_fp8_sdwa v[238:239], v89 src0_sel:WORD_1
	v_pk_fma_f32 v[220:221], v[52:53], v[236:237], v[220:221] op_sel:[1,0,0]
	v_pk_fma_f32 v[222:223], v[52:53], v[238:239], v[222:223] op_sel:[1,0,0]
	v_cvt_pk_f32_fp8_e32 v[232:233], v90
	v_cvt_pk_f32_fp8_sdwa v[234:235], v90 src0_sel:WORD_1
	v_pk_fma_f32 v[224:225], v[52:53], v[232:233], v[224:225] op_sel:[1,0,0]
	v_pk_fma_f32 v[226:227], v[52:53], v[234:235], v[226:227] op_sel:[1,0,0]
	v_cvt_pk_f32_fp8_e32 v[236:237], v91
	v_cvt_pk_f32_fp8_sdwa v[238:239], v91 src0_sel:WORD_1
	v_pk_fma_f32 v[228:229], v[52:53], v[236:237], v[228:229] op_sel:[1,0,0]
	v_pk_fma_f32 v[230:231], v[52:53], v[238:239], v[230:231] op_sel:[1,0,0]
	s_waitcnt vmcnt(29)
	v_cvt_pk_f32_fp8_e32 v[232:233], v92
	v_cvt_pk_f32_fp8_sdwa v[234:235], v92 src0_sel:WORD_1
	v_pk_fma_f32 v[216:217], v[54:55], v[232:233], v[216:217] op_sel_hi:[0,1,1]
	v_pk_fma_f32 v[218:219], v[54:55], v[234:235], v[218:219] op_sel_hi:[0,1,1]
	v_cvt_pk_f32_fp8_e32 v[236:237], v93
	v_cvt_pk_f32_fp8_sdwa v[238:239], v93 src0_sel:WORD_1
	v_pk_fma_f32 v[220:221], v[54:55], v[236:237], v[220:221] op_sel_hi:[0,1,1]
	v_pk_fma_f32 v[222:223], v[54:55], v[238:239], v[222:223] op_sel_hi:[0,1,1]
	v_cvt_pk_f32_fp8_e32 v[232:233], v94
	v_cvt_pk_f32_fp8_sdwa v[234:235], v94 src0_sel:WORD_1
	v_pk_fma_f32 v[224:225], v[54:55], v[232:233], v[224:225] op_sel_hi:[0,1,1]
	v_pk_fma_f32 v[226:227], v[54:55], v[234:235], v[226:227] op_sel_hi:[0,1,1]
	v_cvt_pk_f32_fp8_e32 v[236:237], v95
	v_cvt_pk_f32_fp8_sdwa v[238:239], v95 src0_sel:WORD_1
	v_pk_fma_f32 v[228:229], v[54:55], v[236:237], v[228:229] op_sel_hi:[0,1,1]
	v_pk_fma_f32 v[230:231], v[54:55], v[238:239], v[230:231] op_sel_hi:[0,1,1]
	s_waitcnt vmcnt(28)
	v_cvt_pk_f32_fp8_e32 v[232:233], v96
	v_cvt_pk_f32_fp8_sdwa v[234:235], v96 src0_sel:WORD_1
	v_pk_fma_f32 v[216:217], v[54:55], v[232:233], v[216:217] op_sel:[1,0,0]
	v_pk_fma_f32 v[218:219], v[54:55], v[234:235], v[218:219] op_sel:[1,0,0]
	v_cvt_pk_f32_fp8_e32 v[236:237], v97
	v_cvt_pk_f32_fp8_sdwa v[238:239], v97 src0_sel:WORD_1
	v_pk_fma_f32 v[220:221], v[54:55], v[236:237], v[220:221] op_sel:[1,0,0]
	v_pk_fma_f32 v[222:223], v[54:55], v[238:239], v[222:223] op_sel:[1,0,0]
	v_cvt_pk_f32_fp8_e32 v[232:233], v98
	v_cvt_pk_f32_fp8_sdwa v[234:235], v98 src0_sel:WORD_1
	v_pk_fma_f32 v[224:225], v[54:55], v[232:233], v[224:225] op_sel:[1,0,0]
	v_pk_fma_f32 v[226:227], v[54:55], v[234:235], v[226:227] op_sel:[1,0,0]
	v_cvt_pk_f32_fp8_e32 v[236:237], v99
	v_cvt_pk_f32_fp8_sdwa v[238:239], v99 src0_sel:WORD_1
	v_pk_fma_f32 v[228:229], v[54:55], v[236:237], v[228:229] op_sel:[1,0,0]
	v_pk_fma_f32 v[230:231], v[54:55], v[238:239], v[230:231] op_sel:[1,0,0]
	s_waitcnt vmcnt(27)
	v_cvt_pk_f32_fp8_e32 v[232:233], v100
	v_cvt_pk_f32_fp8_sdwa v[234:235], v100 src0_sel:WORD_1
	v_pk_fma_f32 v[216:217], v[56:57], v[232:233], v[216:217] op_sel_hi:[0,1,1]
	v_pk_fma_f32 v[218:219], v[56:57], v[234:235], v[218:219] op_sel_hi:[0,1,1]
	v_cvt_pk_f32_fp8_e32 v[236:237], v101
	v_cvt_pk_f32_fp8_sdwa v[238:239], v101 src0_sel:WORD_1
	v_pk_fma_f32 v[220:221], v[56:57], v[236:237], v[220:221] op_sel_hi:[0,1,1]
	v_pk_fma_f32 v[222:223], v[56:57], v[238:239], v[222:223] op_sel_hi:[0,1,1]
	v_cvt_pk_f32_fp8_e32 v[232:233], v102
	v_cvt_pk_f32_fp8_sdwa v[234:235], v102 src0_sel:WORD_1
	v_pk_fma_f32 v[224:225], v[56:57], v[232:233], v[224:225] op_sel_hi:[0,1,1]
	v_pk_fma_f32 v[226:227], v[56:57], v[234:235], v[226:227] op_sel_hi:[0,1,1]
	v_cvt_pk_f32_fp8_e32 v[236:237], v103
	v_cvt_pk_f32_fp8_sdwa v[238:239], v103 src0_sel:WORD_1
	v_pk_fma_f32 v[228:229], v[56:57], v[236:237], v[228:229] op_sel_hi:[0,1,1]
	v_pk_fma_f32 v[230:231], v[56:57], v[238:239], v[230:231] op_sel_hi:[0,1,1]
	s_waitcnt vmcnt(26)
	v_cvt_pk_f32_fp8_e32 v[232:233], v104
	v_cvt_pk_f32_fp8_sdwa v[234:235], v104 src0_sel:WORD_1
	v_pk_fma_f32 v[216:217], v[56:57], v[232:233], v[216:217] op_sel:[1,0,0]
	v_pk_fma_f32 v[218:219], v[56:57], v[234:235], v[218:219] op_sel:[1,0,0]
	v_cvt_pk_f32_fp8_e32 v[236:237], v105
	v_cvt_pk_f32_fp8_sdwa v[238:239], v105 src0_sel:WORD_1
	v_pk_fma_f32 v[220:221], v[56:57], v[236:237], v[220:221] op_sel:[1,0,0]
	v_pk_fma_f32 v[222:223], v[56:57], v[238:239], v[222:223] op_sel:[1,0,0]
	v_cvt_pk_f32_fp8_e32 v[232:233], v106
	v_cvt_pk_f32_fp8_sdwa v[234:235], v106 src0_sel:WORD_1
	v_pk_fma_f32 v[224:225], v[56:57], v[232:233], v[224:225] op_sel:[1,0,0]
	v_pk_fma_f32 v[226:227], v[56:57], v[234:235], v[226:227] op_sel:[1,0,0]
	v_cvt_pk_f32_fp8_e32 v[236:237], v107
	v_cvt_pk_f32_fp8_sdwa v[238:239], v107 src0_sel:WORD_1
	v_pk_fma_f32 v[228:229], v[56:57], v[236:237], v[228:229] op_sel:[1,0,0]
	v_pk_fma_f32 v[230:231], v[56:57], v[238:239], v[230:231] op_sel:[1,0,0]
	s_waitcnt vmcnt(25)
; DI f2_t cvt8lo(unsigned w) { return __builtin_amdgcn_cvt_pk_f32_fp8(w, false); }
; DI f2_t cvt8hi(unsigned w) { return __builtin_amdgcn_cvt_pk_f32_fp8(w, true); }
; DI void phase11(const Params& p, char* smem, int rep) {
;     ...
;         for (int k = 0; k < 16; ++k) rows[k] = *(const u32x4*)(vb + (size_t)ida[k] * 2048);
; #pragma unroll
;         for (int k = 0; k < 16; ++k) {
;           const f2_t a2 = {aa[k], aa[k]};
; #pragma unroll
;           for (int d = 0; d < 4; ++d) { const unsigned ww = rows[k][d]; o[2 * d] += a2 * cvt8lo(ww); o[2 * d + 1] += a2 * cvt8hi(ww); }
	v_cvt_pk_f32_fp8_e32 v[232:233], v108
	v_cvt_pk_f32_fp8_sdwa v[234:235], v108 src0_sel:WORD_1
	v_pk_fma_f32 v[216:217], v[58:59], v[232:233], v[216:217] op_sel_hi:[0,1,1]
	v_pk_fma_f32 v[218:219], v[58:59], v[234:235], v[218:219] op_sel_hi:[0,1,1]
	v_cvt_pk_f32_fp8_e32 v[236:237], v109
	v_cvt_pk_f32_fp8_sdwa v[238:239], v109 src0_sel:WORD_1
	v_pk_fma_f32 v[220:221], v[58:59], v[236:237], v[220:221] op_sel_hi:[0,1,1]
	v_pk_fma_f32 v[222:223], v[58:59], v[238:239], v[222:223] op_sel_hi:[0,1,1]
	v_cvt_pk_f32_fp8_e32 v[232:233], v110
	v_cvt_pk_f32_fp8_sdwa v[234:235], v110 src0_sel:WORD_1
	v_pk_fma_f32 v[224:225], v[58:59], v[232:233], v[224:225] op_sel_hi:[0,1,1]
	v_pk_fma_f32 v[226:227], v[58:59], v[234:235], v[226:227] op_sel_hi:[0,1,1]
	v_cvt_pk_f32_fp8_e32 v[236:237], v111
	v_cvt_pk_f32_fp8_sdwa v[238:239], v111 src0_sel:WORD_1
	v_pk_fma_f32 v[228:229], v[58:59], v[236:237], v[228:229] op_sel_hi:[0,1,1]
	v_pk_fma_f32 v[230:231], v[58:59], v[238:239], v[230:231] op_sel_hi:[0,1,1]
	s_waitcnt vmcnt(24)
	v_cvt_pk_f32_fp8_e32 v[232:233], v112
	v_cvt_pk_f32_fp8_sdwa v[234:235], v112 src0_sel:WORD_1
	v_pk_fma_f32 v[216:217], v[58:59], v[232:233], v[216:217] op_sel:[1,0,0]
	v_pk_fma_f32 v[218:219], v[58:59], v[234:235], v[218:219] op_sel:[1,0,0]
	v_cvt_pk_f32_fp8_e32 v[236:237], v113
	v_cvt_pk_f32_fp8_sdwa v[238:239], v113 src0_sel:WORD_1
	v_pk_fma_f32 v[220:221], v[58:59], v[236:237], v[220:221] op_sel:[1,0,0]
	v_pk_fma_f32 v[222:223], v[58:59], v[238:239], v[222:223] op_sel:[1,0,0]
	v_cvt_pk_f32_fp8_e32 v[232:233], v114
	v_cvt_pk_f32_fp8_sdwa v[234:235], v114 src0_sel:WORD_1
	v_pk_fma_f32 v[224:225], v[58:59], v[232:233], v[224:225] op_sel:[1,0,0]
	v_pk_fma_f32 v[226:227], v[58:59], v[234:235], v[226:227] op_sel:[1,0,0]
	v_cvt_pk_f32_fp8_e32 v[236:237], v115
	v_cvt_pk_f32_fp8_sdwa v[238:239], v115 src0_sel:WORD_1
	v_pk_fma_f32 v[228:229], v[58:59], v[236:237], v[228:229] op_sel:[1,0,0]
	v_pk_fma_f32 v[230:231], v[58:59], v[238:239], v[230:231] op_sel:[1,0,0]
	s_waitcnt vmcnt(23)
	v_cvt_pk_f32_fp8_e32 v[232:233], v116
	v_cvt_pk_f32_fp8_sdwa v[234:235], v116 src0_sel:WORD_1
	v_pk_fma_f32 v[216:217], v[60:61], v[232:233], v[216:217] op_sel_hi:[0,1,1]
	v_pk_fma_f32 v[218:219], v[60:61], v[234:235], v[218:219] op_sel_hi:[0,1,1]
	v_cvt_pk_f32_fp8_e32 v[236:237], v117
	v_cvt_pk_f32_fp8_sdwa v[238:239], v117 src0_sel:WORD_1
	v_pk_fma_f32 v[220:221], v[60:61], v[236:237], v[220:221] op_sel_hi:[0,1,1]
	v_pk_fma_f32 v[222:223], v[60:61], v[238:239], v[222:223] op_sel_hi:[0,1,1]
	v_cvt_pk_f32_fp8_e32 v[232:233], v118
	v_cvt_pk_f32_fp8_sdwa v[234:235], v118 src0_sel:WORD_1
	v_pk_fma_f32 v[224:225], v[60:61], v[232:233], v[224:225] op_sel_hi:[0,1,1]
	v_pk_fma_f32 v[226:227], v[60:61], v[234:235], v[226:227] op_sel_hi:[0,1,1]
	v_cvt_pk_f32_fp8_e32 v[236:237], v119
	v_cvt_pk_f32_fp8_sdwa v[238:239], v119 src0_sel:WORD_1
	v_pk_fma_f32 v[228:229], v[60:61], v[236:237], v[228:229] op_sel_hi:[0,1,1]
	v_pk_fma_f32 v[230:231], v[60:61], v[238:239], v[230:231] op_sel_hi:[0,1,1]
	s_waitcnt vmcnt(22)
	v_cvt_pk_f32_fp8_e32 v[232:233], v120
	v_cvt_pk_f32_fp8_sdwa v[234:235], v120 src0_sel:WORD_1
	v_pk_fma_f32 v[216:217], v[60:61], v[232:233], v[216:217] op_sel:[1,0,0]
	v_pk_fma_f32 v[218:219], v[60:61], v[234:235], v[218:219] op_sel:[1,0,0]
	v_cvt_pk_f32_fp8_e32 v[236:237], v121
	v_cvt_pk_f32_fp8_sdwa v[238:239], v121 src0_sel:WORD_1
	v_pk_fma_f32 v[220:221], v[60:61], v[236:237], v[220:221] op_sel:[1,0,0]
	v_pk_fma_f32 v[222:223], v[60:61], v[238:239], v[222:223] op_sel:[1,0,0]
	v_cvt_pk_f32_fp8_e32 v[232:233], v122
	v_cvt_pk_f32_fp8_sdwa v[234:235], v122 src0_sel:WORD_1
	v_pk_fma_f32 v[224:225], v[60:61], v[232:233], v[224:225] op_sel:[1,0,0]
	v_pk_fma_f32 v[226:227], v[60:61], v[234:235], v[226:227] op_sel:[1,0,0]
	v_cvt_pk_f32_fp8_e32 v[236:237], v123
	v_cvt_pk_f32_fp8_sdwa v[238:239], v123 src0_sel:WORD_1
	v_pk_fma_f32 v[228:229], v[60:61], v[236:237], v[228:229] op_sel:[1,0,0]
	v_pk_fma_f32 v[230:231], v[60:61], v[238:239], v[230:231] op_sel:[1,0,0]
	s_waitcnt vmcnt(21)
	v_cvt_pk_f32_fp8_e32 v[232:233], v124
	v_cvt_pk_f32_fp8_sdwa v[234:235], v124 src0_sel:WORD_1
	v_pk_fma_f32 v[216:217], v[62:63], v[232:233], v[216:217] op_sel_hi:[0,1,1]
	v_pk_fma_f32 v[218:219], v[62:63], v[234:235], v[218:219] op_sel_hi:[0,1,1]
	v_cvt_pk_f32_fp8_e32 v[236:237], v125
	v_cvt_pk_f32_fp8_sdwa v[238:239], v125 src0_sel:WORD_1
	v_pk_fma_f32 v[220:221], v[62:63], v[236:237], v[220:221] op_sel_hi:[0,1,1]
	v_pk_fma_f32 v[222:223], v[62:63], v[238:239], v[222:223] op_sel_hi:[0,1,1]
	v_cvt_pk_f32_fp8_e32 v[232:233], v126
	v_cvt_pk_f32_fp8_sdwa v[234:235], v126 src0_sel:WORD_1
	v_pk_fma_f32 v[224:225], v[62:63], v[232:233], v[224:225] op_sel_hi:[0,1,1]
	v_pk_fma_f32 v[226:227], v[62:63], v[234:235], v[226:227] op_sel_hi:[0,1,1]
	v_cvt_pk_f32_fp8_e32 v[236:237], v127
	v_cvt_pk_f32_fp8_sdwa v[238:239], v127 src0_sel:WORD_1
	v_pk_fma_f32 v[228:229], v[62:63], v[236:237], v[228:229] op_sel_hi:[0,1,1]
	v_pk_fma_f32 v[230:231], v[62:63], v[238:239], v[230:231] op_sel_hi:[0,1,1]
	s_waitcnt vmcnt(20)
	v_cvt_pk_f32_fp8_e32 v[232:233], v128
	v_cvt_pk_f32_fp8_sdwa v[234:235], v128 src0_sel:WORD_1
	v_pk_fma_f32 v[216:217], v[62:63], v[232:233], v[216:217] op_sel:[1,0,0]
	v_pk_fma_f32 v[218:219], v[62:63], v[234:235], v[218:219] op_sel:[1,0,0]
	v_cvt_pk_f32_fp8_e32 v[236:237], v129
	v_cvt_pk_f32_fp8_sdwa v[238:239], v129 src0_sel:WORD_1
	v_pk_fma_f32 v[220:221], v[62:63], v[236:237], v[220:221] op_sel:[1,0,0]
	v_pk_fma_f32 v[222:223], v[62:63], v[238:239], v[222:223] op_sel:[1,0,0]
	v_cvt_pk_f32_fp8_e32 v[232:233], v130
	v_cvt_pk_f32_fp8_sdwa v[234:235], v130 src0_sel:WORD_1
	v_pk_fma_f32 v[224:225], v[62:63], v[232:233], v[224:225] op_sel:[1,0,0]
	v_pk_fma_f32 v[226:227], v[62:63], v[234:235], v[226:227] op_sel:[1,0,0]
	v_cvt_pk_f32_fp8_e32 v[236:237], v131
	v_cvt_pk_f32_fp8_sdwa v[238:239], v131 src0_sel:WORD_1
	v_pk_fma_f32 v[228:229], v[62:63], v[236:237], v[228:229] op_sel:[1,0,0]
	v_pk_fma_f32 v[230:231], v[62:63], v[238:239], v[230:231] op_sel:[1,0,0]
	s_waitcnt vmcnt(19)
; DI f2_t cvt8lo(unsigned w) { return __builtin_amdgcn_cvt_pk_f32_fp8(w, false); }
; DI f2_t cvt8hi(unsigned w) { return __builtin_amdgcn_cvt_pk_f32_fp8(w, true); }
; DI void wave_lds_sync() { asm volatile("s_waitcnt lgkmcnt(0)" ::: "memory"); __builtin_amdgcn_wave_barrier(); }
; DI void phase11(const Params& p, char* smem, int rep) {
;     ...
;       wave_lds_sync();
;       lw[(lane & 3) * 32 + (lane >> 2)] = i0; lw[(lane & 3) * 32 + 16 + (lane >> 2)] = i1;
;       lf[(lane & 3) * 32 + (lane >> 2)] = a0; lf[(lane & 3) * 32 + 16 + (lane >> 2)] = a1;
;       wave_lds_sync();
;     ...
;         for (int k = 0; k < 16; ++k) rows[k] = *(const u32x4*)(vb + (size_t)ida[k] * 2048);
; #pragma unroll
;         for (int k = 0; k < 16; ++k) {
;           const f2_t a2 = {aa[k], aa[k]};
; #pragma unroll
;           for (int d = 0; d < 4; ++d) { const unsigned ww = rows[k][d]; o[2 * d] += a2 * cvt8lo(ww); o[2 * d + 1] += a2 * cvt8hi(ww); }
	v_cvt_pk_f32_fp8_e32 v[232:233], v132
	v_cvt_pk_f32_fp8_sdwa v[234:235], v132 src0_sel:WORD_1
	v_pk_fma_f32 v[216:217], v[64:65], v[232:233], v[216:217] op_sel_hi:[0,1,1]
	v_pk_fma_f32 v[218:219], v[64:65], v[234:235], v[218:219] op_sel_hi:[0,1,1]
	v_cvt_pk_f32_fp8_e32 v[236:237], v133
	v_cvt_pk_f32_fp8_sdwa v[238:239], v133 src0_sel:WORD_1
	v_pk_fma_f32 v[220:221], v[64:65], v[236:237], v[220:221] op_sel_hi:[0,1,1]
	v_pk_fma_f32 v[222:223], v[64:65], v[238:239], v[222:223] op_sel_hi:[0,1,1]
	v_cvt_pk_f32_fp8_e32 v[232:233], v134
	v_cvt_pk_f32_fp8_sdwa v[234:235], v134 src0_sel:WORD_1
	v_pk_fma_f32 v[224:225], v[64:65], v[232:233], v[224:225] op_sel_hi:[0,1,1]
	v_pk_fma_f32 v[226:227], v[64:65], v[234:235], v[226:227] op_sel_hi:[0,1,1]
	v_cvt_pk_f32_fp8_e32 v[236:237], v135
	v_cvt_pk_f32_fp8_sdwa v[238:239], v135 src0_sel:WORD_1
	v_pk_fma_f32 v[228:229], v[64:65], v[236:237], v[228:229] op_sel_hi:[0,1,1]
	v_pk_fma_f32 v[230:231], v[64:65], v[238:239], v[230:231] op_sel_hi:[0,1,1]
	s_waitcnt vmcnt(18)
	v_cvt_pk_f32_fp8_e32 v[232:233], v136
	v_cvt_pk_f32_fp8_sdwa v[234:235], v136 src0_sel:WORD_1
	v_pk_fma_f32 v[216:217], v[64:65], v[232:233], v[216:217] op_sel:[1,0,0]
	v_pk_fma_f32 v[218:219], v[64:65], v[234:235], v[218:219] op_sel:[1,0,0]
	v_cvt_pk_f32_fp8_e32 v[236:237], v137
	v_cvt_pk_f32_fp8_sdwa v[238:239], v137 src0_sel:WORD_1
	v_pk_fma_f32 v[220:221], v[64:65], v[236:237], v[220:221] op_sel:[1,0,0]
	v_pk_fma_f32 v[222:223], v[64:65], v[238:239], v[222:223] op_sel:[1,0,0]
	v_cvt_pk_f32_fp8_e32 v[232:233], v138
	v_cvt_pk_f32_fp8_sdwa v[234:235], v138 src0_sel:WORD_1
	v_pk_fma_f32 v[224:225], v[64:65], v[232:233], v[224:225] op_sel:[1,0,0]
	v_pk_fma_f32 v[226:227], v[64:65], v[234:235], v[226:227] op_sel:[1,0,0]
	v_cvt_pk_f32_fp8_e32 v[236:237], v139
	v_cvt_pk_f32_fp8_sdwa v[238:239], v139 src0_sel:WORD_1
	v_pk_fma_f32 v[228:229], v[64:65], v[236:237], v[228:229] op_sel:[1,0,0]
	v_pk_fma_f32 v[230:231], v[64:65], v[238:239], v[230:231] op_sel:[1,0,0]
	s_waitcnt vmcnt(17)
	v_cvt_pk_f32_fp8_e32 v[232:233], v140
	v_cvt_pk_f32_fp8_sdwa v[234:235], v140 src0_sel:WORD_1
	v_pk_fma_f32 v[216:217], v[66:67], v[232:233], v[216:217] op_sel_hi:[0,1,1]
	v_pk_fma_f32 v[218:219], v[66:67], v[234:235], v[218:219] op_sel_hi:[0,1,1]
	v_cvt_pk_f32_fp8_e32 v[236:237], v141
	v_cvt_pk_f32_fp8_sdwa v[238:239], v141 src0_sel:WORD_1
	v_pk_fma_f32 v[220:221], v[66:67], v[236:237], v[220:221] op_sel_hi:[0,1,1]
	v_pk_fma_f32 v[222:223], v[66:67], v[238:239], v[222:223] op_sel_hi:[0,1,1]
	v_cvt_pk_f32_fp8_e32 v[232:233], v142
	v_cvt_pk_f32_fp8_sdwa v[234:235], v142 src0_sel:WORD_1
	v_pk_fma_f32 v[224:225], v[66:67], v[232:233], v[224:225] op_sel_hi:[0,1,1]
	v_pk_fma_f32 v[226:227], v[66:67], v[234:235], v[226:227] op_sel_hi:[0,1,1]
	v_cvt_pk_f32_fp8_e32 v[236:237], v143
	v_cvt_pk_f32_fp8_sdwa v[238:239], v143 src0_sel:WORD_1
	v_pk_fma_f32 v[228:229], v[66:67], v[236:237], v[228:229] op_sel_hi:[0,1,1]
	v_pk_fma_f32 v[230:231], v[66:67], v[238:239], v[230:231] op_sel_hi:[0,1,1]
	s_waitcnt vmcnt(16)
	v_cvt_pk_f32_fp8_e32 v[232:233], v144
	v_cvt_pk_f32_fp8_sdwa v[234:235], v144 src0_sel:WORD_1
	v_pk_fma_f32 v[216:217], v[66:67], v[232:233], v[216:217] op_sel:[1,0,0]
	v_pk_fma_f32 v[218:219], v[66:67], v[234:235], v[218:219] op_sel:[1,0,0]
	v_cvt_pk_f32_fp8_e32 v[236:237], v145
	v_cvt_pk_f32_fp8_sdwa v[238:239], v145 src0_sel:WORD_1
	v_pk_fma_f32 v[220:221], v[66:67], v[236:237], v[220:221] op_sel:[1,0,0]
	v_pk_fma_f32 v[222:223], v[66:67], v[238:239], v[222:223] op_sel:[1,0,0]
	v_cvt_pk_f32_fp8_e32 v[232:233], v146
	v_cvt_pk_f32_fp8_sdwa v[234:235], v146 src0_sel:WORD_1
	v_pk_fma_f32 v[224:225], v[66:67], v[232:233], v[224:225] op_sel:[1,0,0]
	v_pk_fma_f32 v[226:227], v[66:67], v[234:235], v[226:227] op_sel:[1,0,0]
	v_cvt_pk_f32_fp8_e32 v[236:237], v147
	v_cvt_pk_f32_fp8_sdwa v[238:239], v147 src0_sel:WORD_1
	v_pk_fma_f32 v[228:229], v[66:67], v[236:237], v[228:229] op_sel:[1,0,0]
	v_pk_fma_f32 v[230:231], v[66:67], v[238:239], v[230:231] op_sel:[1,0,0]
	ds_write2_b32 v5, v10, v11 offset0:4 offset1:20
	ds_write2_b32 v5, v12, v13 offset0:132 offset1:148
	s_waitcnt lgkmcnt(0)
	ds_read_b128 v[20:23], v6 offset:16
	ds_read_b128 v[24:27], v6 offset:32
	ds_read_b128 v[28:31], v6 offset:48
	ds_read_b128 v[32:35], v6 offset:64
	ds_read_b128 v[36:39], v6 offset:80
	ds_read_b128 v[40:43], v6 offset:96
	ds_read_b128 v[44:47], v6 offset:112
	ds_read_b128 v[48:51], v6 offset:128
	s_waitcnt vmcnt(15)
	v_cvt_pk_f32_fp8_e32 v[232:233], v148
	v_cvt_pk_f32_fp8_sdwa v[234:235], v148 src0_sel:WORD_1
	v_pk_fma_f32 v[216:217], v[68:69], v[232:233], v[216:217] op_sel_hi:[0,1,1]
	v_pk_fma_f32 v[218:219], v[68:69], v[234:235], v[218:219] op_sel_hi:[0,1,1]
	v_cvt_pk_f32_fp8_e32 v[236:237], v149
	v_cvt_pk_f32_fp8_sdwa v[238:239], v149 src0_sel:WORD_1
	v_pk_fma_f32 v[220:221], v[68:69], v[236:237], v[220:221] op_sel_hi:[0,1,1]
	v_pk_fma_f32 v[222:223], v[68:69], v[238:239], v[222:223] op_sel_hi:[0,1,1]
	v_cvt_pk_f32_fp8_e32 v[232:233], v150
	v_cvt_pk_f32_fp8_sdwa v[234:235], v150 src0_sel:WORD_1
	v_pk_fma_f32 v[224:225], v[68:69], v[232:233], v[224:225] op_sel_hi:[0,1,1]
	v_pk_fma_f32 v[226:227], v[68:69], v[234:235], v[226:227] op_sel_hi:[0,1,1]
	v_cvt_pk_f32_fp8_e32 v[236:237], v151
	v_cvt_pk_f32_fp8_sdwa v[238:239], v151 src0_sel:WORD_1
	v_pk_fma_f32 v[228:229], v[68:69], v[236:237], v[228:229] op_sel_hi:[0,1,1]
	v_pk_fma_f32 v[230:231], v[68:69], v[238:239], v[230:231] op_sel_hi:[0,1,1]
	s_waitcnt vmcnt(14)
; DI f2_t cvt8lo(unsigned w) { return __builtin_amdgcn_cvt_pk_f32_fp8(w, false); }
; DI f2_t cvt8hi(unsigned w) { return __builtin_amdgcn_cvt_pk_f32_fp8(w, true); }
; DI void phase11(const Params& p, char* smem, int rep) {
;     ...
;         for (int k = 0; k < 16; ++k) rows[k] = *(const u32x4*)(vb + (size_t)ida[k] * 2048);
; #pragma unroll
;         for (int k = 0; k < 16; ++k) {
;           const f2_t a2 = {aa[k], aa[k]};
; #pragma unroll
;           for (int d = 0; d < 4; ++d) { const unsigned ww = rows[k][d]; o[2 * d] += a2 * cvt8lo(ww); o[2 * d + 1] += a2 * cvt8hi(ww); }
	v_cvt_pk_f32_fp8_e32 v[232:233], v152
	v_cvt_pk_f32_fp8_sdwa v[234:235], v152 src0_sel:WORD_1
	v_pk_fma_f32 v[216:217], v[68:69], v[232:233], v[216:217] op_sel:[1,0,0]
	v_pk_fma_f32 v[218:219], v[68:69], v[234:235], v[218:219] op_sel:[1,0,0]
	v_cvt_pk_f32_fp8_e32 v[236:237], v153
	v_cvt_pk_f32_fp8_sdwa v[238:239], v153 src0_sel:WORD_1
	v_pk_fma_f32 v[220:221], v[68:69], v[236:237], v[220:221] op_sel:[1,0,0]
	v_pk_fma_f32 v[222:223], v[68:69], v[238:239], v[222:223] op_sel:[1,0,0]
	v_cvt_pk_f32_fp8_e32 v[232:233], v154
	v_cvt_pk_f32_fp8_sdwa v[234:235], v154 src0_sel:WORD_1
	v_pk_fma_f32 v[224:225], v[68:69], v[232:233], v[224:225] op_sel:[1,0,0]
	v_pk_fma_f32 v[226:227], v[68:69], v[234:235], v[226:227] op_sel:[1,0,0]
	v_cvt_pk_f32_fp8_e32 v[236:237], v155
	v_cvt_pk_f32_fp8_sdwa v[238:239], v155 src0_sel:WORD_1
	v_pk_fma_f32 v[228:229], v[68:69], v[236:237], v[228:229] op_sel:[1,0,0]
	v_pk_fma_f32 v[230:231], v[68:69], v[238:239], v[230:231] op_sel:[1,0,0]
	s_waitcnt vmcnt(13)
	v_cvt_pk_f32_fp8_e32 v[232:233], v156
	v_cvt_pk_f32_fp8_sdwa v[234:235], v156 src0_sel:WORD_1
	v_pk_fma_f32 v[216:217], v[70:71], v[232:233], v[216:217] op_sel_hi:[0,1,1]
	v_pk_fma_f32 v[218:219], v[70:71], v[234:235], v[218:219] op_sel_hi:[0,1,1]
	v_cvt_pk_f32_fp8_e32 v[236:237], v157
	v_cvt_pk_f32_fp8_sdwa v[238:239], v157 src0_sel:WORD_1
	v_pk_fma_f32 v[220:221], v[70:71], v[236:237], v[220:221] op_sel_hi:[0,1,1]
	v_pk_fma_f32 v[222:223], v[70:71], v[238:239], v[222:223] op_sel_hi:[0,1,1]
	v_cvt_pk_f32_fp8_e32 v[232:233], v158
	v_cvt_pk_f32_fp8_sdwa v[234:235], v158 src0_sel:WORD_1
	v_pk_fma_f32 v[224:225], v[70:71], v[232:233], v[224:225] op_sel_hi:[0,1,1]
	v_pk_fma_f32 v[226:227], v[70:71], v[234:235], v[226:227] op_sel_hi:[0,1,1]
	v_cvt_pk_f32_fp8_e32 v[236:237], v159
	v_cvt_pk_f32_fp8_sdwa v[238:239], v159 src0_sel:WORD_1
	v_pk_fma_f32 v[228:229], v[70:71], v[236:237], v[228:229] op_sel_hi:[0,1,1]
	v_pk_fma_f32 v[230:231], v[70:71], v[238:239], v[230:231] op_sel_hi:[0,1,1]
	s_waitcnt vmcnt(12)
	v_cvt_pk_f32_fp8_e32 v[232:233], v160
	v_cvt_pk_f32_fp8_sdwa v[234:235], v160 src0_sel:WORD_1
	v_pk_fma_f32 v[216:217], v[70:71], v[232:233], v[216:217] op_sel:[1,0,0]
	v_pk_fma_f32 v[218:219], v[70:71], v[234:235], v[218:219] op_sel:[1,0,0]
	v_cvt_pk_f32_fp8_e32 v[236:237], v161
	v_cvt_pk_f32_fp8_sdwa v[238:239], v161 src0_sel:WORD_1
	v_pk_fma_f32 v[220:221], v[70:71], v[236:237], v[220:221] op_sel:[1,0,0]
	v_pk_fma_f32 v[222:223], v[70:71], v[238:239], v[222:223] op_sel:[1,0,0]
	v_cvt_pk_f32_fp8_e32 v[232:233], v162
	v_cvt_pk_f32_fp8_sdwa v[234:235], v162 src0_sel:WORD_1
	v_pk_fma_f32 v[224:225], v[70:71], v[232:233], v[224:225] op_sel:[1,0,0]
	v_pk_fma_f32 v[226:227], v[70:71], v[234:235], v[226:227] op_sel:[1,0,0]
	v_cvt_pk_f32_fp8_e32 v[236:237], v163
	v_cvt_pk_f32_fp8_sdwa v[238:239], v163 src0_sel:WORD_1
	v_pk_fma_f32 v[228:229], v[70:71], v[236:237], v[228:229] op_sel:[1,0,0]
	v_pk_fma_f32 v[230:231], v[70:71], v[238:239], v[230:231] op_sel:[1,0,0]
	s_waitcnt vmcnt(11)
	v_cvt_pk_f32_fp8_e32 v[232:233], v164
	v_cvt_pk_f32_fp8_sdwa v[234:235], v164 src0_sel:WORD_1
	v_pk_fma_f32 v[216:217], v[72:73], v[232:233], v[216:217] op_sel_hi:[0,1,1]
	v_pk_fma_f32 v[218:219], v[72:73], v[234:235], v[218:219] op_sel_hi:[0,1,1]
	v_cvt_pk_f32_fp8_e32 v[236:237], v165
	v_cvt_pk_f32_fp8_sdwa v[238:239], v165 src0_sel:WORD_1
	v_pk_fma_f32 v[220:221], v[72:73], v[236:237], v[220:221] op_sel_hi:[0,1,1]
	v_pk_fma_f32 v[222:223], v[72:73], v[238:239], v[222:223] op_sel_hi:[0,1,1]
	v_cvt_pk_f32_fp8_e32 v[232:233], v166
	v_cvt_pk_f32_fp8_sdwa v[234:235], v166 src0_sel:WORD_1
	v_pk_fma_f32 v[224:225], v[72:73], v[232:233], v[224:225] op_sel_hi:[0,1,1]
	v_pk_fma_f32 v[226:227], v[72:73], v[234:235], v[226:227] op_sel_hi:[0,1,1]
	v_cvt_pk_f32_fp8_e32 v[236:237], v167
	v_cvt_pk_f32_fp8_sdwa v[238:239], v167 src0_sel:WORD_1
	v_pk_fma_f32 v[228:229], v[72:73], v[236:237], v[228:229] op_sel_hi:[0,1,1]
	v_pk_fma_f32 v[230:231], v[72:73], v[238:239], v[230:231] op_sel_hi:[0,1,1]
	s_waitcnt vmcnt(10)
	v_cvt_pk_f32_fp8_e32 v[232:233], v168
	v_cvt_pk_f32_fp8_sdwa v[234:235], v168 src0_sel:WORD_1
	v_pk_fma_f32 v[216:217], v[72:73], v[232:233], v[216:217] op_sel:[1,0,0]
	v_pk_fma_f32 v[218:219], v[72:73], v[234:235], v[218:219] op_sel:[1,0,0]
	v_cvt_pk_f32_fp8_e32 v[236:237], v169
	v_cvt_pk_f32_fp8_sdwa v[238:239], v169 src0_sel:WORD_1
	v_pk_fma_f32 v[220:221], v[72:73], v[236:237], v[220:221] op_sel:[1,0,0]
	v_pk_fma_f32 v[222:223], v[72:73], v[238:239], v[222:223] op_sel:[1,0,0]
	v_cvt_pk_f32_fp8_e32 v[232:233], v170
	v_cvt_pk_f32_fp8_sdwa v[234:235], v170 src0_sel:WORD_1
	v_pk_fma_f32 v[224:225], v[72:73], v[232:233], v[224:225] op_sel:[1,0,0]
	v_pk_fma_f32 v[226:227], v[72:73], v[234:235], v[226:227] op_sel:[1,0,0]
	v_cvt_pk_f32_fp8_e32 v[236:237], v171
	v_cvt_pk_f32_fp8_sdwa v[238:239], v171 src0_sel:WORD_1
	v_pk_fma_f32 v[228:229], v[72:73], v[236:237], v[228:229] op_sel:[1,0,0]
	v_pk_fma_f32 v[230:231], v[72:73], v[238:239], v[230:231] op_sel:[1,0,0]
	s_waitcnt vmcnt(9)
	v_cvt_pk_f32_fp8_e32 v[232:233], v172
	v_cvt_pk_f32_fp8_sdwa v[234:235], v172 src0_sel:WORD_1
	v_pk_fma_f32 v[216:217], v[74:75], v[232:233], v[216:217] op_sel_hi:[0,1,1]
	v_pk_fma_f32 v[218:219], v[74:75], v[234:235], v[218:219] op_sel_hi:[0,1,1]
	v_cvt_pk_f32_fp8_e32 v[236:237], v173
	v_cvt_pk_f32_fp8_sdwa v[238:239], v173 src0_sel:WORD_1
	v_pk_fma_f32 v[220:221], v[74:75], v[236:237], v[220:221] op_sel_hi:[0,1,1]
	v_pk_fma_f32 v[222:223], v[74:75], v[238:239], v[222:223] op_sel_hi:[0,1,1]
	v_cvt_pk_f32_fp8_e32 v[232:233], v174
	v_cvt_pk_f32_fp8_sdwa v[234:235], v174 src0_sel:WORD_1
	v_pk_fma_f32 v[224:225], v[74:75], v[232:233], v[224:225] op_sel_hi:[0,1,1]
	v_pk_fma_f32 v[226:227], v[74:75], v[234:235], v[226:227] op_sel_hi:[0,1,1]
	v_cvt_pk_f32_fp8_e32 v[236:237], v175
	v_cvt_pk_f32_fp8_sdwa v[238:239], v175 src0_sel:WORD_1
	v_pk_fma_f32 v[228:229], v[74:75], v[236:237], v[228:229] op_sel_hi:[0,1,1]
	v_pk_fma_f32 v[230:231], v[74:75], v[238:239], v[230:231] op_sel_hi:[0,1,1]
	s_waitcnt vmcnt(8)
; DI f2_t cvt8lo(unsigned w) { return __builtin_amdgcn_cvt_pk_f32_fp8(w, false); }
; DI f2_t cvt8hi(unsigned w) { return __builtin_amdgcn_cvt_pk_f32_fp8(w, true); }
; DI void phase11(const Params& p, char* smem, int rep) {
;     ...
;         for (int k = 0; k < 16; ++k) rows[k] = *(const u32x4*)(vb + (size_t)ida[k] * 2048);
; #pragma unroll
;         for (int k = 0; k < 16; ++k) {
;           const f2_t a2 = {aa[k], aa[k]};
; #pragma unroll
;           for (int d = 0; d < 4; ++d) { const unsigned ww = rows[k][d]; o[2 * d] += a2 * cvt8lo(ww); o[2 * d + 1] += a2 * cvt8hi(ww); }
	v_cvt_pk_f32_fp8_e32 v[232:233], v176
	v_cvt_pk_f32_fp8_sdwa v[234:235], v176 src0_sel:WORD_1
	v_pk_fma_f32 v[216:217], v[74:75], v[232:233], v[216:217] op_sel:[1,0,0]
	v_pk_fma_f32 v[218:219], v[74:75], v[234:235], v[218:219] op_sel:[1,0,0]
	v_cvt_pk_f32_fp8_e32 v[236:237], v177
	v_cvt_pk_f32_fp8_sdwa v[238:239], v177 src0_sel:WORD_1
	v_pk_fma_f32 v[220:221], v[74:75], v[236:237], v[220:221] op_sel:[1,0,0]
	v_pk_fma_f32 v[222:223], v[74:75], v[238:239], v[222:223] op_sel:[1,0,0]
	v_cvt_pk_f32_fp8_e32 v[232:233], v178
	v_cvt_pk_f32_fp8_sdwa v[234:235], v178 src0_sel:WORD_1
	v_pk_fma_f32 v[224:225], v[74:75], v[232:233], v[224:225] op_sel:[1,0,0]
	v_pk_fma_f32 v[226:227], v[74:75], v[234:235], v[226:227] op_sel:[1,0,0]
	v_cvt_pk_f32_fp8_e32 v[236:237], v179
	v_cvt_pk_f32_fp8_sdwa v[238:239], v179 src0_sel:WORD_1
	v_pk_fma_f32 v[228:229], v[74:75], v[236:237], v[228:229] op_sel:[1,0,0]
	v_pk_fma_f32 v[230:231], v[74:75], v[238:239], v[230:231] op_sel:[1,0,0]
	s_waitcnt vmcnt(7)
	v_cvt_pk_f32_fp8_e32 v[232:233], v180
	v_cvt_pk_f32_fp8_sdwa v[234:235], v180 src0_sel:WORD_1
	v_pk_fma_f32 v[216:217], v[76:77], v[232:233], v[216:217] op_sel_hi:[0,1,1]
	v_pk_fma_f32 v[218:219], v[76:77], v[234:235], v[218:219] op_sel_hi:[0,1,1]
	v_cvt_pk_f32_fp8_e32 v[236:237], v181
	v_cvt_pk_f32_fp8_sdwa v[238:239], v181 src0_sel:WORD_1
	v_pk_fma_f32 v[220:221], v[76:77], v[236:237], v[220:221] op_sel_hi:[0,1,1]
	v_pk_fma_f32 v[222:223], v[76:77], v[238:239], v[222:223] op_sel_hi:[0,1,1]
	v_cvt_pk_f32_fp8_e32 v[232:233], v182
	v_cvt_pk_f32_fp8_sdwa v[234:235], v182 src0_sel:WORD_1
	v_pk_fma_f32 v[224:225], v[76:77], v[232:233], v[224:225] op_sel_hi:[0,1,1]
	v_pk_fma_f32 v[226:227], v[76:77], v[234:235], v[226:227] op_sel_hi:[0,1,1]
	v_cvt_pk_f32_fp8_e32 v[236:237], v183
	v_cvt_pk_f32_fp8_sdwa v[238:239], v183 src0_sel:WORD_1
	v_pk_fma_f32 v[228:229], v[76:77], v[236:237], v[228:229] op_sel_hi:[0,1,1]
	v_pk_fma_f32 v[230:231], v[76:77], v[238:239], v[230:231] op_sel_hi:[0,1,1]
	s_waitcnt vmcnt(6)
	v_cvt_pk_f32_fp8_e32 v[232:233], v184
	v_cvt_pk_f32_fp8_sdwa v[234:235], v184 src0_sel:WORD_1
	v_pk_fma_f32 v[216:217], v[76:77], v[232:233], v[216:217] op_sel:[1,0,0]
	v_pk_fma_f32 v[218:219], v[76:77], v[234:235], v[218:219] op_sel:[1,0,0]
	v_cvt_pk_f32_fp8_e32 v[236:237], v185
	v_cvt_pk_f32_fp8_sdwa v[238:239], v185 src0_sel:WORD_1
	v_pk_fma_f32 v[220:221], v[76:77], v[236:237], v[220:221] op_sel:[1,0,0]
	v_pk_fma_f32 v[222:223], v[76:77], v[238:239], v[222:223] op_sel:[1,0,0]
	v_cvt_pk_f32_fp8_e32 v[232:233], v186
	v_cvt_pk_f32_fp8_sdwa v[234:235], v186 src0_sel:WORD_1
	v_pk_fma_f32 v[224:225], v[76:77], v[232:233], v[224:225] op_sel:[1,0,0]
	v_pk_fma_f32 v[226:227], v[76:77], v[234:235], v[226:227] op_sel:[1,0,0]
	v_cvt_pk_f32_fp8_e32 v[236:237], v187
	v_cvt_pk_f32_fp8_sdwa v[238:239], v187 src0_sel:WORD_1
	v_pk_fma_f32 v[228:229], v[76:77], v[236:237], v[228:229] op_sel:[1,0,0]
	v_pk_fma_f32 v[230:231], v[76:77], v[238:239], v[230:231] op_sel:[1,0,0]
	s_waitcnt vmcnt(5)
	v_cvt_pk_f32_fp8_e32 v[232:233], v190
	v_cvt_pk_f32_fp8_sdwa v[234:235], v190 src0_sel:WORD_1
	v_pk_fma_f32 v[216:217], v[78:79], v[232:233], v[216:217] op_sel_hi:[0,1,1]
	v_pk_fma_f32 v[218:219], v[78:79], v[234:235], v[218:219] op_sel_hi:[0,1,1]
	v_cvt_pk_f32_fp8_e32 v[236:237], v191
	v_cvt_pk_f32_fp8_sdwa v[238:239], v191 src0_sel:WORD_1
	v_pk_fma_f32 v[220:221], v[78:79], v[236:237], v[220:221] op_sel_hi:[0,1,1]
	v_pk_fma_f32 v[222:223], v[78:79], v[238:239], v[222:223] op_sel_hi:[0,1,1]
	v_cvt_pk_f32_fp8_e32 v[232:233], v192
	v_cvt_pk_f32_fp8_sdwa v[234:235], v192 src0_sel:WORD_1
	v_pk_fma_f32 v[224:225], v[78:79], v[232:233], v[224:225] op_sel_hi:[0,1,1]
	v_pk_fma_f32 v[226:227], v[78:79], v[234:235], v[226:227] op_sel_hi:[0,1,1]
	v_cvt_pk_f32_fp8_e32 v[236:237], v193
	v_cvt_pk_f32_fp8_sdwa v[238:239], v193 src0_sel:WORD_1
	v_pk_fma_f32 v[228:229], v[78:79], v[236:237], v[228:229] op_sel_hi:[0,1,1]
	v_pk_fma_f32 v[230:231], v[78:79], v[238:239], v[230:231] op_sel_hi:[0,1,1]
	s_waitcnt vmcnt(4)
	v_cvt_pk_f32_fp8_e32 v[232:233], v194
	v_cvt_pk_f32_fp8_sdwa v[234:235], v194 src0_sel:WORD_1
	v_pk_fma_f32 v[216:217], v[78:79], v[232:233], v[216:217] op_sel:[1,0,0]
	v_pk_fma_f32 v[218:219], v[78:79], v[234:235], v[218:219] op_sel:[1,0,0]
	v_cvt_pk_f32_fp8_e32 v[236:237], v195
	v_cvt_pk_f32_fp8_sdwa v[238:239], v195 src0_sel:WORD_1
	v_pk_fma_f32 v[220:221], v[78:79], v[236:237], v[220:221] op_sel:[1,0,0]
	v_pk_fma_f32 v[222:223], v[78:79], v[238:239], v[222:223] op_sel:[1,0,0]
	v_cvt_pk_f32_fp8_e32 v[232:233], v196
	v_cvt_pk_f32_fp8_sdwa v[234:235], v196 src0_sel:WORD_1
	v_pk_fma_f32 v[224:225], v[78:79], v[232:233], v[224:225] op_sel:[1,0,0]
	v_pk_fma_f32 v[226:227], v[78:79], v[234:235], v[226:227] op_sel:[1,0,0]
	v_cvt_pk_f32_fp8_e32 v[236:237], v197
	v_cvt_pk_f32_fp8_sdwa v[238:239], v197 src0_sel:WORD_1
	v_pk_fma_f32 v[228:229], v[78:79], v[236:237], v[228:229] op_sel:[1,0,0]
	v_pk_fma_f32 v[230:231], v[78:79], v[238:239], v[230:231] op_sel:[1,0,0]
	s_waitcnt vmcnt(3)
; DI unsigned pk2(float a, float b) { f2_t v = {a, b}; bf2_t r = __builtin_convertvector(v, bf2_t); return __builtin_bit_cast(unsigned, r); }
; DI f2_t cvt8lo(unsigned w) { return __builtin_amdgcn_cvt_pk_f32_fp8(w, false); }
; DI f2_t cvt8hi(unsigned w) { return __builtin_amdgcn_cvt_pk_f32_fp8(w, true); }
; DI void phase11(const Params& p, char* smem, int rep) {
;     ...
;         for (int k = 0; k < 16; ++k) rows[k] = *(const u32x4*)(vb + (size_t)ida[k] * 2048);
; #pragma unroll
;         for (int k = 0; k < 16; ++k) {
;           const f2_t a2 = {aa[k], aa[k]};
; #pragma unroll
;           for (int d = 0; d < 4; ++d) { const unsigned ww = rows[k][d]; o[2 * d] += a2 * cvt8lo(ww); o[2 * d + 1] += a2 * cvt8hi(ww); }
;         }
;       }
;       float ov[16];
; #pragma unroll
;       for (int d = 0; d < 4; ++d) { ov[4 * d] = o[2 * d].x; ov[4 * d + 1] = o[2 * d].y; ov[4 * d + 2] = o[2 * d + 1].x; ov[4 * d + 3] = o[2 * d + 1].y; }
;       float q8[8], q4[4];
; #pragma unroll
;       for (int k = 0; k < 8; ++k) q8[k] = (b5 ? ov[8 + k] : ov[k]) + __shfl_xor(b5 ? ov[k] : ov[8 + k], 32);
; #pragma unroll
;       for (int k = 0; k < 4; ++k) q4[k] = (b4 ? q8[4 + k] : q8[k]) + __shfl_xor(b4 ? q8[k] : q8[4 + k], 16);
;       *(uint2*)(OUTP + (size_t)tok * D_ + s * 256 + l15 * 16 + 8 * b5 + 4 * b4) = make_uint2(pk2(q4[0], q4[1]), pk2(q4[2], q4[3]));
;     }
	v_cvt_pk_f32_fp8_e32 v[232:233], v198
	v_cvt_pk_f32_fp8_sdwa v[234:235], v198 src0_sel:WORD_1
	v_pk_fma_f32 v[216:217], v[80:81], v[232:233], v[216:217] op_sel_hi:[0,1,1]
	v_pk_fma_f32 v[218:219], v[80:81], v[234:235], v[218:219] op_sel_hi:[0,1,1]
	v_cvt_pk_f32_fp8_e32 v[236:237], v199
	v_cvt_pk_f32_fp8_sdwa v[238:239], v199 src0_sel:WORD_1
	v_pk_fma_f32 v[220:221], v[80:81], v[236:237], v[220:221] op_sel_hi:[0,1,1]
	v_pk_fma_f32 v[222:223], v[80:81], v[238:239], v[222:223] op_sel_hi:[0,1,1]
	v_cvt_pk_f32_fp8_e32 v[232:233], v200
	v_cvt_pk_f32_fp8_sdwa v[234:235], v200 src0_sel:WORD_1
	v_pk_fma_f32 v[224:225], v[80:81], v[232:233], v[224:225] op_sel_hi:[0,1,1]
	v_pk_fma_f32 v[226:227], v[80:81], v[234:235], v[226:227] op_sel_hi:[0,1,1]
	v_cvt_pk_f32_fp8_e32 v[236:237], v201
	v_cvt_pk_f32_fp8_sdwa v[238:239], v201 src0_sel:WORD_1
	v_pk_fma_f32 v[228:229], v[80:81], v[236:237], v[228:229] op_sel_hi:[0,1,1]
	v_pk_fma_f32 v[230:231], v[80:81], v[238:239], v[230:231] op_sel_hi:[0,1,1]
	s_waitcnt vmcnt(2)
	v_cvt_pk_f32_fp8_e32 v[232:233], v202
	v_cvt_pk_f32_fp8_sdwa v[234:235], v202 src0_sel:WORD_1
	v_pk_fma_f32 v[216:217], v[80:81], v[232:233], v[216:217] op_sel:[1,0,0]
	v_pk_fma_f32 v[218:219], v[80:81], v[234:235], v[218:219] op_sel:[1,0,0]
	v_cvt_pk_f32_fp8_e32 v[236:237], v203
	v_cvt_pk_f32_fp8_sdwa v[238:239], v203 src0_sel:WORD_1
	v_pk_fma_f32 v[220:221], v[80:81], v[236:237], v[220:221] op_sel:[1,0,0]
	v_pk_fma_f32 v[222:223], v[80:81], v[238:239], v[222:223] op_sel:[1,0,0]
	v_cvt_pk_f32_fp8_e32 v[232:233], v204
	v_cvt_pk_f32_fp8_sdwa v[234:235], v204 src0_sel:WORD_1
	v_pk_fma_f32 v[224:225], v[80:81], v[232:233], v[224:225] op_sel:[1,0,0]
	v_pk_fma_f32 v[226:227], v[80:81], v[234:235], v[226:227] op_sel:[1,0,0]
	v_cvt_pk_f32_fp8_e32 v[236:237], v205
	v_cvt_pk_f32_fp8_sdwa v[238:239], v205 src0_sel:WORD_1
	v_pk_fma_f32 v[228:229], v[80:81], v[236:237], v[228:229] op_sel:[1,0,0]
	v_pk_fma_f32 v[230:231], v[80:81], v[238:239], v[230:231] op_sel:[1,0,0]
	s_waitcnt vmcnt(1)
	v_cvt_pk_f32_fp8_e32 v[232:233], v206
	v_cvt_pk_f32_fp8_sdwa v[234:235], v206 src0_sel:WORD_1
	v_pk_fma_f32 v[216:217], v[82:83], v[232:233], v[216:217] op_sel_hi:[0,1,1]
	v_pk_fma_f32 v[218:219], v[82:83], v[234:235], v[218:219] op_sel_hi:[0,1,1]
	v_cvt_pk_f32_fp8_e32 v[236:237], v207
	v_cvt_pk_f32_fp8_sdwa v[238:239], v207 src0_sel:WORD_1
	v_pk_fma_f32 v[220:221], v[82:83], v[236:237], v[220:221] op_sel_hi:[0,1,1]
	v_pk_fma_f32 v[222:223], v[82:83], v[238:239], v[222:223] op_sel_hi:[0,1,1]
	v_cvt_pk_f32_fp8_e32 v[232:233], v208
	v_cvt_pk_f32_fp8_sdwa v[234:235], v208 src0_sel:WORD_1
	v_pk_fma_f32 v[224:225], v[82:83], v[232:233], v[224:225] op_sel_hi:[0,1,1]
	v_pk_fma_f32 v[226:227], v[82:83], v[234:235], v[226:227] op_sel_hi:[0,1,1]
	v_cvt_pk_f32_fp8_e32 v[236:237], v209
	v_cvt_pk_f32_fp8_sdwa v[238:239], v209 src0_sel:WORD_1
	v_pk_fma_f32 v[228:229], v[82:83], v[236:237], v[228:229] op_sel_hi:[0,1,1]
	v_pk_fma_f32 v[230:231], v[82:83], v[238:239], v[230:231] op_sel_hi:[0,1,1]
	s_waitcnt vmcnt(0)
	v_cvt_pk_f32_fp8_e32 v[232:233], v210
	v_cvt_pk_f32_fp8_sdwa v[234:235], v210 src0_sel:WORD_1
	v_pk_fma_f32 v[216:217], v[82:83], v[232:233], v[216:217] op_sel:[1,0,0]
	v_pk_fma_f32 v[218:219], v[82:83], v[234:235], v[218:219] op_sel:[1,0,0]
	v_cvt_pk_f32_fp8_e32 v[236:237], v211
	v_cvt_pk_f32_fp8_sdwa v[238:239], v211 src0_sel:WORD_1
	v_pk_fma_f32 v[220:221], v[82:83], v[236:237], v[220:221] op_sel:[1,0,0]
	v_pk_fma_f32 v[222:223], v[82:83], v[238:239], v[222:223] op_sel:[1,0,0]
	v_cvt_pk_f32_fp8_e32 v[232:233], v212
	v_cvt_pk_f32_fp8_sdwa v[234:235], v212 src0_sel:WORD_1
	v_pk_fma_f32 v[224:225], v[82:83], v[232:233], v[224:225] op_sel:[1,0,0]
	v_pk_fma_f32 v[226:227], v[82:83], v[234:235], v[226:227] op_sel:[1,0,0]
	v_cvt_pk_f32_fp8_e32 v[236:237], v213
	v_cvt_pk_f32_fp8_sdwa v[238:239], v213 src0_sel:WORD_1
	v_pk_fma_f32 v[228:229], v[82:83], v[236:237], v[228:229] op_sel:[1,0,0]
	v_pk_fma_f32 v[230:231], v[82:83], v[238:239], v[230:231] op_sel:[1,0,0]
	ds_read_b128 v[52:55], v6 offset:528
	ds_read_b128 v[56:59], v6 offset:544
	ds_read_b128 v[60:63], v6 offset:560
	ds_read_b128 v[64:67], v6 offset:576
	ds_read_b128 v[68:71], v6 offset:592
	ds_read_b128 v[72:75], v6 offset:608
	ds_read_b128 v[76:79], v6 offset:624
	ds_read_b128 v[80:83], v6 offset:640
	v_add_u32_e32 v214, s46, v4
	s_nop 0
	v_permlane32_swap_b32_e32 v216, v224
	v_permlane32_swap_b32_e32 v217, v225
	v_permlane32_swap_b32_e32 v218, v226
	v_permlane32_swap_b32_e32 v219, v227
	v_permlane32_swap_b32_e32 v220, v228
	v_permlane32_swap_b32_e32 v221, v229
	v_permlane32_swap_b32_e32 v222, v230
	v_permlane32_swap_b32_e32 v223, v231
	v_pk_add_f32 v[216:217], v[216:217], v[224:225]
	v_pk_add_f32 v[218:219], v[218:219], v[226:227]
	v_pk_add_f32 v[220:221], v[220:221], v[228:229]
	v_pk_add_f32 v[222:223], v[222:223], v[230:231]
	s_nop 1
	v_permlane16_swap_b32_e32 v216, v220
	v_permlane16_swap_b32_e32 v217, v221
	v_permlane16_swap_b32_e32 v218, v222
	v_permlane16_swap_b32_e32 v219, v223
	v_pk_add_f32 v[216:217], v[216:217], v[220:221]
	v_pk_add_f32 v[218:219], v[218:219], v[222:223]
	v_cvt_pk_bf16_f32 v232, v216, v217
	v_cvt_pk_bf16_f32 v233, v218, v219
	global_store_dwordx2 v214, v[232:233], s[14:15]
	s_add_i32 s48, s48, 1
	s_add_i32 s34, s34, 4
	s_cmp_lt_u32 s48, s49
	s_cbranch_scc0 .Lp11_chunk_done
	s_cmp_lt_u32 s34, 8192
	s_cbranch_scc1 .Lp11_body
	s_branch .Lp11_slice_next
